# g25 + back-edge rotation of the four GEMM k-loops (loop-back barrier becomes loop head, exit-path barrier copy)
# baseline (speedup 1.0000x reference)
; DI int tidx() { int t = __builtin_amdgcn_workitem_id_x(); asm volatile("" : "+v"(t)); return t; }
;   DI unsigned rowoff(int r, int sch) const { const int g = r & 3, bc = r >> 2, b = bc / NCMP, c = bc - b * NCMP; return (unsigned)(b * Sn + c * 16) * 512u + g * 64 + sch; }
; template <int NI, class XL, class EP>
; DI void gemm_tile(const u16* __restrict__ W, int ldw, int f0, int t0, int K, XL xl, EP ep, unsigned char* smem) {
;     ...
;   const int tid = tidx(), lane = tid & 63, wave = tid >> 6;
;   const int wf = wave >> 1, wt = wave & 1, lr = lane & 15, lq = lane >> 4;
;   const int srow = tid >> 2, sch = (tid & 3) * 8;
;   f32x4 acc[4][NI];
; #pragma unroll
;   for (int i = 0; i < 4; ++i)
; #pragma unroll
;     for (int j = 0; j < NI; ++j) acc[i][j] = (f32x4){0.f, 0.f, 0.f, 0.f};
;   u32x4 wr[2], xr[XR];
;   const unsigned wbyte = ((unsigned)(f0 + srow * 2) * 32u + sch) * 2u;
;   const unsigned xbyte = xl.rowoff(t0 + srow * XR, sch) * 2u;
;   const int xrs = xl.rstride();
;   const int nk = K >> 5;
;   auto gload = [&](int it) {
;     const int k = it * 32;
;     const char* wb = (const char*)(W + (size_t)(k >> 5) * ldw * 32);
;     const char* xb = (const char*)xl.kbase(k);
; #pragma unroll
;     for (int i = 0; i < 2; ++i) wr[i] = *(const u32x4*)(wb + wbyte + i * 64);
; #pragma unroll
;     for (int i = 0; i < XR; ++i) xr[i] = *(const u32x4*)(xb + xbyte + i * xrs);
;   };
;   auto lstore = [&](int buf) {
;     u16* Ws = S0 + buf * BUF; u16* Xs = Ws + 128 * LST;
; #pragma unroll
;     for (int i = 0; i < 2; ++i) *(u32x4*)(Ws + (srow * 2 + i) * LST + sch) = wr[i];
; #pragma unroll
;     for (int i = 0; i < XR; ++i) *(u32x4*)(Xs + (srow * XR + i) * LST + sch) = xr[i];
;   };
;   gload(0);
;   __syncthreads();
;   lstore(0);
;   __syncthreads();
;   if (nk > 1) gload(1);
.Lp1_dyn_skip_a:
	v_mov_b32_e32 v161, v218
	s_and_b32 s22, s59, 7
	s_or_b32 s61, s22, s53
	v_ashrrev_i32_e32 v44, 2, v161
	s_lshl_b32 s22, s59, 5
	v_lshlrev_b32_e32 v0, 3, v161
	v_lshlrev_b32_e32 v46, 6, v44
	s_and_b32 s60, s22, 0xffffff00
	v_and_b32_e32 v45, 24, v0
	v_lshl_add_u32 v0, s61, 12, v46
	s_add_i32 s60, s60, s54
	v_or_b32_e32 v0, v0, v45
	v_and_b32_e32 v48, 0x3fffffc, v161
	v_lshlrev_b32_e32 v47, 1, v0
	v_add_u32_e32 v0, s60, v48
	v_lshlrev_b32_e32 v162, 1, v45
	v_readlane_b32 s22, v245, 25
	v_lshl_or_b32 v49, v0, 6, v162
	v_readlane_b32 s23, v245, 26
	global_load_dwordx4 v[16:19], v47, s[42:43]
	global_load_dwordx4 v[20:23], v47, s[42:43] offset:64
	s_nop 2
	global_load_dwordx4 v[24:27], v49, s[22:23]
	global_load_dwordx4 v[28:31], v49, s[22:23] offset:64
	global_load_dwordx4 v[32:35], v49, s[22:23] offset:128
	global_load_dwordx4 v[36:39], v49, s[22:23] offset:192
	v_mul_lo_u32 v167, v44, s37
	v_or_b32_e32 v163, v167, v162
	v_add_u32_e32 v164, v163, v167
	s_barrier
	s_and_b32 s23, s58, 0x3ffff00
	s_and_b32 s24, s57, 7
	s_add_i32 s24, s56, s24
	s_add_i32 s23, s54, s23
	v_ashrrev_i32_e32 v51, 1, v161
	v_and_b32_e32 v50, 15, v161
	v_lshrrev_b32_e32 v52, 1, v161
	v_lshlrev_b32_e32 v53, 1, v161
	v_and_b32_e32 v159, 0xffffffc0, v51
	v_add_u32_e32 v44, s23, v48
	v_lshl_add_u32 v46, s24, 12, v46
	v_mov_b32_e32 v0, 0
	v_and_b32_e32 v158, 24, v52
	v_and_or_b32 v160, v53, s44, v50
	v_or_b32_e32 v48, v159, v50
	v_lshl_or_b32 v152, v44, 6, v162
	v_or_b32_e32 v44, v46, v45
	s_mov_b32 s22, 1
	v_mov_b32_e32 v155, v153
	v_mov_b32_e32 v1, v0
	v_mov_b32_e32 v2, v0
	v_mov_b32_e32 v3, v0
	v_mov_b32_e32 v4, v0
	v_mov_b32_e32 v5, v0
	v_mov_b32_e32 v6, v0
	v_mov_b32_e32 v7, v0
	v_mov_b32_e32 v8, v0
	v_mov_b32_e32 v9, v0
	v_mov_b32_e32 v10, v0
	v_mov_b32_e32 v11, v0
	v_mov_b32_e32 v12, v0
	v_mov_b32_e32 v13, v0
	v_mov_b32_e32 v14, v0
	v_mov_b32_e32 v15, v0
	v_mov_b32_e32 v40, v0
	v_mov_b32_e32 v41, v0
	v_mov_b32_e32 v42, v0
	v_mov_b32_e32 v43, v0
	v_mul_u32_u24_e32 v165, 48, v160
	v_lshlrev_b32_e32 v166, 1, v158
	v_mul_lo_u32 v168, v48, 48
	v_lshlrev_b32_e32 v154, 1, v44
	v_mov_b64_e32 v[156:157], v[152:153]
	v_mov_b32_e32 v56, v0
	v_mov_b32_e32 v57, v0
	v_mov_b32_e32 v58, v0
	v_mov_b32_e32 v59, v0
	v_mov_b32_e32 v68, v0
	v_mov_b32_e32 v69, v0
	v_mov_b32_e32 v70, v0
	v_mov_b32_e32 v71, v0
	v_mov_b32_e32 v80, v0
	v_mov_b32_e32 v81, v0
	v_mov_b32_e32 v82, v0
	v_mov_b32_e32 v83, v0
	v_mov_b32_e32 v44, v0
	v_mov_b32_e32 v45, v0
	v_mov_b32_e32 v46, v0
	v_mov_b32_e32 v48, v0
	s_waitcnt vmcnt(5)
	ds_write_b128 v163, v[16:19]
	s_waitcnt vmcnt(4)
	ds_write_b128 v163, v[20:23] offset:96
	s_waitcnt vmcnt(3)
	ds_write_b128 v164, v[24:27] offset:12288
	s_waitcnt vmcnt(2)
	ds_write_b128 v164, v[28:31] offset:12384
	s_waitcnt vmcnt(1)
	ds_write_b128 v164, v[32:35] offset:12480
	s_waitcnt vmcnt(0)
	ds_write_b128 v164, v[36:39] offset:12576
	s_waitcnt lgkmcnt(0)
	global_load_dwordx4 v[20:23], v47, s[6:7]
	global_load_dwordx4 v[16:19], v47, s[6:7] offset:64
	global_load_dwordx4 v[36:39], v49, s[8:9]
	global_load_dwordx4 v[32:35], v49, s[8:9] offset:64
	global_load_dwordx4 v[28:31], v49, s[8:9] offset:128
	global_load_dwordx4 v[24:27], v49, s[8:9] offset:192
	s_add_u32 s98, s42, s45
	s_addc_u32 s99, s43, 0
	s_add_u32 s100, s42, s46
	s_addc_u32 s101, s43, 0
	global_load_dwordx4 v[200:203], v154, s[98:99]
	global_load_dwordx4 v[204:207], v154, s[98:99] offset:64
	global_load_dwordx4 v[208:211], v156, s[100:101] offset:2048
	global_load_dwordx4 v[212:215], v156, s[100:101] offset:2112
	global_load_dwordx4 v[220:223], v156, s[100:101] offset:2176
	global_load_dwordx4 v[224:227], v156, s[100:101] offset:2240
	s_add_u32 s98, s98, s4
	s_addc_u32 s99, s99, s5
	s_add_u32 s100, s100, s14
	s_addc_u32 s101, s101, s15
	v_mov_b32_e32 v47, v0
	v_mov_b32_e32 v49, v0
	v_mov_b32_e32 v50, v0
	v_mov_b32_e32 v51, v0
	v_mov_b32_e32 v52, v0
	v_mov_b32_e32 v53, v0
	v_mov_b32_e32 v54, v0
	v_mov_b32_e32 v55, v0
	v_mov_b32_e32 v64, v0
	v_mov_b32_e32 v65, v0
	v_mov_b32_e32 v66, v0
	v_mov_b32_e32 v67, v0
	v_mov_b32_e32 v76, v0
	v_mov_b32_e32 v77, v0
	v_mov_b32_e32 v78, v0
	v_mov_b32_e32 v79, v0
	v_mov_b32_e32 v88, v0
	v_mov_b32_e32 v89, v0
	v_mov_b32_e32 v90, v0
	v_mov_b32_e32 v91, v0
	v_mov_b32_e32 v100, v0
	v_mov_b32_e32 v101, v0
	v_mov_b32_e32 v102, v0
	v_mov_b32_e32 v103, v0
	v_mov_b32_e32 v112, v0
	v_mov_b32_e32 v113, v0
	v_mov_b32_e32 v114, v0
	v_mov_b32_e32 v115, v0
	v_mov_b32_e32 v60, v0
	v_mov_b32_e32 v61, v0
	v_mov_b32_e32 v62, v0
	v_mov_b32_e32 v63, v0
	v_mov_b32_e32 v72, v0
	v_mov_b32_e32 v73, v0
	v_mov_b32_e32 v74, v0
	v_mov_b32_e32 v75, v0
	v_mov_b32_e32 v84, v0
	v_mov_b32_e32 v85, v0
	v_mov_b32_e32 v86, v0
	v_mov_b32_e32 v87, v0
	v_mov_b32_e32 v96, v0
	v_mov_b32_e32 v97, v0
	v_mov_b32_e32 v98, v0
	v_mov_b32_e32 v99, v0
	v_mov_b32_e32 v108, v0
	v_mov_b32_e32 v109, v0
	v_mov_b32_e32 v110, v0
	v_mov_b32_e32 v111, v0
	v_mov_b32_e32 v120, v0
	v_mov_b32_e32 v121, v0
	v_mov_b32_e32 v122, v0
	v_mov_b32_e32 v123, v0
	v_mov_b32_e32 v128, v0
	v_mov_b32_e32 v129, v0
	v_mov_b32_e32 v130, v0
	v_mov_b32_e32 v131, v0
	v_mov_b32_e32 v136, v0
	v_mov_b32_e32 v137, v0
	v_mov_b32_e32 v138, v0
	v_mov_b32_e32 v139, v0
	v_mov_b32_e32 v92, v0
	v_mov_b32_e32 v93, v0
	v_mov_b32_e32 v94, v0
	v_mov_b32_e32 v95, v0
	v_mov_b32_e32 v104, v0
	v_mov_b32_e32 v105, v0
	v_mov_b32_e32 v106, v0
	v_mov_b32_e32 v107, v0
	v_mov_b32_e32 v116, v0
	v_mov_b32_e32 v117, v0
	v_mov_b32_e32 v118, v0
	v_mov_b32_e32 v119, v0
	v_mov_b32_e32 v124, v0
	v_mov_b32_e32 v125, v0
	v_mov_b32_e32 v126, v0
	v_mov_b32_e32 v127, v0
	v_mov_b32_e32 v132, v0
	v_mov_b32_e32 v133, v0
	v_mov_b32_e32 v134, v0
	v_mov_b32_e32 v135, v0
	v_mov_b32_e32 v140, v0
	v_mov_b32_e32 v141, v0
	v_mov_b32_e32 v142, v0
	v_mov_b32_e32 v143, v0
	v_mov_b32_e32 v144, v0
	v_mov_b32_e32 v145, v0
	v_mov_b32_e32 v146, v0
	v_mov_b32_e32 v147, v0
	v_mov_b32_e32 v148, v0
	v_mov_b32_e32 v149, v0
	v_mov_b32_e32 v150, v0
	v_mov_b32_e32 v151, v0
	v_lshl_add_u32 v228, v168, 1, v166
	v_lshl_add_u32 v152, v165, 1, v166
	v_add_u32_e32 v194, v167, v162
	v_add_u32_e32 v195, v194, v167
; DI f32x4 mfma16(bf16x8 a, bf16x8 b, f32x4 c) { return __builtin_amdgcn_mfma_f32_16x16x32_bf16(a, b, c, 0, 0, 0); }
; template <int NI, class XL, class EP>
; DI void gemm_tile(const u16* __restrict__ W, int ldw, int f0, int t0, int K, XL xl, EP ep, unsigned char* smem) {
;     ...
;   for (int it = 0; it < nk; ++it) {
;     const u16* Ws = S0 + (it & 1) * BUF; const u16* Xs = Ws + 128 * LST;
;     __builtin_amdgcn_s_setprio(1);
;     bf16x8 a[4];
; #pragma unroll
;     for (int mi = 0; mi < 4; ++mi) a[mi] = *(const bf16x8*)(Ws + (wf * 64 + mi * 16 + lr) * LST + lq * 8);
; #pragma unroll
;     for (int ni = 0; ni < NI; ++ni) {
;       const bf16x8 b = *(const bf16x8*)(Xs + (wt * (NI * 16) + ni * 16 + lr) * LST + lq * 8);
; #pragma unroll
;       for (int mi = 0; mi < 4; ++mi) acc[mi][ni] = mfma16(a[mi], b, acc[mi][ni]);
;     }
;     __builtin_amdgcn_sched_group_barrier(0x100, 6, 0);
; #pragma unroll
;     for (int ni = 0; ni < NI; ++ni) { __builtin_amdgcn_sched_group_barrier(0x008, 4, 0); if (ni + 2 < NI) __builtin_amdgcn_sched_group_barrier(0x100, 1, 0); }
;     __builtin_amdgcn_s_setprio(0);
;     if (it + 1 < nk) lstore((it + 1) & 1);
;     if (it + 2 < nk) gload(it + 2);
;     __syncthreads();
.LBB0_269:
	s_barrier
	s_setprio 1
	ds_read_b128 v[170:173], v228 offset:0
	ds_read_b128 v[174:177], v228 offset:1536
	ds_read_b128 v[182:185], v228 offset:3072
	ds_read_b128 v[186:189], v228 offset:4608
	ds_read_b128 v[178:181], v152 offset:12288
	ds_read_b128 v[190:193], v152 offset:13824
	s_waitcnt lgkmcnt(1)
	v_mfma_f32_16x16x32_bf16 v[148:151], v[170:173], v[178:181], v[148:151]
	v_mfma_f32_16x16x32_bf16 v[136:139], v[174:177], v[178:181], v[136:139]
	v_mfma_f32_16x16x32_bf16 v[112:115], v[182:185], v[178:181], v[112:115]
	v_mfma_f32_16x16x32_bf16 v[80:83], v[186:189], v[178:181], v[80:83]
	ds_read_b128 v[178:181], v152 offset:15360
	s_waitcnt vmcnt(6)
	ds_write_b128 v194, v[20:23] offset:36864
	s_waitcnt lgkmcnt(2)
	v_mfma_f32_16x16x32_bf16 v[144:147], v[170:173], v[190:193], v[144:147]
	v_mfma_f32_16x16x32_bf16 v[128:131], v[174:177], v[190:193], v[128:131]
	v_mfma_f32_16x16x32_bf16 v[100:103], v[182:185], v[190:193], v[100:103]
	v_mfma_f32_16x16x32_bf16 v[68:71], v[186:189], v[190:193], v[68:71]
	ds_read_b128 v[190:193], v152 offset:16896
	ds_write_b128 v194, v[16:19] offset:36960
	global_load_dwordx4 v[20:23], v154, s[98:99]
	global_load_dwordx4 v[16:19], v154, s[98:99] offset:64
	s_waitcnt lgkmcnt(3)
	v_mfma_f32_16x16x32_bf16 v[140:143], v[170:173], v[178:181], v[140:143]
	v_mfma_f32_16x16x32_bf16 v[120:123], v[174:177], v[178:181], v[120:123]
	v_mfma_f32_16x16x32_bf16 v[88:91], v[182:185], v[178:181], v[88:91]
	v_mfma_f32_16x16x32_bf16 v[56:59], v[186:189], v[178:181], v[56:59]
	ds_read_b128 v[178:181], v152 offset:18432
	ds_write_b128 v195, v[36:39] offset:49152
	global_load_dwordx4 v[36:39], v156, s[100:101] offset:2048
	s_waitcnt lgkmcnt(3)
	v_mfma_f32_16x16x32_bf16 v[132:135], v[170:173], v[190:193], v[132:135]
	v_mfma_f32_16x16x32_bf16 v[108:111], v[174:177], v[190:193], v[108:111]
	v_mfma_f32_16x16x32_bf16 v[76:79], v[182:185], v[190:193], v[76:79]
	v_mfma_f32_16x16x32_bf16 v[40:43], v[186:189], v[190:193], v[40:43]
	ds_read_b128 v[190:193], v152 offset:19968
	ds_write_b128 v195, v[32:35] offset:49248
	global_load_dwordx4 v[32:35], v156, s[100:101] offset:2112
	s_waitcnt lgkmcnt(3)
	v_mfma_f32_16x16x32_bf16 v[124:127], v[170:173], v[178:181], v[124:127]
	v_mfma_f32_16x16x32_bf16 v[96:99], v[174:177], v[178:181], v[96:99]
	v_mfma_f32_16x16x32_bf16 v[64:67], v[182:185], v[178:181], v[64:67]
	v_mfma_f32_16x16x32_bf16 v[12:15], v[186:189], v[178:181], v[12:15]
	ds_read_b128 v[178:181], v152 offset:21504
	ds_write_b128 v195, v[28:31] offset:49344
	global_load_dwordx4 v[28:31], v156, s[100:101] offset:2176
	s_waitcnt lgkmcnt(3)
	v_mfma_f32_16x16x32_bf16 v[116:119], v[170:173], v[190:193], v[116:119]
	v_mfma_f32_16x16x32_bf16 v[84:87], v[174:177], v[190:193], v[84:87]
	v_mfma_f32_16x16x32_bf16 v[52:55], v[182:185], v[190:193], v[52:55]
	v_mfma_f32_16x16x32_bf16 v[8:11], v[186:189], v[190:193], v[8:11]
	ds_read_b128 v[190:193], v152 offset:23040
	ds_write_b128 v195, v[24:27] offset:49440
	global_load_dwordx4 v[24:27], v156, s[100:101] offset:2240
	s_waitcnt lgkmcnt(3)
	v_mfma_f32_16x16x32_bf16 v[104:107], v[170:173], v[178:181], v[104:107]
	v_mfma_f32_16x16x32_bf16 v[72:75], v[174:177], v[178:181], v[72:75]
	v_mfma_f32_16x16x32_bf16 v[48:51], v[182:185], v[178:181], v[48:51]
	v_mfma_f32_16x16x32_bf16 v[4:7], v[186:189], v[178:181], v[4:7]
	s_add_u32 s98, s98, s4
	s_addc_u32 s99, s99, s5
	s_add_u32 s100, s100, s14
	s_addc_u32 s101, s101, s15
	s_waitcnt lgkmcnt(1)
	v_mfma_f32_16x16x32_bf16 v[92:95], v[170:173], v[190:193], v[92:95]
	v_mfma_f32_16x16x32_bf16 v[60:63], v[174:177], v[190:193], v[60:63]
	v_mfma_f32_16x16x32_bf16 v[44:47], v[182:185], v[190:193], v[44:47]
	v_mfma_f32_16x16x32_bf16 v[0:3], v[186:189], v[190:193], v[0:3]
	s_setprio 0
	s_waitcnt lgkmcnt(0)
	s_barrier
	s_setprio 1
	ds_read_b128 v[170:173], v228 offset:36864
	ds_read_b128 v[174:177], v228 offset:38400
	ds_read_b128 v[182:185], v228 offset:39936
	ds_read_b128 v[186:189], v228 offset:41472
	ds_read_b128 v[178:181], v152 offset:49152
	ds_read_b128 v[190:193], v152 offset:50688
	s_waitcnt lgkmcnt(1)
	v_mfma_f32_16x16x32_bf16 v[148:151], v[170:173], v[178:181], v[148:151]
	v_mfma_f32_16x16x32_bf16 v[136:139], v[174:177], v[178:181], v[136:139]
	v_mfma_f32_16x16x32_bf16 v[112:115], v[182:185], v[178:181], v[112:115]
	v_mfma_f32_16x16x32_bf16 v[80:83], v[186:189], v[178:181], v[80:83]
	ds_read_b128 v[178:181], v152 offset:52224
	s_waitcnt vmcnt(6)
	ds_write_b128 v194, v[200:203] offset:0
	s_waitcnt lgkmcnt(2)
	v_mfma_f32_16x16x32_bf16 v[144:147], v[170:173], v[190:193], v[144:147]
	v_mfma_f32_16x16x32_bf16 v[128:131], v[174:177], v[190:193], v[128:131]
	v_mfma_f32_16x16x32_bf16 v[100:103], v[182:185], v[190:193], v[100:103]
	v_mfma_f32_16x16x32_bf16 v[68:71], v[186:189], v[190:193], v[68:71]
	ds_read_b128 v[190:193], v152 offset:53760
	ds_write_b128 v194, v[204:207] offset:96
	global_load_dwordx4 v[200:203], v154, s[98:99]
	global_load_dwordx4 v[204:207], v154, s[98:99] offset:64
	s_waitcnt lgkmcnt(3)
	v_mfma_f32_16x16x32_bf16 v[140:143], v[170:173], v[178:181], v[140:143]
	v_mfma_f32_16x16x32_bf16 v[120:123], v[174:177], v[178:181], v[120:123]
	v_mfma_f32_16x16x32_bf16 v[88:91], v[182:185], v[178:181], v[88:91]
	v_mfma_f32_16x16x32_bf16 v[56:59], v[186:189], v[178:181], v[56:59]
	ds_read_b128 v[178:181], v152 offset:55296
	ds_write_b128 v195, v[208:211] offset:12288
	global_load_dwordx4 v[208:211], v156, s[100:101] offset:2048
	s_waitcnt lgkmcnt(3)
; DI f32x4 mfma16(bf16x8 a, bf16x8 b, f32x4 c) { return __builtin_amdgcn_mfma_f32_16x16x32_bf16(a, b, c, 0, 0, 0); }
; template <int NI, class XL, class EP>
; DI void gemm_tile(const u16* __restrict__ W, int ldw, int f0, int t0, int K, XL xl, EP ep, unsigned char* smem) {
;     ...
;   for (int it = 0; it < nk; ++it) {
;     const u16* Ws = S0 + (it & 1) * BUF; const u16* Xs = Ws + 128 * LST;
;     __builtin_amdgcn_s_setprio(1);
;     bf16x8 a[4];
; #pragma unroll
;     for (int mi = 0; mi < 4; ++mi) a[mi] = *(const bf16x8*)(Ws + (wf * 64 + mi * 16 + lr) * LST + lq * 8);
; #pragma unroll
;     for (int ni = 0; ni < NI; ++ni) {
;       const bf16x8 b = *(const bf16x8*)(Xs + (wt * (NI * 16) + ni * 16 + lr) * LST + lq * 8);
; #pragma unroll
;       for (int mi = 0; mi < 4; ++mi) acc[mi][ni] = mfma16(a[mi], b, acc[mi][ni]);
;     }
;     __builtin_amdgcn_sched_group_barrier(0x100, 6, 0);
; #pragma unroll
;     for (int ni = 0; ni < NI; ++ni) { __builtin_amdgcn_sched_group_barrier(0x008, 4, 0); if (ni + 2 < NI) __builtin_amdgcn_sched_group_barrier(0x100, 1, 0); }
;     __builtin_amdgcn_s_setprio(0);
;     if (it + 1 < nk) lstore((it + 1) & 1);
;     if (it + 2 < nk) gload(it + 2);
;     __syncthreads();
	v_mfma_f32_16x16x32_bf16 v[132:135], v[170:173], v[190:193], v[132:135]
	v_mfma_f32_16x16x32_bf16 v[108:111], v[174:177], v[190:193], v[108:111]
	v_mfma_f32_16x16x32_bf16 v[76:79], v[182:185], v[190:193], v[76:79]
	v_mfma_f32_16x16x32_bf16 v[40:43], v[186:189], v[190:193], v[40:43]
	ds_read_b128 v[190:193], v152 offset:56832
	ds_write_b128 v195, v[212:215] offset:12384
	global_load_dwordx4 v[212:215], v156, s[100:101] offset:2112
	s_waitcnt lgkmcnt(3)
	v_mfma_f32_16x16x32_bf16 v[124:127], v[170:173], v[178:181], v[124:127]
	v_mfma_f32_16x16x32_bf16 v[96:99], v[174:177], v[178:181], v[96:99]
	v_mfma_f32_16x16x32_bf16 v[64:67], v[182:185], v[178:181], v[64:67]
	v_mfma_f32_16x16x32_bf16 v[12:15], v[186:189], v[178:181], v[12:15]
	ds_read_b128 v[178:181], v152 offset:58368
	ds_write_b128 v195, v[220:223] offset:12480
	global_load_dwordx4 v[220:223], v156, s[100:101] offset:2176
	s_waitcnt lgkmcnt(3)
	v_mfma_f32_16x16x32_bf16 v[116:119], v[170:173], v[190:193], v[116:119]
	v_mfma_f32_16x16x32_bf16 v[84:87], v[174:177], v[190:193], v[84:87]
	v_mfma_f32_16x16x32_bf16 v[52:55], v[182:185], v[190:193], v[52:55]
	v_mfma_f32_16x16x32_bf16 v[8:11], v[186:189], v[190:193], v[8:11]
	ds_read_b128 v[190:193], v152 offset:59904
	ds_write_b128 v195, v[224:227] offset:12576
	global_load_dwordx4 v[224:227], v156, s[100:101] offset:2240
	s_waitcnt lgkmcnt(3)
	v_mfma_f32_16x16x32_bf16 v[104:107], v[170:173], v[178:181], v[104:107]
	v_mfma_f32_16x16x32_bf16 v[72:75], v[174:177], v[178:181], v[72:75]
	v_mfma_f32_16x16x32_bf16 v[48:51], v[182:185], v[178:181], v[48:51]
	v_mfma_f32_16x16x32_bf16 v[4:7], v[186:189], v[178:181], v[4:7]
	s_add_u32 s98, s98, s4
	s_addc_u32 s99, s99, s5
	s_add_u32 s100, s100, s14
	s_addc_u32 s101, s101, s15
	s_add_i32 s22, s22, 2
	s_waitcnt lgkmcnt(1)
	v_mfma_f32_16x16x32_bf16 v[92:95], v[170:173], v[190:193], v[92:95]
	v_mfma_f32_16x16x32_bf16 v[60:63], v[174:177], v[190:193], v[60:63]
	v_mfma_f32_16x16x32_bf16 v[44:47], v[182:185], v[190:193], v[44:47]
	v_mfma_f32_16x16x32_bf16 v[0:3], v[186:189], v[190:193], v[0:3]
	s_setprio 0
	s_cmp_eq_u32 s22, 29
	s_waitcnt lgkmcnt(0)
	s_cbranch_scc0 .LBB0_269
	s_barrier
	s_setprio 1
	ds_read_b128 v[170:173], v228 offset:0
	ds_read_b128 v[174:177], v228 offset:1536
	ds_read_b128 v[182:185], v228 offset:3072
	ds_read_b128 v[186:189], v228 offset:4608
	ds_read_b128 v[178:181], v152 offset:12288
	ds_read_b128 v[190:193], v152 offset:13824
	s_waitcnt lgkmcnt(1)
	v_mfma_f32_16x16x32_bf16 v[148:151], v[170:173], v[178:181], v[148:151]
	v_mfma_f32_16x16x32_bf16 v[136:139], v[174:177], v[178:181], v[136:139]
	v_mfma_f32_16x16x32_bf16 v[112:115], v[182:185], v[178:181], v[112:115]
	v_mfma_f32_16x16x32_bf16 v[80:83], v[186:189], v[178:181], v[80:83]
	ds_read_b128 v[178:181], v152 offset:15360
	s_waitcnt vmcnt(6)
	ds_write_b128 v194, v[20:23] offset:36864
	s_waitcnt lgkmcnt(2)
	v_mfma_f32_16x16x32_bf16 v[144:147], v[170:173], v[190:193], v[144:147]
	v_mfma_f32_16x16x32_bf16 v[128:131], v[174:177], v[190:193], v[128:131]
	v_mfma_f32_16x16x32_bf16 v[100:103], v[182:185], v[190:193], v[100:103]
	v_mfma_f32_16x16x32_bf16 v[68:71], v[186:189], v[190:193], v[68:71]
	ds_read_b128 v[190:193], v152 offset:16896
	ds_write_b128 v194, v[16:19] offset:36960
	global_load_dwordx4 v[20:23], v154, s[98:99]
	global_load_dwordx4 v[16:19], v154, s[98:99] offset:64
	s_waitcnt lgkmcnt(3)
	v_mfma_f32_16x16x32_bf16 v[140:143], v[170:173], v[178:181], v[140:143]
	v_mfma_f32_16x16x32_bf16 v[120:123], v[174:177], v[178:181], v[120:123]
	v_mfma_f32_16x16x32_bf16 v[88:91], v[182:185], v[178:181], v[88:91]
	v_mfma_f32_16x16x32_bf16 v[56:59], v[186:189], v[178:181], v[56:59]
	ds_read_b128 v[178:181], v152 offset:18432
	ds_write_b128 v195, v[36:39] offset:49152
	global_load_dwordx4 v[36:39], v156, s[100:101] offset:2048
	s_waitcnt lgkmcnt(3)
	v_mfma_f32_16x16x32_bf16 v[132:135], v[170:173], v[190:193], v[132:135]
	v_mfma_f32_16x16x32_bf16 v[108:111], v[174:177], v[190:193], v[108:111]
	v_mfma_f32_16x16x32_bf16 v[76:79], v[182:185], v[190:193], v[76:79]
	v_mfma_f32_16x16x32_bf16 v[40:43], v[186:189], v[190:193], v[40:43]
	ds_read_b128 v[190:193], v152 offset:19968
	ds_write_b128 v195, v[32:35] offset:49248
	global_load_dwordx4 v[32:35], v156, s[100:101] offset:2112
	s_waitcnt lgkmcnt(3)
	v_mfma_f32_16x16x32_bf16 v[124:127], v[170:173], v[178:181], v[124:127]
	v_mfma_f32_16x16x32_bf16 v[96:99], v[174:177], v[178:181], v[96:99]
	v_mfma_f32_16x16x32_bf16 v[64:67], v[182:185], v[178:181], v[64:67]
	v_mfma_f32_16x16x32_bf16 v[12:15], v[186:189], v[178:181], v[12:15]
	ds_read_b128 v[178:181], v152 offset:21504
	ds_write_b128 v195, v[28:31] offset:49344
	global_load_dwordx4 v[28:31], v156, s[100:101] offset:2176
	s_waitcnt lgkmcnt(3)
	v_mfma_f32_16x16x32_bf16 v[116:119], v[170:173], v[190:193], v[116:119]
	v_mfma_f32_16x16x32_bf16 v[84:87], v[174:177], v[190:193], v[84:87]
	v_mfma_f32_16x16x32_bf16 v[52:55], v[182:185], v[190:193], v[52:55]
	v_mfma_f32_16x16x32_bf16 v[8:11], v[186:189], v[190:193], v[8:11]
	ds_read_b128 v[190:193], v152 offset:23040
	ds_write_b128 v195, v[24:27] offset:49440
	global_load_dwordx4 v[24:27], v156, s[100:101] offset:2240
	s_waitcnt lgkmcnt(3)
	v_mfma_f32_16x16x32_bf16 v[104:107], v[170:173], v[178:181], v[104:107]
	v_mfma_f32_16x16x32_bf16 v[72:75], v[174:177], v[178:181], v[72:75]
	v_mfma_f32_16x16x32_bf16 v[48:51], v[182:185], v[178:181], v[48:51]
	v_mfma_f32_16x16x32_bf16 v[4:7], v[186:189], v[178:181], v[4:7]
	s_add_u32 s98, s98, s4
	s_addc_u32 s99, s99, s5
	s_add_u32 s100, s100, s14
	s_addc_u32 s101, s101, s15
	s_waitcnt lgkmcnt(1)
	v_mfma_f32_16x16x32_bf16 v[92:95], v[170:173], v[190:193], v[92:95]
	v_mfma_f32_16x16x32_bf16 v[60:63], v[174:177], v[190:193], v[60:63]
	v_mfma_f32_16x16x32_bf16 v[44:47], v[182:185], v[190:193], v[44:47]
	v_mfma_f32_16x16x32_bf16 v[0:3], v[186:189], v[190:193], v[0:3]
	s_setprio 0
	s_waitcnt lgkmcnt(0)
	s_barrier
; DI f32x4 mfma16(bf16x8 a, bf16x8 b, f32x4 c) { return __builtin_amdgcn_mfma_f32_16x16x32_bf16(a, b, c, 0, 0, 0); }
; template <int NI, class XL, class EP>
; DI void gemm_tile(const u16* __restrict__ W, int ldw, int f0, int t0, int K, XL xl, EP ep, unsigned char* smem) {
;     ...
;   for (int it = 0; it < nk; ++it) {
;     const u16* Ws = S0 + (it & 1) * BUF; const u16* Xs = Ws + 128 * LST;
;     __builtin_amdgcn_s_setprio(1);
;     bf16x8 a[4];
; #pragma unroll
;     for (int mi = 0; mi < 4; ++mi) a[mi] = *(const bf16x8*)(Ws + (wf * 64 + mi * 16 + lr) * LST + lq * 8);
; #pragma unroll
;     for (int ni = 0; ni < NI; ++ni) {
;       const bf16x8 b = *(const bf16x8*)(Xs + (wt * (NI * 16) + ni * 16 + lr) * LST + lq * 8);
; #pragma unroll
;       for (int mi = 0; mi < 4; ++mi) acc[mi][ni] = mfma16(a[mi], b, acc[mi][ni]);
;     }
;     __builtin_amdgcn_sched_group_barrier(0x100, 6, 0);
; #pragma unroll
;     for (int ni = 0; ni < NI; ++ni) { __builtin_amdgcn_sched_group_barrier(0x008, 4, 0); if (ni + 2 < NI) __builtin_amdgcn_sched_group_barrier(0x100, 1, 0); }
;     __builtin_amdgcn_s_setprio(0);
;     if (it + 1 < nk) lstore((it + 1) & 1);
;     if (it + 2 < nk) gload(it + 2);
;     __syncthreads();
	s_setprio 1
	ds_read_b128 v[170:173], v228 offset:36864
	ds_read_b128 v[174:177], v228 offset:38400
	ds_read_b128 v[182:185], v228 offset:39936
	ds_read_b128 v[186:189], v228 offset:41472
	ds_read_b128 v[178:181], v152 offset:49152
	ds_read_b128 v[190:193], v152 offset:50688
	s_waitcnt lgkmcnt(1)
	v_mfma_f32_16x16x32_bf16 v[148:151], v[170:173], v[178:181], v[148:151]
	v_mfma_f32_16x16x32_bf16 v[136:139], v[174:177], v[178:181], v[136:139]
	v_mfma_f32_16x16x32_bf16 v[112:115], v[182:185], v[178:181], v[112:115]
	v_mfma_f32_16x16x32_bf16 v[80:83], v[186:189], v[178:181], v[80:83]
	ds_read_b128 v[178:181], v152 offset:52224
	s_waitcnt vmcnt(6)
	ds_write_b128 v194, v[200:203] offset:0
	s_waitcnt lgkmcnt(2)
	v_mfma_f32_16x16x32_bf16 v[144:147], v[170:173], v[190:193], v[144:147]
	v_mfma_f32_16x16x32_bf16 v[128:131], v[174:177], v[190:193], v[128:131]
	v_mfma_f32_16x16x32_bf16 v[100:103], v[182:185], v[190:193], v[100:103]
	v_mfma_f32_16x16x32_bf16 v[68:71], v[186:189], v[190:193], v[68:71]
	ds_read_b128 v[190:193], v152 offset:53760
	ds_write_b128 v194, v[204:207] offset:96
	s_waitcnt lgkmcnt(3)
	v_mfma_f32_16x16x32_bf16 v[140:143], v[170:173], v[178:181], v[140:143]
	v_mfma_f32_16x16x32_bf16 v[120:123], v[174:177], v[178:181], v[120:123]
	v_mfma_f32_16x16x32_bf16 v[88:91], v[182:185], v[178:181], v[88:91]
	v_mfma_f32_16x16x32_bf16 v[56:59], v[186:189], v[178:181], v[56:59]
	ds_read_b128 v[178:181], v152 offset:55296
	ds_write_b128 v195, v[208:211] offset:12288
	s_waitcnt lgkmcnt(3)
	v_mfma_f32_16x16x32_bf16 v[132:135], v[170:173], v[190:193], v[132:135]
	v_mfma_f32_16x16x32_bf16 v[108:111], v[174:177], v[190:193], v[108:111]
	v_mfma_f32_16x16x32_bf16 v[76:79], v[182:185], v[190:193], v[76:79]
	v_mfma_f32_16x16x32_bf16 v[40:43], v[186:189], v[190:193], v[40:43]
	ds_read_b128 v[190:193], v152 offset:56832
	ds_write_b128 v195, v[212:215] offset:12384
	s_waitcnt lgkmcnt(3)
	v_mfma_f32_16x16x32_bf16 v[124:127], v[170:173], v[178:181], v[124:127]
	v_mfma_f32_16x16x32_bf16 v[96:99], v[174:177], v[178:181], v[96:99]
	v_mfma_f32_16x16x32_bf16 v[64:67], v[182:185], v[178:181], v[64:67]
	v_mfma_f32_16x16x32_bf16 v[12:15], v[186:189], v[178:181], v[12:15]
	ds_read_b128 v[178:181], v152 offset:58368
	ds_write_b128 v195, v[220:223] offset:12480
	s_waitcnt lgkmcnt(3)
	v_mfma_f32_16x16x32_bf16 v[116:119], v[170:173], v[190:193], v[116:119]
	v_mfma_f32_16x16x32_bf16 v[84:87], v[174:177], v[190:193], v[84:87]
	v_mfma_f32_16x16x32_bf16 v[52:55], v[182:185], v[190:193], v[52:55]
	v_mfma_f32_16x16x32_bf16 v[8:11], v[186:189], v[190:193], v[8:11]
	ds_read_b128 v[190:193], v152 offset:59904
	ds_write_b128 v195, v[224:227] offset:12576
	s_waitcnt lgkmcnt(3)
	v_mfma_f32_16x16x32_bf16 v[104:107], v[170:173], v[178:181], v[104:107]
	v_mfma_f32_16x16x32_bf16 v[72:75], v[174:177], v[178:181], v[72:75]
	v_mfma_f32_16x16x32_bf16 v[48:51], v[182:185], v[178:181], v[48:51]
	v_mfma_f32_16x16x32_bf16 v[4:7], v[186:189], v[178:181], v[4:7]
	s_add_i32 s22, s22, 2
	s_waitcnt lgkmcnt(1)
	v_mfma_f32_16x16x32_bf16 v[92:95], v[170:173], v[190:193], v[92:95]
	v_mfma_f32_16x16x32_bf16 v[60:63], v[174:177], v[190:193], v[60:63]
	v_mfma_f32_16x16x32_bf16 v[44:47], v[182:185], v[190:193], v[44:47]
	v_mfma_f32_16x16x32_bf16 v[0:3], v[186:189], v[190:193], v[0:3]
	s_setprio 0
	s_waitcnt lgkmcnt(0)
	s_barrier
	s_setprio 1
	v_lshl_add_u32 v152, v168, 1, v166
	ds_read_b128 v[154:157], v152
	v_lshl_add_u32 v228, v165, 1, v166
	ds_read_b128 v[166:169], v152 offset:1536
	ds_read_b128 v[174:177], v152 offset:3072
	ds_read_b128 v[178:181], v152 offset:4608
	ds_read_b128 v[170:173], v228 offset:12288
	ds_read_b128 v[182:185], v228 offset:13824
	s_waitcnt lgkmcnt(1)
	v_mfma_f32_16x16x32_bf16 v[148:151], v[154:157], v[170:173], v[148:151]
	v_mfma_f32_16x16x32_bf16 v[136:139], v[166:169], v[170:173], v[136:139]
	v_mfma_f32_16x16x32_bf16 v[112:115], v[174:177], v[170:173], v[112:115]
	v_mfma_f32_16x16x32_bf16 v[170:173], v[178:181], v[170:173], v[80:83]
	s_nop 2
	ds_read_b128 v[80:83], v228 offset:15360
	s_waitcnt vmcnt(5)
	ds_write_b128 v163, v[20:23] offset:36864
	s_waitcnt lgkmcnt(2)
	v_mfma_f32_16x16x32_bf16 v[144:147], v[154:157], v[182:185], v[144:147]
	v_mfma_f32_16x16x32_bf16 v[128:131], v[166:169], v[182:185], v[128:131]
	v_mfma_f32_16x16x32_bf16 v[100:103], v[174:177], v[182:185], v[100:103]
	v_mfma_f32_16x16x32_bf16 v[68:71], v[178:181], v[182:185], v[68:71]
	ds_read_b128 v[182:185], v228 offset:16896
	s_waitcnt vmcnt(4)
	ds_write_b128 v163, v[16:19] offset:36960
	s_waitcnt lgkmcnt(3)
	v_mfma_f32_16x16x32_bf16 v[140:143], v[154:157], v[80:83], v[140:143]
	v_mfma_f32_16x16x32_bf16 v[186:189], v[166:169], v[80:83], v[120:123]
	v_mfma_f32_16x16x32_bf16 v[88:91], v[174:177], v[80:83], v[88:91]
	v_mfma_f32_16x16x32_bf16 v[56:59], v[178:181], v[80:83], v[56:59]
	ds_read_b128 v[80:83], v228 offset:18432
	s_waitcnt vmcnt(3)
	ds_write_b128 v164, v[36:39] offset:49152
	s_waitcnt lgkmcnt(3)
	v_mfma_f32_16x16x32_bf16 v[132:135], v[154:157], v[182:185], v[132:135]
	v_mfma_f32_16x16x32_bf16 v[108:111], v[166:169], v[182:185], v[108:111]
	v_mfma_f32_16x16x32_bf16 v[76:79], v[174:177], v[182:185], v[76:79]
	v_mfma_f32_16x16x32_bf16 v[182:185], v[178:181], v[182:185], v[40:43]
	s_nop 2
	ds_read_b128 v[40:43], v228 offset:19968
	s_waitcnt vmcnt(2)
	ds_write_b128 v164, v[32:35] offset:49248
	s_waitcnt lgkmcnt(3)
	v_mfma_f32_16x16x32_bf16 v[190:193], v[154:157], v[80:83], v[124:127]
	v_mfma_f32_16x16x32_bf16 v[96:99], v[166:169], v[80:83], v[96:99]
	v_mfma_f32_16x16x32_bf16 v[194:197], v[174:177], v[80:83], v[64:67]
	v_mfma_f32_16x16x32_bf16 v[198:201], v[178:181], v[80:83], v[12:15]
	s_nop 2
	ds_read_b128 v[12:15], v228 offset:21504
	s_waitcnt vmcnt(1)
	ds_write_b128 v164, v[28:31] offset:49344
	s_waitcnt lgkmcnt(3)
	v_mfma_f32_16x16x32_bf16 v[202:205], v[154:157], v[40:43], v[116:119]
	v_mfma_f32_16x16x32_bf16 v[84:87], v[166:169], v[40:43], v[84:87]
	v_mfma_f32_16x16x32_bf16 v[52:55], v[174:177], v[40:43], v[52:55]
	v_mfma_f32_16x16x32_bf16 v[206:209], v[178:181], v[40:43], v[8:11]
	s_nop 2
	ds_read_b128 v[8:11], v228 offset:23040
	s_waitcnt vmcnt(0)
	ds_write_b128 v164, v[24:27] offset:49440
	s_waitcnt lgkmcnt(3)
	v_mfma_f32_16x16x32_bf16 v[210:213], v[154:157], v[12:15], v[104:107]
	v_mfma_f32_16x16x32_bf16 v[214:217], v[166:169], v[12:15], v[72:75]
	v_mfma_f32_16x16x32_bf16 v[220:223], v[174:177], v[12:15], v[48:51]
	v_mfma_f32_16x16x32_bf16 v[224:227], v[178:181], v[12:15], v[4:7]
	s_waitcnt lgkmcnt(1)
	v_mfma_f32_16x16x32_bf16 v[92:95], v[154:157], v[8:11], v[92:95]
	v_mfma_f32_16x16x32_bf16 v[60:63], v[166:169], v[8:11], v[60:63]
	v_mfma_f32_16x16x32_bf16 v[154:157], v[174:177], v[8:11], v[44:47]
	v_mfma_f32_16x16x32_bf16 v[166:169], v[178:181], v[8:11], v[0:3]
	s_setprio 0
	s_waitcnt lgkmcnt(0)
	s_barrier
; DI f32x4 mfma16(bf16x8 a, bf16x8 b, f32x4 c) { return __builtin_amdgcn_mfma_f32_16x16x32_bf16(a, b, c, 0, 0, 0); }
; template <int NI, class XL, class EP>
; DI void gemm_tile(const u16* __restrict__ W, int ldw, int f0, int t0, int K, XL xl, EP ep, unsigned char* smem) {
;     ...
;   for (int it = 0; it < nk; ++it) {
;     const u16* Ws = S0 + (it & 1) * BUF; const u16* Xs = Ws + 128 * LST;
;     __builtin_amdgcn_s_setprio(1);
;     bf16x8 a[4];
; #pragma unroll
;     for (int mi = 0; mi < 4; ++mi) a[mi] = *(const bf16x8*)(Ws + (wf * 64 + mi * 16 + lr) * LST + lq * 8);
; #pragma unroll
;     for (int ni = 0; ni < NI; ++ni) {
;       const bf16x8 b = *(const bf16x8*)(Xs + (wt * (NI * 16) + ni * 16 + lr) * LST + lq * 8);
; #pragma unroll
;       for (int mi = 0; mi < 4; ++mi) acc[mi][ni] = mfma16(a[mi], b, acc[mi][ni]);
;     }
;     __builtin_amdgcn_sched_group_barrier(0x100, 6, 0);
; #pragma unroll
;     for (int ni = 0; ni < NI; ++ni) { __builtin_amdgcn_sched_group_barrier(0x008, 4, 0); if (ni + 2 < NI) __builtin_amdgcn_sched_group_barrier(0x100, 1, 0); }
;     __builtin_amdgcn_s_setprio(0);
;     if (it + 1 < nk) lstore((it + 1) & 1);
;     if (it + 2 < nk) gload(it + 2);
;     __syncthreads();
;   }
;   ep(acc, f0 + wf * 64, t0 + wt * (NI * 16), lr, lq, wf, wt);
; DI void phase1(const Params& p, const Sched& sched, unsigned char* smem) {
;     ...
;       u16* dst; int ld, cb;
;       if (tn < 8) { dst = (u16*)(p.ws + OFF_QB); ld = 1024; cb = 0; }
;       else if (tn < 12) { dst = (u16*)(p.ws + OFF_KVC); ld = 512; cb = 1024; }
;       else if (tn < 16) { dst = (u16*)(p.ws + OFF_KVS); ld = 512; cb = 1536; }
;       else if (tn < 20) { dst = (u16*)(p.ws + OFF_KVW); ld = 512; cb = 2048; }
;       else if (tn < 22) { dst = (u16*)(p.ws + OFF_MQ); ld = 256; cb = 2560; }
;       else if (tn < 24) { dst = (u16*)(p.ws + OFF_MKV); ld = 256; cb = 2816; }
;       else if (tn < 32) { dst = (u16*)(p.ws + OFF_MA); ld = 1024; cb = 3072; }
;       else { dst = (u16*)(p.ws + OFF_MB); ld = 1024; cb = 4096; }
	s_setprio 1
	ds_read_b128 v[36:39], v152 offset:36864
	ds_read_b128 v[162:165], v152 offset:38400
	ds_read_b128 v[174:177], v152 offset:39936
	ds_read_b128 v[178:181], v152 offset:41472
	ds_read_b128 v[0:3], v228 offset:49152
	ds_read_b128 v[4:7], v228 offset:50688
	s_waitcnt lgkmcnt(1)
	v_mfma_f32_16x16x32_bf16 v[124:127], v[36:39], v[0:3], v[148:151]
	v_mfma_f32_16x16x32_bf16 v[80:83], v[162:165], v[0:3], v[136:139]
	v_mfma_f32_16x16x32_bf16 v[28:31], v[174:177], v[0:3], v[112:115]
	v_mfma_f32_16x16x32_bf16 v[0:3], v[178:181], v[0:3], v[170:173]
	ds_read_b128 v[8:11], v228 offset:52224
	s_waitcnt lgkmcnt(1)
	v_mfma_f32_16x16x32_bf16 v[120:123], v[36:39], v[4:7], v[144:147]
	v_mfma_f32_16x16x32_bf16 v[72:75], v[162:165], v[4:7], v[128:131]
	v_mfma_f32_16x16x32_bf16 v[32:35], v[174:177], v[4:7], v[100:103]
	v_mfma_f32_16x16x32_bf16 v[4:7], v[178:181], v[4:7], v[68:71]
	ds_read_b128 v[12:15], v228 offset:53760
	s_waitcnt lgkmcnt(1)
	v_mfma_f32_16x16x32_bf16 v[116:119], v[36:39], v[8:11], v[140:143]
	v_mfma_f32_16x16x32_bf16 v[64:67], v[162:165], v[8:11], v[186:189]
	v_mfma_f32_16x16x32_bf16 v[40:43], v[174:177], v[8:11], v[88:91]
	v_mfma_f32_16x16x32_bf16 v[8:11], v[178:181], v[8:11], v[56:59]
	ds_read_b128 v[16:19], v228 offset:55296
	s_waitcnt lgkmcnt(1)
	v_mfma_f32_16x16x32_bf16 v[112:115], v[36:39], v[12:15], v[132:135]
	v_mfma_f32_16x16x32_bf16 v[68:71], v[162:165], v[12:15], v[108:111]
	v_mfma_f32_16x16x32_bf16 v[44:47], v[174:177], v[12:15], v[76:79]
	v_mfma_f32_16x16x32_bf16 v[12:15], v[178:181], v[12:15], v[182:185]
	ds_read_b128 v[20:23], v228 offset:56832
	s_waitcnt lgkmcnt(1)
	v_mfma_f32_16x16x32_bf16 v[108:111], v[36:39], v[16:19], v[190:193]
	v_mfma_f32_16x16x32_bf16 v[76:79], v[162:165], v[16:19], v[96:99]
	v_mfma_f32_16x16x32_bf16 v[48:51], v[174:177], v[16:19], v[194:197]
	v_mfma_f32_16x16x32_bf16 v[16:19], v[178:181], v[16:19], v[198:201]
	ds_read_b128 v[24:27], v228 offset:58368
	s_waitcnt lgkmcnt(1)
	v_mfma_f32_16x16x32_bf16 v[104:107], v[36:39], v[20:23], v[202:205]
	v_mfma_f32_16x16x32_bf16 v[84:87], v[162:165], v[20:23], v[84:87]
	v_mfma_f32_16x16x32_bf16 v[52:55], v[174:177], v[20:23], v[52:55]
	v_mfma_f32_16x16x32_bf16 v[20:23], v[178:181], v[20:23], v[206:209]
	ds_read_b128 v[128:131], v228 offset:59904
	s_waitcnt lgkmcnt(1)
	v_mfma_f32_16x16x32_bf16 v[100:103], v[36:39], v[24:27], v[210:213]
	v_mfma_f32_16x16x32_bf16 v[88:91], v[162:165], v[24:27], v[214:217]
	v_mfma_f32_16x16x32_bf16 v[56:59], v[174:177], v[24:27], v[220:223]
	v_mfma_f32_16x16x32_bf16 v[24:27], v[178:181], v[24:27], v[224:227]
	s_waitcnt lgkmcnt(0)
	v_mfma_f32_16x16x32_bf16 v[96:99], v[36:39], v[128:131], v[92:95]
	v_mfma_f32_16x16x32_bf16 v[92:95], v[162:165], v[128:131], v[60:63]
	v_mfma_f32_16x16x32_bf16 v[60:63], v[174:177], v[128:131], v[154:157]
	v_mfma_f32_16x16x32_bf16 v[36:39], v[178:181], v[128:131], v[166:169]
	s_setprio 0
	s_cmp_lt_i32 s61, 8
	s_barrier
	s_cbranch_scc1 .LBB0_275
	s_cmp_lt_u32 s61, 12
	s_cselect_b64 s[22:23], -1, 0
	s_or_b64 s[24:25], s[22:23], s[16:17]
	s_and_b64 s[22:23], s[22:23], exec
	s_cselect_b32 s22, s48, 0x17b00800
	s_cselect_b32 s62, s47, 0xfffffa00
	s_add_u32 s22, s42, s22
	s_addc_u32 s23, s43, 0
	s_and_b64 vcc, exec, s[24:25]
	s_cbranch_vccnz .LBB0_276
	s_cmp_lt_u32 s61, 20
	s_cbranch_scc1 .LBB0_277
	s_cmp_lt_u32 s61, 22
	s_cselect_b64 s[22:23], -1, 0
	s_or_b64 s[24:25], s[22:23], s[18:19]
	s_and_b64 s[22:23], s[22:23], exec
	s_cselect_b32 s22, s50, 0x21b00800
	s_cselect_b32 s62, s49, 0xfffff500
	s_add_u32 s22, s42, s22
	s_addc_u32 s23, s43, 0
	s_and_b64 vcc, exec, s[24:25]
	s_cbranch_vccnz .LBB0_278
	s_mov_b64 s[24:25], 0x400
	s_mov_b64 s[22:23], s[20:21]
	s_mov_b32 s62, s55
	s_branch .LBB0_279

; DI int tidx() { int t = __builtin_amdgcn_workitem_id_x(); asm volatile("" : "+v"(t)); return t; }
;   DI unsigned rowoff(int r, int sch) const { const int g = r & 3, bc = r >> 2, b = bc / NCMP, c = bc - b * NCMP; return (unsigned)(b * Sn + c * 16) * 512u + g * 64 + sch; }
; template <int NI, class XL, class EP>
; DI void gemm_tile(const u16* __restrict__ W, int ldw, int f0, int t0, int K, XL xl, EP ep, unsigned char* smem) {
;     ...
;   const int tid = tidx(), lane = tid & 63, wave = tid >> 6;
;   const int wf = wave >> 1, wt = wave & 1, lr = lane & 15, lq = lane >> 4;
;   const int srow = tid >> 2, sch = (tid & 3) * 8;
;   f32x4 acc[4][NI];
; #pragma unroll
;   for (int i = 0; i < 4; ++i)
; #pragma unroll
;     for (int j = 0; j < NI; ++j) acc[i][j] = (f32x4){0.f, 0.f, 0.f, 0.f};
;   u32x4 wr[2], xr[XR];
;   const unsigned wbyte = ((unsigned)(f0 + srow * 2) * 32u + sch) * 2u;
;   const unsigned xbyte = xl.rowoff(t0 + srow * XR, sch) * 2u;
;   const int xrs = xl.rstride();
;   const int nk = K >> 5;
;   auto gload = [&](int it) {
;     const int k = it * 32;
;     const char* wb = (const char*)(W + (size_t)(k >> 5) * ldw * 32);
;     const char* xb = (const char*)xl.kbase(k);
; #pragma unroll
;     for (int i = 0; i < 2; ++i) wr[i] = *(const u32x4*)(wb + wbyte + i * 64);
; #pragma unroll
;     for (int i = 0; i < XR; ++i) xr[i] = *(const u32x4*)(xb + xbyte + i * xrs);
;   };
;   auto lstore = [&](int buf) {
;     u16* Ws = S0 + buf * BUF; u16* Xs = Ws + 128 * LST;
; #pragma unroll
;     for (int i = 0; i < 2; ++i) *(u32x4*)(Ws + (srow * 2 + i) * LST + sch) = wr[i];
; #pragma unroll
;     for (int i = 0; i < XR; ++i) *(u32x4*)(Xs + (srow * XR + i) * LST + sch) = xr[i];
;   };
;   gload(0);
;   __syncthreads();
;   lstore(0);
;   __syncthreads();
;   if (nk > 1) gload(1);
.Lp6_dyn_skip_a:
	v_mov_b32_e32 v46, v218
	s_and_b32 s34, s31, 7
	v_ashrrev_i32_e32 v47, 2, v46
	v_lshlrev_b32_e32 v0, 3, v46
	v_lshlrev_b32_e32 v49, 6, v47
	s_ashr_i32 s37, s31, 3
	v_and_b32_e32 v48, 24, v0
	v_lshl_add_u32 v0, s34, 12, v49
	s_add_i32 s35, s37, s29
	v_or_b32_e32 v0, v0, v48
	s_lshl_b32 s33, s35, 8
	v_lshlrev_b32_e32 v50, 1, v0
	v_and_b32_e32 v0, 0x3fffffc, v46
	v_add_u32_e32 v0, s33, v0
	v_lshlrev_b32_e32 v161, 1, v48
	v_lshl_or_b32 v51, v0, 6, v161
	global_load_dwordx4 v[16:19], v50, s[4:5]
	global_load_dwordx4 v[20:23], v50, s[4:5] offset:64
	global_load_dwordx4 v[24:27], v51, s[16:17]
	global_load_dwordx4 v[28:31], v51, s[16:17] offset:64
	global_load_dwordx4 v[32:35], v51, s[16:17] offset:128
	global_load_dwordx4 v[36:39], v51, s[16:17] offset:192
	v_mul_lo_u32 v166, v47, s22
	v_or_b32_e32 v162, v166, v161
	v_add_u32_e32 v163, v162, v166
	s_barrier
	v_bfe_u32 v158, v46, 4, 2
	v_and_b32_e32 v52, 15, v46
	v_ashrrev_i32_e32 v53, 1, v46
	v_lshlrev_b32_e32 v54, 1, v46
	v_lshlrev_b32_e32 v46, 6, v46
	s_and_b32 s44, s30, 7
	s_add_i32 s37, s20, s37
	v_and_b32_e32 v46, 0xffffff00, v46
	v_and_b32_e32 v160, 0xffffffc0, v53
	v_lshl_add_u32 v46, s37, 14, v46
	v_lshl_add_u32 v49, s44, 12, v49
	v_mov_b32_e32 v0, 0
	v_and_or_b32 v159, v54, s23, v52
	v_or_b32_e32 v47, v160, v52
	v_or_b32_e32 v152, v46, v161
	v_or_b32_e32 v46, v49, v48
	s_mov_b32 s36, 1
	v_mov_b32_e32 v155, v153
	v_mov_b32_e32 v1, v0
	v_mov_b32_e32 v2, v0
	v_mov_b32_e32 v3, v0
	v_mov_b32_e32 v4, v0
	v_mov_b32_e32 v5, v0
	v_mov_b32_e32 v6, v0
	v_mov_b32_e32 v7, v0
	v_mov_b32_e32 v8, v0
	v_mov_b32_e32 v9, v0
	v_mov_b32_e32 v10, v0
	v_mov_b32_e32 v11, v0
	v_mov_b32_e32 v12, v0
	v_mov_b32_e32 v13, v0
	v_mov_b32_e32 v14, v0
	v_mov_b32_e32 v15, v0
	v_mov_b32_e32 v40, v0
	v_mov_b32_e32 v41, v0
	v_mov_b32_e32 v42, v0
	v_mov_b32_e32 v43, v0
	v_mov_b32_e32 v44, v0
	v_mov_b32_e32 v45, v0
	v_lshlrev_b32_e32 v164, 4, v158
	v_mul_u32_u24_e32 v165, 48, v159
	v_mul_lo_u32 v167, v47, 48
	v_lshlrev_b32_e32 v154, 1, v46
	v_mov_b64_e32 v[156:157], v[152:153]
	v_mov_b32_e32 v46, v0
	v_mov_b32_e32 v47, v0
	v_mov_b32_e32 v68, v0
	v_mov_b32_e32 v69, v0
	v_mov_b32_e32 v70, v0
	v_mov_b32_e32 v71, v0
	v_mov_b32_e32 v80, v0
	v_mov_b32_e32 v81, v0
	v_mov_b32_e32 v82, v0
	v_mov_b32_e32 v83, v0
	v_mov_b32_e32 v48, v0
	v_mov_b32_e32 v49, v0
	v_mov_b32_e32 v52, v0
	v_mov_b32_e32 v53, v0
	v_mov_b32_e32 v54, v0
	v_mov_b32_e32 v55, v0
	v_mov_b32_e32 v56, v0
	v_mov_b32_e32 v57, v0
	v_mov_b32_e32 v58, v0
	s_waitcnt vmcnt(5)
	ds_write_b128 v162, v[16:19]
	s_waitcnt vmcnt(4)
	ds_write_b128 v162, v[20:23] offset:96
	s_waitcnt vmcnt(3)
	ds_write_b128 v163, v[24:27] offset:12288
	s_waitcnt vmcnt(2)
	ds_write_b128 v163, v[28:31] offset:12384
	s_waitcnt vmcnt(1)
	ds_write_b128 v163, v[32:35] offset:12480
	s_waitcnt vmcnt(0)
	ds_write_b128 v163, v[36:39] offset:12576
	s_waitcnt lgkmcnt(0)
	global_load_dwordx4 v[20:23], v50, s[8:9]
	global_load_dwordx4 v[16:19], v50, s[8:9] offset:64
	global_load_dwordx4 v[36:39], v51, s[6:7]
	global_load_dwordx4 v[32:35], v51, s[6:7] offset:64
	global_load_dwordx4 v[28:31], v51, s[6:7] offset:128
	global_load_dwordx4 v[24:27], v51, s[6:7] offset:192
	s_add_u32 s98, s42, s24
	s_addc_u32 s99, s43, 0
	s_add_u32 s100, s42, s25
	s_addc_u32 s101, s43, 0
	global_load_dwordx4 v[200:203], v154, s[98:99]
	global_load_dwordx4 v[204:207], v154, s[98:99] offset:64
	global_load_dwordx4 v[208:211], v156, s[100:101] offset:2048
	global_load_dwordx4 v[212:215], v156, s[100:101] offset:2112
	global_load_dwordx4 v[220:223], v156, s[100:101] offset:2176
	global_load_dwordx4 v[224:227], v156, s[100:101] offset:2240
	s_add_u32 s98, s98, s18
	s_addc_u32 s99, s99, s19
	s_add_u32 s100, s100, s10
	s_addc_u32 s101, s101, s11
	v_mov_b32_e32 v50, v0
	v_mov_b32_e32 v51, v0
	v_mov_b32_e32 v59, v0
	v_mov_b32_e32 v64, v0
	v_mov_b32_e32 v65, v0
	v_mov_b32_e32 v66, v0
	v_mov_b32_e32 v67, v0
	v_mov_b32_e32 v76, v0
	v_mov_b32_e32 v77, v0
	v_mov_b32_e32 v78, v0
	v_mov_b32_e32 v79, v0
	v_mov_b32_e32 v88, v0
	v_mov_b32_e32 v89, v0
	v_mov_b32_e32 v90, v0
	v_mov_b32_e32 v91, v0
	v_mov_b32_e32 v100, v0
	v_mov_b32_e32 v101, v0
	v_mov_b32_e32 v102, v0
	v_mov_b32_e32 v103, v0
	v_mov_b32_e32 v112, v0
	v_mov_b32_e32 v113, v0
	v_mov_b32_e32 v114, v0
	v_mov_b32_e32 v115, v0
	v_mov_b32_e32 v60, v0
	v_mov_b32_e32 v61, v0
	v_mov_b32_e32 v62, v0
	v_mov_b32_e32 v63, v0
	v_mov_b32_e32 v72, v0
	v_mov_b32_e32 v73, v0
	v_mov_b32_e32 v74, v0
	v_mov_b32_e32 v75, v0
	v_mov_b32_e32 v84, v0
	v_mov_b32_e32 v85, v0
	v_mov_b32_e32 v86, v0
	v_mov_b32_e32 v87, v0
	v_mov_b32_e32 v96, v0
	v_mov_b32_e32 v97, v0
	v_mov_b32_e32 v98, v0
	v_mov_b32_e32 v99, v0
	v_mov_b32_e32 v108, v0
	v_mov_b32_e32 v109, v0
	v_mov_b32_e32 v110, v0
	v_mov_b32_e32 v111, v0
	v_mov_b32_e32 v120, v0
	v_mov_b32_e32 v121, v0
	v_mov_b32_e32 v122, v0
	v_mov_b32_e32 v123, v0
	v_mov_b32_e32 v128, v0
	v_mov_b32_e32 v129, v0
	v_mov_b32_e32 v130, v0
	v_mov_b32_e32 v131, v0
	v_mov_b32_e32 v136, v0
	v_mov_b32_e32 v137, v0
	v_mov_b32_e32 v138, v0
	v_mov_b32_e32 v139, v0
	v_mov_b32_e32 v92, v0
	v_mov_b32_e32 v93, v0
	v_mov_b32_e32 v94, v0
	v_mov_b32_e32 v95, v0
	v_mov_b32_e32 v104, v0
	v_mov_b32_e32 v105, v0
	v_mov_b32_e32 v106, v0
	v_mov_b32_e32 v107, v0
	v_mov_b32_e32 v116, v0
	v_mov_b32_e32 v117, v0
	v_mov_b32_e32 v118, v0
	v_mov_b32_e32 v119, v0
	v_mov_b32_e32 v124, v0
	v_mov_b32_e32 v125, v0
	v_mov_b32_e32 v126, v0
	v_mov_b32_e32 v127, v0
	v_mov_b32_e32 v132, v0
	v_mov_b32_e32 v133, v0
	v_mov_b32_e32 v134, v0
	v_mov_b32_e32 v135, v0
	v_mov_b32_e32 v140, v0
	v_mov_b32_e32 v141, v0
	v_mov_b32_e32 v142, v0
	v_mov_b32_e32 v143, v0
	v_mov_b32_e32 v144, v0
	v_mov_b32_e32 v145, v0
	v_mov_b32_e32 v146, v0
	v_mov_b32_e32 v147, v0
	v_mov_b32_e32 v148, v0
	v_mov_b32_e32 v149, v0
	v_mov_b32_e32 v150, v0
	v_mov_b32_e32 v151, v0
	v_lshl_add_u32 v228, v167, 1, v164
	v_lshl_add_u32 v152, v165, 1, v164
	v_add_u32_e32 v229, v166, v161
	v_add_u32_e32 v230, v229, v166
; DI f32x4 mfma16(bf16x8 a, bf16x8 b, f32x4 c) { return __builtin_amdgcn_mfma_f32_16x16x32_bf16(a, b, c, 0, 0, 0); }
; template <int NI, class XL, class EP>
; DI void gemm_tile(const u16* __restrict__ W, int ldw, int f0, int t0, int K, XL xl, EP ep, unsigned char* smem) {
;     ...
;   for (int it = 0; it < nk; ++it) {
;     const u16* Ws = S0 + (it & 1) * BUF; const u16* Xs = Ws + 128 * LST;
;     __builtin_amdgcn_s_setprio(1);
;     bf16x8 a[4];
; #pragma unroll
;     for (int mi = 0; mi < 4; ++mi) a[mi] = *(const bf16x8*)(Ws + (wf * 64 + mi * 16 + lr) * LST + lq * 8);
; #pragma unroll
;     for (int ni = 0; ni < NI; ++ni) {
;       const bf16x8 b = *(const bf16x8*)(Xs + (wt * (NI * 16) + ni * 16 + lr) * LST + lq * 8);
; #pragma unroll
;       for (int mi = 0; mi < 4; ++mi) acc[mi][ni] = mfma16(a[mi], b, acc[mi][ni]);
;     }
;     __builtin_amdgcn_sched_group_barrier(0x100, 6, 0);
; #pragma unroll
;     for (int ni = 0; ni < NI; ++ni) { __builtin_amdgcn_sched_group_barrier(0x008, 4, 0); if (ni + 2 < NI) __builtin_amdgcn_sched_group_barrier(0x100, 1, 0); }
;     __builtin_amdgcn_s_setprio(0);
;     if (it + 1 < nk) lstore((it + 1) & 1);
;     if (it + 2 < nk) gload(it + 2);
;     __syncthreads();
.LBB0_812:
	s_barrier
	s_setprio 1
	ds_read_b128 v[168:171], v228 offset:0
	ds_read_b128 v[172:175], v228 offset:1536
	ds_read_b128 v[180:183], v228 offset:3072
	ds_read_b128 v[184:187], v228 offset:4608
	ds_read_b128 v[176:179], v152 offset:12288
	ds_read_b128 v[188:191], v152 offset:13824
	s_waitcnt lgkmcnt(1)
	v_mfma_f32_16x16x32_bf16 v[148:151], v[168:171], v[176:179], v[148:151]
	v_mfma_f32_16x16x32_bf16 v[136:139], v[172:175], v[176:179], v[136:139]
	v_mfma_f32_16x16x32_bf16 v[112:115], v[180:183], v[176:179], v[112:115]
	v_mfma_f32_16x16x32_bf16 v[80:83], v[184:187], v[176:179], v[80:83]
	ds_read_b128 v[176:179], v152 offset:15360
	s_waitcnt vmcnt(6)
	ds_write_b128 v229, v[20:23] offset:36864
	s_waitcnt lgkmcnt(2)
	v_mfma_f32_16x16x32_bf16 v[144:147], v[168:171], v[188:191], v[144:147]
	v_mfma_f32_16x16x32_bf16 v[128:131], v[172:175], v[188:191], v[128:131]
	v_mfma_f32_16x16x32_bf16 v[100:103], v[180:183], v[188:191], v[100:103]
	v_mfma_f32_16x16x32_bf16 v[68:71], v[184:187], v[188:191], v[68:71]
	ds_read_b128 v[188:191], v152 offset:16896
	ds_write_b128 v229, v[16:19] offset:36960
	global_load_dwordx4 v[20:23], v154, s[98:99]
	global_load_dwordx4 v[16:19], v154, s[98:99] offset:64
	s_waitcnt lgkmcnt(3)
	v_mfma_f32_16x16x32_bf16 v[140:143], v[168:171], v[176:179], v[140:143]
	v_mfma_f32_16x16x32_bf16 v[120:123], v[172:175], v[176:179], v[120:123]
	v_mfma_f32_16x16x32_bf16 v[88:91], v[180:183], v[176:179], v[88:91]
	v_mfma_f32_16x16x32_bf16 v[44:47], v[184:187], v[176:179], v[44:47]
	ds_read_b128 v[176:179], v152 offset:18432
	ds_write_b128 v230, v[36:39] offset:49152
	global_load_dwordx4 v[36:39], v156, s[100:101] offset:2048
	s_waitcnt lgkmcnt(3)
	v_mfma_f32_16x16x32_bf16 v[132:135], v[168:171], v[188:191], v[132:135]
	v_mfma_f32_16x16x32_bf16 v[108:111], v[172:175], v[188:191], v[108:111]
	v_mfma_f32_16x16x32_bf16 v[76:79], v[180:183], v[188:191], v[76:79]
	v_mfma_f32_16x16x32_bf16 v[40:43], v[184:187], v[188:191], v[40:43]
	ds_read_b128 v[188:191], v152 offset:19968
	ds_write_b128 v230, v[32:35] offset:49248
	global_load_dwordx4 v[32:35], v156, s[100:101] offset:2112
	s_waitcnt lgkmcnt(3)
	v_mfma_f32_16x16x32_bf16 v[124:127], v[168:171], v[176:179], v[124:127]
	v_mfma_f32_16x16x32_bf16 v[96:99], v[172:175], v[176:179], v[96:99]
	v_mfma_f32_16x16x32_bf16 v[64:67], v[180:183], v[176:179], v[64:67]
	v_mfma_f32_16x16x32_bf16 v[12:15], v[184:187], v[176:179], v[12:15]
	ds_read_b128 v[176:179], v152 offset:21504
	ds_write_b128 v230, v[28:31] offset:49344
	global_load_dwordx4 v[28:31], v156, s[100:101] offset:2176
	s_waitcnt lgkmcnt(3)
	v_mfma_f32_16x16x32_bf16 v[116:119], v[168:171], v[188:191], v[116:119]
	v_mfma_f32_16x16x32_bf16 v[84:87], v[172:175], v[188:191], v[84:87]
	v_mfma_f32_16x16x32_bf16 v[56:59], v[180:183], v[188:191], v[56:59]
	v_mfma_f32_16x16x32_bf16 v[8:11], v[184:187], v[188:191], v[8:11]
	ds_read_b128 v[188:191], v152 offset:23040
	ds_write_b128 v230, v[24:27] offset:49440
	global_load_dwordx4 v[24:27], v156, s[100:101] offset:2240
	s_waitcnt lgkmcnt(3)
	v_mfma_f32_16x16x32_bf16 v[104:107], v[168:171], v[176:179], v[104:107]
	v_mfma_f32_16x16x32_bf16 v[72:75], v[172:175], v[176:179], v[72:75]
	v_mfma_f32_16x16x32_bf16 v[52:55], v[180:183], v[176:179], v[52:55]
	v_mfma_f32_16x16x32_bf16 v[4:7], v[184:187], v[176:179], v[4:7]
	s_add_u32 s98, s98, s18
	s_addc_u32 s99, s99, s19
	s_add_u32 s100, s100, s10
	s_addc_u32 s101, s101, s11
	s_waitcnt lgkmcnt(1)
	v_mfma_f32_16x16x32_bf16 v[92:95], v[168:171], v[188:191], v[92:95]
	v_mfma_f32_16x16x32_bf16 v[60:63], v[172:175], v[188:191], v[60:63]
	v_mfma_f32_16x16x32_bf16 v[48:51], v[180:183], v[188:191], v[48:51]
	v_mfma_f32_16x16x32_bf16 v[0:3], v[184:187], v[188:191], v[0:3]
	s_setprio 0
	s_waitcnt lgkmcnt(0)
	s_barrier
	s_setprio 1
	ds_read_b128 v[168:171], v228 offset:36864
	ds_read_b128 v[172:175], v228 offset:38400
	ds_read_b128 v[180:183], v228 offset:39936
	ds_read_b128 v[184:187], v228 offset:41472
	ds_read_b128 v[176:179], v152 offset:49152
	ds_read_b128 v[188:191], v152 offset:50688
	s_waitcnt lgkmcnt(1)
	v_mfma_f32_16x16x32_bf16 v[148:151], v[168:171], v[176:179], v[148:151]
	v_mfma_f32_16x16x32_bf16 v[136:139], v[172:175], v[176:179], v[136:139]
	v_mfma_f32_16x16x32_bf16 v[112:115], v[180:183], v[176:179], v[112:115]
	v_mfma_f32_16x16x32_bf16 v[80:83], v[184:187], v[176:179], v[80:83]
	ds_read_b128 v[176:179], v152 offset:52224
	s_waitcnt vmcnt(6)
	ds_write_b128 v229, v[200:203] offset:0
	s_waitcnt lgkmcnt(2)
	v_mfma_f32_16x16x32_bf16 v[144:147], v[168:171], v[188:191], v[144:147]
	v_mfma_f32_16x16x32_bf16 v[128:131], v[172:175], v[188:191], v[128:131]
	v_mfma_f32_16x16x32_bf16 v[100:103], v[180:183], v[188:191], v[100:103]
	v_mfma_f32_16x16x32_bf16 v[68:71], v[184:187], v[188:191], v[68:71]
	ds_read_b128 v[188:191], v152 offset:53760
	ds_write_b128 v229, v[204:207] offset:96
	global_load_dwordx4 v[200:203], v154, s[98:99]
	global_load_dwordx4 v[204:207], v154, s[98:99] offset:64
	s_waitcnt lgkmcnt(3)
	v_mfma_f32_16x16x32_bf16 v[140:143], v[168:171], v[176:179], v[140:143]
	v_mfma_f32_16x16x32_bf16 v[120:123], v[172:175], v[176:179], v[120:123]
	v_mfma_f32_16x16x32_bf16 v[88:91], v[180:183], v[176:179], v[88:91]
	v_mfma_f32_16x16x32_bf16 v[44:47], v[184:187], v[176:179], v[44:47]
	ds_read_b128 v[176:179], v152 offset:55296
	ds_write_b128 v230, v[208:211] offset:12288
	global_load_dwordx4 v[208:211], v156, s[100:101] offset:2048
	s_waitcnt lgkmcnt(3)
; DI f32x4 mfma16(bf16x8 a, bf16x8 b, f32x4 c) { return __builtin_amdgcn_mfma_f32_16x16x32_bf16(a, b, c, 0, 0, 0); }
; template <int NI, class XL, class EP>
; DI void gemm_tile(const u16* __restrict__ W, int ldw, int f0, int t0, int K, XL xl, EP ep, unsigned char* smem) {
;     ...
;   for (int it = 0; it < nk; ++it) {
;     const u16* Ws = S0 + (it & 1) * BUF; const u16* Xs = Ws + 128 * LST;
;     __builtin_amdgcn_s_setprio(1);
;     bf16x8 a[4];
; #pragma unroll
;     for (int mi = 0; mi < 4; ++mi) a[mi] = *(const bf16x8*)(Ws + (wf * 64 + mi * 16 + lr) * LST + lq * 8);
; #pragma unroll
;     for (int ni = 0; ni < NI; ++ni) {
;       const bf16x8 b = *(const bf16x8*)(Xs + (wt * (NI * 16) + ni * 16 + lr) * LST + lq * 8);
; #pragma unroll
;       for (int mi = 0; mi < 4; ++mi) acc[mi][ni] = mfma16(a[mi], b, acc[mi][ni]);
;     }
;     __builtin_amdgcn_sched_group_barrier(0x100, 6, 0);
; #pragma unroll
;     for (int ni = 0; ni < NI; ++ni) { __builtin_amdgcn_sched_group_barrier(0x008, 4, 0); if (ni + 2 < NI) __builtin_amdgcn_sched_group_barrier(0x100, 1, 0); }
;     __builtin_amdgcn_s_setprio(0);
;     if (it + 1 < nk) lstore((it + 1) & 1);
;     if (it + 2 < nk) gload(it + 2);
;     __syncthreads();
	v_mfma_f32_16x16x32_bf16 v[132:135], v[168:171], v[188:191], v[132:135]
	v_mfma_f32_16x16x32_bf16 v[108:111], v[172:175], v[188:191], v[108:111]
	v_mfma_f32_16x16x32_bf16 v[76:79], v[180:183], v[188:191], v[76:79]
	v_mfma_f32_16x16x32_bf16 v[40:43], v[184:187], v[188:191], v[40:43]
	ds_read_b128 v[188:191], v152 offset:56832
	ds_write_b128 v230, v[212:215] offset:12384
	global_load_dwordx4 v[212:215], v156, s[100:101] offset:2112
	s_waitcnt lgkmcnt(3)
	v_mfma_f32_16x16x32_bf16 v[124:127], v[168:171], v[176:179], v[124:127]
	v_mfma_f32_16x16x32_bf16 v[96:99], v[172:175], v[176:179], v[96:99]
	v_mfma_f32_16x16x32_bf16 v[64:67], v[180:183], v[176:179], v[64:67]
	v_mfma_f32_16x16x32_bf16 v[12:15], v[184:187], v[176:179], v[12:15]
	ds_read_b128 v[176:179], v152 offset:58368
	ds_write_b128 v230, v[220:223] offset:12480
	global_load_dwordx4 v[220:223], v156, s[100:101] offset:2176
	s_waitcnt lgkmcnt(3)
	v_mfma_f32_16x16x32_bf16 v[116:119], v[168:171], v[188:191], v[116:119]
	v_mfma_f32_16x16x32_bf16 v[84:87], v[172:175], v[188:191], v[84:87]
	v_mfma_f32_16x16x32_bf16 v[56:59], v[180:183], v[188:191], v[56:59]
	v_mfma_f32_16x16x32_bf16 v[8:11], v[184:187], v[188:191], v[8:11]
	ds_read_b128 v[188:191], v152 offset:59904
	ds_write_b128 v230, v[224:227] offset:12576
	global_load_dwordx4 v[224:227], v156, s[100:101] offset:2240
	s_waitcnt lgkmcnt(3)
	v_mfma_f32_16x16x32_bf16 v[104:107], v[168:171], v[176:179], v[104:107]
	v_mfma_f32_16x16x32_bf16 v[72:75], v[172:175], v[176:179], v[72:75]
	v_mfma_f32_16x16x32_bf16 v[52:55], v[180:183], v[176:179], v[52:55]
	v_mfma_f32_16x16x32_bf16 v[4:7], v[184:187], v[176:179], v[4:7]
	s_add_u32 s98, s98, s18
	s_addc_u32 s99, s99, s19
	s_add_u32 s100, s100, s10
	s_addc_u32 s101, s101, s11
	s_add_i32 s36, s36, 2
	s_waitcnt lgkmcnt(1)
	v_mfma_f32_16x16x32_bf16 v[92:95], v[168:171], v[188:191], v[92:95]
	v_mfma_f32_16x16x32_bf16 v[60:63], v[172:175], v[188:191], v[60:63]
	v_mfma_f32_16x16x32_bf16 v[48:51], v[180:183], v[188:191], v[48:51]
	v_mfma_f32_16x16x32_bf16 v[0:3], v[184:187], v[188:191], v[0:3]
	s_setprio 0
	s_cmp_lg_u32 s36, 29
	s_waitcnt lgkmcnt(0)
	s_cbranch_scc1 .LBB0_812
	s_barrier
	s_setprio 1
	ds_read_b128 v[168:171], v228 offset:0
	ds_read_b128 v[172:175], v228 offset:1536
	ds_read_b128 v[180:183], v228 offset:3072
	ds_read_b128 v[184:187], v228 offset:4608
	ds_read_b128 v[176:179], v152 offset:12288
	ds_read_b128 v[188:191], v152 offset:13824
	s_waitcnt lgkmcnt(1)
	v_mfma_f32_16x16x32_bf16 v[148:151], v[168:171], v[176:179], v[148:151]
	v_mfma_f32_16x16x32_bf16 v[136:139], v[172:175], v[176:179], v[136:139]
	v_mfma_f32_16x16x32_bf16 v[112:115], v[180:183], v[176:179], v[112:115]
	v_mfma_f32_16x16x32_bf16 v[80:83], v[184:187], v[176:179], v[80:83]
	ds_read_b128 v[176:179], v152 offset:15360
	s_waitcnt vmcnt(6)
	ds_write_b128 v229, v[20:23] offset:36864
	s_waitcnt lgkmcnt(2)
	v_mfma_f32_16x16x32_bf16 v[144:147], v[168:171], v[188:191], v[144:147]
	v_mfma_f32_16x16x32_bf16 v[128:131], v[172:175], v[188:191], v[128:131]
	v_mfma_f32_16x16x32_bf16 v[100:103], v[180:183], v[188:191], v[100:103]
	v_mfma_f32_16x16x32_bf16 v[68:71], v[184:187], v[188:191], v[68:71]
	ds_read_b128 v[188:191], v152 offset:16896
	ds_write_b128 v229, v[16:19] offset:36960
	global_load_dwordx4 v[20:23], v154, s[98:99]
	global_load_dwordx4 v[16:19], v154, s[98:99] offset:64
	s_waitcnt lgkmcnt(3)
	v_mfma_f32_16x16x32_bf16 v[140:143], v[168:171], v[176:179], v[140:143]
	v_mfma_f32_16x16x32_bf16 v[120:123], v[172:175], v[176:179], v[120:123]
	v_mfma_f32_16x16x32_bf16 v[88:91], v[180:183], v[176:179], v[88:91]
	v_mfma_f32_16x16x32_bf16 v[44:47], v[184:187], v[176:179], v[44:47]
	ds_read_b128 v[176:179], v152 offset:18432
	ds_write_b128 v230, v[36:39] offset:49152
	global_load_dwordx4 v[36:39], v156, s[100:101] offset:2048
	s_waitcnt lgkmcnt(3)
	v_mfma_f32_16x16x32_bf16 v[132:135], v[168:171], v[188:191], v[132:135]
	v_mfma_f32_16x16x32_bf16 v[108:111], v[172:175], v[188:191], v[108:111]
	v_mfma_f32_16x16x32_bf16 v[76:79], v[180:183], v[188:191], v[76:79]
	v_mfma_f32_16x16x32_bf16 v[40:43], v[184:187], v[188:191], v[40:43]
	ds_read_b128 v[188:191], v152 offset:19968
	ds_write_b128 v230, v[32:35] offset:49248
	global_load_dwordx4 v[32:35], v156, s[100:101] offset:2112
	s_waitcnt lgkmcnt(3)
	v_mfma_f32_16x16x32_bf16 v[124:127], v[168:171], v[176:179], v[124:127]
	v_mfma_f32_16x16x32_bf16 v[96:99], v[172:175], v[176:179], v[96:99]
	v_mfma_f32_16x16x32_bf16 v[64:67], v[180:183], v[176:179], v[64:67]
	v_mfma_f32_16x16x32_bf16 v[12:15], v[184:187], v[176:179], v[12:15]
	ds_read_b128 v[176:179], v152 offset:21504
	ds_write_b128 v230, v[28:31] offset:49344
	global_load_dwordx4 v[28:31], v156, s[100:101] offset:2176
	s_waitcnt lgkmcnt(3)
	v_mfma_f32_16x16x32_bf16 v[116:119], v[168:171], v[188:191], v[116:119]
	v_mfma_f32_16x16x32_bf16 v[84:87], v[172:175], v[188:191], v[84:87]
	v_mfma_f32_16x16x32_bf16 v[56:59], v[180:183], v[188:191], v[56:59]
	v_mfma_f32_16x16x32_bf16 v[8:11], v[184:187], v[188:191], v[8:11]
	ds_read_b128 v[188:191], v152 offset:23040
	ds_write_b128 v230, v[24:27] offset:49440
	global_load_dwordx4 v[24:27], v156, s[100:101] offset:2240
	s_waitcnt lgkmcnt(3)
	v_mfma_f32_16x16x32_bf16 v[104:107], v[168:171], v[176:179], v[104:107]
	v_mfma_f32_16x16x32_bf16 v[72:75], v[172:175], v[176:179], v[72:75]
	v_mfma_f32_16x16x32_bf16 v[52:55], v[180:183], v[176:179], v[52:55]
	v_mfma_f32_16x16x32_bf16 v[4:7], v[184:187], v[176:179], v[4:7]
	s_add_u32 s98, s98, s18
	s_addc_u32 s99, s99, s19
	s_add_u32 s100, s100, s10
	s_addc_u32 s101, s101, s11
	s_waitcnt lgkmcnt(1)
	v_mfma_f32_16x16x32_bf16 v[92:95], v[168:171], v[188:191], v[92:95]
	v_mfma_f32_16x16x32_bf16 v[60:63], v[172:175], v[188:191], v[60:63]
	v_mfma_f32_16x16x32_bf16 v[48:51], v[180:183], v[188:191], v[48:51]
	v_mfma_f32_16x16x32_bf16 v[0:3], v[184:187], v[188:191], v[0:3]
	s_setprio 0
	s_waitcnt lgkmcnt(0)
	s_barrier
; DI f32x4 mfma16(bf16x8 a, bf16x8 b, f32x4 c) { return __builtin_amdgcn_mfma_f32_16x16x32_bf16(a, b, c, 0, 0, 0); }
; template <int NI, class XL, class EP>
; DI void gemm_tile(const u16* __restrict__ W, int ldw, int f0, int t0, int K, XL xl, EP ep, unsigned char* smem) {
;     ...
;   for (int it = 0; it < nk; ++it) {
;     const u16* Ws = S0 + (it & 1) * BUF; const u16* Xs = Ws + 128 * LST;
;     __builtin_amdgcn_s_setprio(1);
;     bf16x8 a[4];
; #pragma unroll
;     for (int mi = 0; mi < 4; ++mi) a[mi] = *(const bf16x8*)(Ws + (wf * 64 + mi * 16 + lr) * LST + lq * 8);
; #pragma unroll
;     for (int ni = 0; ni < NI; ++ni) {
;       const bf16x8 b = *(const bf16x8*)(Xs + (wt * (NI * 16) + ni * 16 + lr) * LST + lq * 8);
; #pragma unroll
;       for (int mi = 0; mi < 4; ++mi) acc[mi][ni] = mfma16(a[mi], b, acc[mi][ni]);
;     }
;     __builtin_amdgcn_sched_group_barrier(0x100, 6, 0);
; #pragma unroll
;     for (int ni = 0; ni < NI; ++ni) { __builtin_amdgcn_sched_group_barrier(0x008, 4, 0); if (ni + 2 < NI) __builtin_amdgcn_sched_group_barrier(0x100, 1, 0); }
;     __builtin_amdgcn_s_setprio(0);
;     if (it + 1 < nk) lstore((it + 1) & 1);
;     if (it + 2 < nk) gload(it + 2);
;     __syncthreads();
	s_setprio 1
	ds_read_b128 v[168:171], v228 offset:36864
	ds_read_b128 v[172:175], v228 offset:38400
	ds_read_b128 v[180:183], v228 offset:39936
	ds_read_b128 v[184:187], v228 offset:41472
	ds_read_b128 v[176:179], v152 offset:49152
	ds_read_b128 v[188:191], v152 offset:50688
	s_waitcnt lgkmcnt(1)
	v_mfma_f32_16x16x32_bf16 v[148:151], v[168:171], v[176:179], v[148:151]
	v_mfma_f32_16x16x32_bf16 v[136:139], v[172:175], v[176:179], v[136:139]
	v_mfma_f32_16x16x32_bf16 v[112:115], v[180:183], v[176:179], v[112:115]
	v_mfma_f32_16x16x32_bf16 v[80:83], v[184:187], v[176:179], v[80:83]
	ds_read_b128 v[176:179], v152 offset:52224
	s_waitcnt vmcnt(6)
	ds_write_b128 v229, v[200:203] offset:0
	s_waitcnt lgkmcnt(2)
	v_mfma_f32_16x16x32_bf16 v[144:147], v[168:171], v[188:191], v[144:147]
	v_mfma_f32_16x16x32_bf16 v[128:131], v[172:175], v[188:191], v[128:131]
	v_mfma_f32_16x16x32_bf16 v[100:103], v[180:183], v[188:191], v[100:103]
	v_mfma_f32_16x16x32_bf16 v[68:71], v[184:187], v[188:191], v[68:71]
	ds_read_b128 v[188:191], v152 offset:53760
	ds_write_b128 v229, v[204:207] offset:96
	s_waitcnt lgkmcnt(3)
	v_mfma_f32_16x16x32_bf16 v[140:143], v[168:171], v[176:179], v[140:143]
	v_mfma_f32_16x16x32_bf16 v[120:123], v[172:175], v[176:179], v[120:123]
	v_mfma_f32_16x16x32_bf16 v[88:91], v[180:183], v[176:179], v[88:91]
	v_mfma_f32_16x16x32_bf16 v[44:47], v[184:187], v[176:179], v[44:47]
	ds_read_b128 v[176:179], v152 offset:55296
	ds_write_b128 v230, v[208:211] offset:12288
	s_waitcnt lgkmcnt(3)
	v_mfma_f32_16x16x32_bf16 v[132:135], v[168:171], v[188:191], v[132:135]
	v_mfma_f32_16x16x32_bf16 v[108:111], v[172:175], v[188:191], v[108:111]
	v_mfma_f32_16x16x32_bf16 v[76:79], v[180:183], v[188:191], v[76:79]
	v_mfma_f32_16x16x32_bf16 v[40:43], v[184:187], v[188:191], v[40:43]
	ds_read_b128 v[188:191], v152 offset:56832
	ds_write_b128 v230, v[212:215] offset:12384
	s_waitcnt lgkmcnt(3)
	v_mfma_f32_16x16x32_bf16 v[124:127], v[168:171], v[176:179], v[124:127]
	v_mfma_f32_16x16x32_bf16 v[96:99], v[172:175], v[176:179], v[96:99]
	v_mfma_f32_16x16x32_bf16 v[64:67], v[180:183], v[176:179], v[64:67]
	v_mfma_f32_16x16x32_bf16 v[12:15], v[184:187], v[176:179], v[12:15]
	ds_read_b128 v[176:179], v152 offset:58368
	ds_write_b128 v230, v[220:223] offset:12480
	s_waitcnt lgkmcnt(3)
	v_mfma_f32_16x16x32_bf16 v[116:119], v[168:171], v[188:191], v[116:119]
	v_mfma_f32_16x16x32_bf16 v[84:87], v[172:175], v[188:191], v[84:87]
	v_mfma_f32_16x16x32_bf16 v[56:59], v[180:183], v[188:191], v[56:59]
	v_mfma_f32_16x16x32_bf16 v[8:11], v[184:187], v[188:191], v[8:11]
	ds_read_b128 v[188:191], v152 offset:59904
	ds_write_b128 v230, v[224:227] offset:12576
	s_waitcnt lgkmcnt(3)
	v_mfma_f32_16x16x32_bf16 v[104:107], v[168:171], v[176:179], v[104:107]
	v_mfma_f32_16x16x32_bf16 v[72:75], v[172:175], v[176:179], v[72:75]
	v_mfma_f32_16x16x32_bf16 v[52:55], v[180:183], v[176:179], v[52:55]
	v_mfma_f32_16x16x32_bf16 v[4:7], v[184:187], v[176:179], v[4:7]
	s_add_i32 s36, s36, 2
	s_waitcnt lgkmcnt(1)
	v_mfma_f32_16x16x32_bf16 v[92:95], v[168:171], v[188:191], v[92:95]
	v_mfma_f32_16x16x32_bf16 v[60:63], v[172:175], v[188:191], v[60:63]
	v_mfma_f32_16x16x32_bf16 v[48:51], v[180:183], v[188:191], v[48:51]
	v_mfma_f32_16x16x32_bf16 v[0:3], v[184:187], v[188:191], v[0:3]
	s_setprio 0
	s_waitcnt lgkmcnt(0)
	s_barrier
	s_setprio 1
	v_lshl_add_u32 v152, v167, 1, v164
	ds_read_b128 v[154:157], v152
	v_lshl_add_u32 v161, v165, 1, v164
	ds_read_b128 v[164:167], v152 offset:1536
	ds_read_b128 v[172:175], v152 offset:3072
	ds_read_b128 v[176:179], v152 offset:4608
	ds_read_b128 v[168:171], v161 offset:12288
	ds_read_b128 v[180:183], v161 offset:13824
	s_waitcnt lgkmcnt(1)
	v_mfma_f32_16x16x32_bf16 v[148:151], v[154:157], v[168:171], v[148:151]
	v_mfma_f32_16x16x32_bf16 v[136:139], v[164:167], v[168:171], v[136:139]
	v_mfma_f32_16x16x32_bf16 v[112:115], v[172:175], v[168:171], v[112:115]
	v_mfma_f32_16x16x32_bf16 v[80:83], v[176:179], v[168:171], v[80:83]
	ds_read_b128 v[168:171], v161 offset:15360
	s_waitcnt vmcnt(5)
	ds_write_b128 v162, v[20:23] offset:36864
	s_waitcnt lgkmcnt(2)
	v_mfma_f32_16x16x32_bf16 v[144:147], v[154:157], v[180:183], v[144:147]
	v_mfma_f32_16x16x32_bf16 v[128:131], v[164:167], v[180:183], v[128:131]
	v_mfma_f32_16x16x32_bf16 v[100:103], v[172:175], v[180:183], v[100:103]
	v_mfma_f32_16x16x32_bf16 v[68:71], v[176:179], v[180:183], v[68:71]
	ds_read_b128 v[180:183], v161 offset:16896
	s_waitcnt vmcnt(4)
	ds_write_b128 v162, v[16:19] offset:36960
	s_waitcnt lgkmcnt(3)
	v_mfma_f32_16x16x32_bf16 v[140:143], v[154:157], v[168:171], v[140:143]
	v_mfma_f32_16x16x32_bf16 v[120:123], v[164:167], v[168:171], v[120:123]
	v_mfma_f32_16x16x32_bf16 v[184:187], v[172:175], v[168:171], v[88:91]
	v_mfma_f32_16x16x32_bf16 v[44:47], v[176:179], v[168:171], v[44:47]
	s_nop 1
	ds_read_b128 v[88:91], v161 offset:18432
	s_waitcnt vmcnt(3)
	ds_write_b128 v163, v[36:39] offset:49152
	s_waitcnt lgkmcnt(3)
	v_mfma_f32_16x16x32_bf16 v[132:135], v[154:157], v[180:183], v[132:135]
	v_mfma_f32_16x16x32_bf16 v[168:171], v[164:167], v[180:183], v[108:111]
	v_mfma_f32_16x16x32_bf16 v[188:191], v[172:175], v[180:183], v[76:79]
	v_mfma_f32_16x16x32_bf16 v[180:183], v[176:179], v[180:183], v[40:43]
	s_nop 2
	ds_read_b128 v[40:43], v161 offset:19968
	s_waitcnt vmcnt(2)
	ds_write_b128 v163, v[32:35] offset:49248
	s_waitcnt lgkmcnt(3)
	v_mfma_f32_16x16x32_bf16 v[124:127], v[154:157], v[88:91], v[124:127]
	v_mfma_f32_16x16x32_bf16 v[192:195], v[164:167], v[88:91], v[96:99]
	v_mfma_f32_16x16x32_bf16 v[196:199], v[172:175], v[88:91], v[64:67]
	v_mfma_f32_16x16x32_bf16 v[200:203], v[176:179], v[88:91], v[12:15]
	s_nop 2
	ds_read_b128 v[12:15], v161 offset:21504
	s_waitcnt vmcnt(1)
	ds_write_b128 v163, v[28:31] offset:49344
	s_waitcnt lgkmcnt(3)
	v_mfma_f32_16x16x32_bf16 v[116:119], v[154:157], v[40:43], v[116:119]
	v_mfma_f32_16x16x32_bf16 v[204:207], v[164:167], v[40:43], v[84:87]
	v_mfma_f32_16x16x32_bf16 v[56:59], v[172:175], v[40:43], v[56:59]
	v_mfma_f32_16x16x32_bf16 v[208:211], v[176:179], v[40:43], v[8:11]
	s_nop 2
	ds_read_b128 v[8:11], v161 offset:23040
	s_waitcnt vmcnt(0)
	ds_write_b128 v163, v[24:27] offset:49440
	s_waitcnt lgkmcnt(3)
	v_mfma_f32_16x16x32_bf16 v[212:215], v[154:157], v[12:15], v[104:107]
	v_mfma_f32_16x16x32_bf16 v[72:75], v[164:167], v[12:15], v[72:75]
	v_mfma_f32_16x16x32_bf16 v[220:223], v[172:175], v[12:15], v[52:55]
	v_mfma_f32_16x16x32_bf16 v[224:227], v[176:179], v[12:15], v[4:7]
	s_waitcnt lgkmcnt(1)
	v_mfma_f32_16x16x32_bf16 v[154:157], v[154:157], v[8:11], v[92:95]
	v_mfma_f32_16x16x32_bf16 v[60:63], v[164:167], v[8:11], v[60:63]
	v_mfma_f32_16x16x32_bf16 v[164:167], v[172:175], v[8:11], v[48:51]
	v_mfma_f32_16x16x32_bf16 v[172:175], v[176:179], v[8:11], v[0:3]
	s_setprio 0
	s_waitcnt lgkmcnt(0)
	s_barrier
; DI void store4(u16* dst, f32x4 v) { uint2 w; w.x = cvtpk(v[0], v[1]); w.y = cvtpk(v[2], v[3]); *(uint2*)dst = w; }
; DI f32x4 mfma16(bf16x8 a, bf16x8 b, f32x4 c) { return __builtin_amdgcn_mfma_f32_16x16x32_bf16(a, b, c, 0, 0, 0); }
; template <int NI, class XL, class EP>
; DI void gemm_tile(const u16* __restrict__ W, int ldw, int f0, int t0, int K, XL xl, EP ep, unsigned char* smem) {
;     ...
;   for (int it = 0; it < nk; ++it) {
;     const u16* Ws = S0 + (it & 1) * BUF; const u16* Xs = Ws + 128 * LST;
;     __builtin_amdgcn_s_setprio(1);
;     bf16x8 a[4];
; #pragma unroll
;     for (int mi = 0; mi < 4; ++mi) a[mi] = *(const bf16x8*)(Ws + (wf * 64 + mi * 16 + lr) * LST + lq * 8);
; #pragma unroll
;     for (int ni = 0; ni < NI; ++ni) {
;       const bf16x8 b = *(const bf16x8*)(Xs + (wt * (NI * 16) + ni * 16 + lr) * LST + lq * 8);
; #pragma unroll
;       for (int mi = 0; mi < 4; ++mi) acc[mi][ni] = mfma16(a[mi], b, acc[mi][ni]);
;     }
;     __builtin_amdgcn_sched_group_barrier(0x100, 6, 0);
; #pragma unroll
;     for (int ni = 0; ni < NI; ++ni) { __builtin_amdgcn_sched_group_barrier(0x008, 4, 0); if (ni + 2 < NI) __builtin_amdgcn_sched_group_barrier(0x100, 1, 0); }
;     __builtin_amdgcn_s_setprio(0);
;     if (it + 1 < nk) lstore((it + 1) & 1);
;     if (it + 2 < nk) gload(it + 2);
;     __syncthreads();
;   }
;   ep(acc, f0 + wf * 64, t0 + wt * (NI * 16), lr, lq, wf, wt);
; DI void phase6(const Params& p, const Sched& sched, unsigned char* smem) {
;     ...
;     gemm_tile<8>((const u16*)(p.ws + OFF_WO), 1024, tn * 128, tm * 256, 1024, xl, [&](f32x4 (&acc)[4][8], int fb, int tb, int lr, int lq, int wf, int wt) {
;       constexpr int EST = 136;
;       u16* Ls = (u16*)smem;
;       const int b = tb >> 11;
;       __syncthreads();
; #pragma unroll
;       for (int mi = 0; mi < 4; ++mi) {
;         const int f = fb + mi * 16 + lq * 4; const float4 gm = *(const float4*)(mod + (size_t)b * 6144 + 2048 + f);
; #pragma unroll
;         for (int ni = 0; ni < 8; ++ni) {
;           const f32x4 o = {gm.x * acc[mi][ni][0], gm.y * acc[mi][ni][1], gm.z * acc[mi][ni][2], gm.w * acc[mi][ni][3]};
;           store4(Ls + (wt * 128 + ni * 16 + lr) * EST + wf * 64 + mi * 16 + lq * 4, o);
;         }
;       }
	s_lshl_b32 s34, s34, 7
	s_setprio 1
	ds_read_b128 v[28:31], v152 offset:36864
	ds_read_b128 v[176:179], v152 offset:38400
	ds_read_b128 v[228:231], v152 offset:39936
	ds_read_b128 v[232:235], v152 offset:41472
	ds_read_b128 v[0:3], v161 offset:49152
	ds_read_b128 v[4:7], v161 offset:50688
	s_waitcnt lgkmcnt(1)
	v_mfma_f32_16x16x32_bf16 v[88:91], v[28:31], v[0:3], v[148:151]
	v_mfma_f32_16x16x32_bf16 v[64:67], v[176:179], v[0:3], v[136:139]
	v_mfma_f32_16x16x32_bf16 v[32:35], v[228:231], v[0:3], v[112:115]
	v_mfma_f32_16x16x32_bf16 v[0:3], v[232:235], v[0:3], v[80:83]
	ds_read_b128 v[8:11], v161 offset:52224
	s_waitcnt lgkmcnt(1)
	v_mfma_f32_16x16x32_bf16 v[96:99], v[28:31], v[4:7], v[144:147]
	v_mfma_f32_16x16x32_bf16 v[76:79], v[176:179], v[4:7], v[128:131]
	v_mfma_f32_16x16x32_bf16 v[36:39], v[228:231], v[4:7], v[100:103]
	v_mfma_f32_16x16x32_bf16 v[4:7], v[232:235], v[4:7], v[68:71]
	ds_read_b128 v[12:15], v161 offset:53760
	s_waitcnt lgkmcnt(1)
	v_mfma_f32_16x16x32_bf16 v[104:107], v[28:31], v[8:11], v[140:143]
	v_mfma_f32_16x16x32_bf16 v[84:87], v[176:179], v[8:11], v[120:123]
	v_mfma_f32_16x16x32_bf16 v[40:43], v[228:231], v[8:11], v[184:187]
	v_mfma_f32_16x16x32_bf16 v[8:11], v[232:235], v[8:11], v[44:47]
	ds_read_b128 v[16:19], v161 offset:55296
	s_waitcnt lgkmcnt(1)
	v_mfma_f32_16x16x32_bf16 v[108:111], v[28:31], v[12:15], v[132:135]
	v_mfma_f32_16x16x32_bf16 v[92:95], v[176:179], v[12:15], v[168:171]
	v_mfma_f32_16x16x32_bf16 v[44:47], v[228:231], v[12:15], v[188:191]
	v_mfma_f32_16x16x32_bf16 v[12:15], v[232:235], v[12:15], v[180:183]
	ds_read_b128 v[20:23], v161 offset:56832
	s_waitcnt lgkmcnt(1)
	v_mfma_f32_16x16x32_bf16 v[112:115], v[28:31], v[16:19], v[124:127]
	v_mfma_f32_16x16x32_bf16 v[100:103], v[176:179], v[16:19], v[192:195]
	v_mfma_f32_16x16x32_bf16 v[48:51], v[228:231], v[16:19], v[196:199]
	v_mfma_f32_16x16x32_bf16 v[16:19], v[232:235], v[16:19], v[200:203]
	ds_read_b128 v[24:27], v161 offset:58368
	s_waitcnt lgkmcnt(1)
	v_mfma_f32_16x16x32_bf16 v[116:119], v[28:31], v[20:23], v[116:119]
	v_mfma_f32_16x16x32_bf16 v[68:71], v[176:179], v[20:23], v[204:207]
	v_mfma_f32_16x16x32_bf16 v[52:55], v[228:231], v[20:23], v[56:59]
	v_mfma_f32_16x16x32_bf16 v[20:23], v[232:235], v[20:23], v[208:211]
	ds_read_b128 v[128:131], v161 offset:59904
	s_waitcnt lgkmcnt(1)
	v_mfma_f32_16x16x32_bf16 v[120:123], v[28:31], v[24:27], v[212:215]
	v_mfma_f32_16x16x32_bf16 v[80:83], v[176:179], v[24:27], v[72:75]
	v_mfma_f32_16x16x32_bf16 v[56:59], v[228:231], v[24:27], v[220:223]
	v_mfma_f32_16x16x32_bf16 v[24:27], v[232:235], v[24:27], v[224:227]
	s_waitcnt lgkmcnt(0)
	v_mfma_f32_16x16x32_bf16 v[124:127], v[28:31], v[128:131], v[154:157]
	v_mfma_f32_16x16x32_bf16 v[72:75], v[176:179], v[128:131], v[60:63]
	v_mfma_f32_16x16x32_bf16 v[60:63], v[228:231], v[128:131], v[164:167]
	v_mfma_f32_16x16x32_bf16 v[28:31], v[232:235], v[128:131], v[172:175]
	s_setprio 0
	s_ashr_i32 s35, s35, 3
	v_add_u32_e32 v128, s34, v160
	s_mul_hi_i32 s37, s35, 0x6000
	s_mulk_i32 s35, 0x6000
	v_lshl_or_b32 v128, v158, 2, v128
	s_add_u32 s36, s72, s35
	s_addc_u32 s37, s73, s37
	v_ashrrev_i32_e32 v129, 31, v128
	v_lshl_add_u64 v[128:129], v[128:129], 2, s[36:37]
	v_add_co_u32_e32 v140, vcc, s26, v128
	v_mul_u32_u24_e32 v138, 0x88, v159
	s_nop 0
	v_addc_co_u32_e32 v141, vcc, 0, v129, vcc
	v_lshlrev_b32_e32 v136, 1, v160
	v_lshlrev_b32_e32 v137, 3, v158
	v_lshlrev_b32_e32 v138, 1, v138
	s_barrier
	global_load_dwordx4 v[128:131], v[140:141], off
	global_load_dwordx4 v[132:135], v[140:141], off offset:64
	v_add3_u32 v144, v136, v137, v138
	global_load_dwordx4 v[136:139], v[140:141], off offset:128
	v_add_u32_e32 v145, 0x1000, v144
	global_load_dwordx4 v[140:143], v[140:141], off offset:192
	v_add_u32_e32 v146, 0x2000, v144
	v_add_u32_e32 v147, 0x3000, v144
	v_add_u32_e32 v148, 0x4000, v144
	s_waitcnt vmcnt(3)
	v_pk_mul_f32 v[88:89], v[88:89], v[128:129]
	v_pk_mul_f32 v[90:91], v[90:91], v[130:131]
	v_pk_mul_f32 v[96:97], v[96:97], v[128:129]
	s_waitcnt vmcnt(1)
	v_pk_mul_f32 v[32:33], v[32:33], v[136:137]
	v_pk_mul_f32 v[34:35], v[34:35], v[138:139]
	s_waitcnt vmcnt(0)
	v_pk_mul_f32 v[0:1], v[0:1], v[140:141]
	v_pk_mul_f32 v[2:3], v[2:3], v[142:143]
	v_cvt_pk_bf16_f32 v32, v32, v33
	v_cvt_pk_bf16_f32 v33, v34, v35
	v_cvt_pk_bf16_f32 v0, v0, v1
	v_cvt_pk_bf16_f32 v1, v2, v3
	v_pk_mul_f32 v[34:35], v[36:37], v[136:137]
	v_pk_mul_f32 v[36:37], v[38:39], v[138:139]
	ds_write2_b64 v144, v[32:33], v[0:1] offset0:8 offset1:12
	v_pk_mul_f32 v[0:1], v[4:5], v[140:141]
	v_pk_mul_f32 v[2:3], v[6:7], v[142:143]
	v_cvt_pk_bf16_f32 v34, v34, v35
	v_cvt_pk_bf16_f32 v35, v36, v37
	v_cvt_pk_bf16_f32 v0, v0, v1
	v_cvt_pk_bf16_f32 v1, v2, v3
	v_pk_mul_f32 v[36:37], v[40:41], v[136:137]
	v_pk_mul_f32 v[38:39], v[42:43], v[138:139]
	ds_write2_b64 v145, v[34:35], v[0:1] offset0:40 offset1:44
	v_pk_mul_f32 v[0:1], v[8:9], v[140:141]
	v_pk_mul_f32 v[2:3], v[10:11], v[142:143]
	v_cvt_pk_bf16_f32 v36, v36, v37
	v_cvt_pk_bf16_f32 v37, v38, v39
	v_cvt_pk_bf16_f32 v0, v0, v1
	v_cvt_pk_bf16_f32 v1, v2, v3
	v_pk_mul_f32 v[38:39], v[44:45], v[136:137]
	v_pk_mul_f32 v[40:41], v[46:47], v[138:139]
	ds_write2_b64 v146, v[36:37], v[0:1] offset0:72 offset1:76
	v_pk_mul_f32 v[0:1], v[12:13], v[140:141]
	v_pk_mul_f32 v[2:3], v[14:15], v[142:143]
	v_cvt_pk_bf16_f32 v38, v38, v39
	v_cvt_pk_bf16_f32 v39, v40, v41
	v_cvt_pk_bf16_f32 v0, v0, v1
	v_cvt_pk_bf16_f32 v1, v2, v3
	v_pk_mul_f32 v[98:99], v[98:99], v[130:131]
	v_pk_mul_f32 v[64:65], v[64:65], v[132:133]
	v_pk_mul_f32 v[66:67], v[66:67], v[134:135]
	v_pk_mul_f32 v[76:77], v[76:77], v[132:133]
	v_pk_mul_f32 v[78:79], v[78:79], v[134:135]
; DI void store4(u16* dst, f32x4 v) { uint2 w; w.x = cvtpk(v[0], v[1]); w.y = cvtpk(v[2], v[3]); *(uint2*)dst = w; }
; DI void phase6(const Params& p, const Sched& sched, unsigned char* smem) {
;     ...
; #pragma unroll
;       for (int mi = 0; mi < 4; ++mi) {
;         const int f = fb + mi * 16 + lq * 4; const float4 gm = *(const float4*)(mod + (size_t)b * 6144 + 2048 + f);
; #pragma unroll
;         for (int ni = 0; ni < 8; ++ni) {
;           const f32x4 o = {gm.x * acc[mi][ni][0], gm.y * acc[mi][ni][1], gm.z * acc[mi][ni][2], gm.w * acc[mi][ni][3]};
;           store4(Ls + (wt * 128 + ni * 16 + lr) * EST + wf * 64 + mi * 16 + lq * 4, o);
;         }
;       }
;       __syncthreads();
	v_pk_mul_f32 v[40:41], v[48:49], v[136:137]
	v_pk_mul_f32 v[42:43], v[50:51], v[138:139]
	ds_write2_b64 v147, v[38:39], v[0:1] offset0:104 offset1:108
	v_pk_mul_f32 v[0:1], v[16:17], v[140:141]
	v_pk_mul_f32 v[2:3], v[18:19], v[142:143]
	v_cvt_pk_bf16_f32 v88, v88, v89
	v_cvt_pk_bf16_f32 v89, v90, v91
	v_cvt_pk_bf16_f32 v90, v96, v97
	v_cvt_pk_bf16_f32 v91, v98, v99
	v_cvt_pk_bf16_f32 v64, v64, v65
	v_cvt_pk_bf16_f32 v65, v66, v67
	v_cvt_pk_bf16_f32 v66, v76, v77
	v_cvt_pk_bf16_f32 v67, v78, v79
	v_cvt_pk_bf16_f32 v40, v40, v41
	v_cvt_pk_bf16_f32 v41, v42, v43
	v_cvt_pk_bf16_f32 v0, v0, v1
	v_cvt_pk_bf16_f32 v1, v2, v3
	v_pk_mul_f32 v[106:107], v[106:107], v[130:131]
	v_pk_mul_f32 v[116:117], v[116:117], v[128:129]
	v_pk_mul_f32 v[118:119], v[118:119], v[130:131]
	ds_write2_b64 v144, v[88:89], v[64:65] offset1:4
	ds_write2_b64 v145, v[90:91], v[66:67] offset0:32 offset1:36
	v_pk_mul_f32 v[64:65], v[68:69], v[132:133]
	v_pk_mul_f32 v[66:67], v[70:71], v[134:135]
	v_pk_mul_f32 v[42:43], v[52:53], v[136:137]
	v_pk_mul_f32 v[44:45], v[54:55], v[138:139]
	ds_write2_b64 v148, v[40:41], v[0:1] offset0:136 offset1:140
	v_pk_mul_f32 v[0:1], v[20:21], v[140:141]
	v_pk_mul_f32 v[2:3], v[22:23], v[142:143]
	v_cvt_pk_bf16_f32 v97, v106, v107
	v_cvt_pk_bf16_f32 v106, v116, v117
	v_cvt_pk_bf16_f32 v107, v118, v119
	v_cvt_pk_bf16_f32 v64, v64, v65
	v_cvt_pk_bf16_f32 v65, v66, v67
	v_add_u32_e32 v68, 0x5000, v144
	v_cvt_pk_bf16_f32 v42, v42, v43
	v_cvt_pk_bf16_f32 v43, v44, v45
	v_cvt_pk_bf16_f32 v0, v0, v1
	v_cvt_pk_bf16_f32 v1, v2, v3
	v_pk_mul_f32 v[108:109], v[108:109], v[128:129]
	v_pk_mul_f32 v[120:121], v[120:121], v[128:129]
	v_pk_mul_f32 v[122:123], v[122:123], v[130:131]
	ds_write2_b64 v68, v[106:107], v[64:65] offset0:160 offset1:164
	v_pk_mul_f32 v[64:65], v[80:81], v[132:133]
	v_pk_mul_f32 v[66:67], v[82:83], v[134:135]
	v_pk_mul_f32 v[44:45], v[56:57], v[136:137]
	v_pk_mul_f32 v[46:47], v[58:59], v[138:139]
	ds_write2_b64 v68, v[42:43], v[0:1] offset0:168 offset1:172
	v_pk_mul_f32 v[0:1], v[24:25], v[140:141]
	v_pk_mul_f32 v[2:3], v[26:27], v[142:143]
	v_cvt_pk_bf16_f32 v98, v108, v109
	v_cvt_pk_bf16_f32 v108, v120, v121
	v_cvt_pk_bf16_f32 v109, v122, v123
	v_cvt_pk_bf16_f32 v64, v64, v65
	v_cvt_pk_bf16_f32 v65, v66, v67
	v_add_u32_e32 v69, 0x6000, v144
	v_cvt_pk_bf16_f32 v44, v44, v45
	v_cvt_pk_bf16_f32 v45, v46, v47
	v_cvt_pk_bf16_f32 v0, v0, v1
	v_cvt_pk_bf16_f32 v1, v2, v3
	v_pk_mul_f32 v[104:105], v[104:105], v[128:129]
	v_pk_mul_f32 v[110:111], v[110:111], v[130:131]
	v_pk_mul_f32 v[112:113], v[112:113], v[128:129]
	v_pk_mul_f32 v[114:115], v[114:115], v[130:131]
	v_pk_mul_f32 v[124:125], v[124:125], v[128:129]
	v_pk_mul_f32 v[126:127], v[126:127], v[130:131]
	v_pk_mul_f32 v[84:85], v[84:85], v[132:133]
	v_pk_mul_f32 v[86:87], v[86:87], v[134:135]
	v_pk_mul_f32 v[92:93], v[92:93], v[132:133]
	v_pk_mul_f32 v[94:95], v[94:95], v[134:135]
	v_pk_mul_f32 v[100:101], v[100:101], v[132:133]
	v_pk_mul_f32 v[102:103], v[102:103], v[134:135]
	ds_write2_b64 v69, v[108:109], v[64:65] offset0:192 offset1:196
	v_pk_mul_f32 v[64:65], v[72:73], v[132:133]
	v_pk_mul_f32 v[66:67], v[74:75], v[134:135]
	v_pk_mul_f32 v[46:47], v[60:61], v[136:137]
	v_pk_mul_f32 v[48:49], v[62:63], v[138:139]
	ds_write2_b64 v69, v[44:45], v[0:1] offset0:200 offset1:204
	v_pk_mul_f32 v[0:1], v[28:29], v[140:141]
	v_pk_mul_f32 v[2:3], v[30:31], v[142:143]
	v_cvt_pk_bf16_f32 v96, v104, v105
	v_cvt_pk_bf16_f32 v99, v110, v111
	v_cvt_pk_bf16_f32 v104, v112, v113
	v_cvt_pk_bf16_f32 v105, v114, v115
	v_cvt_pk_bf16_f32 v110, v124, v125
	v_cvt_pk_bf16_f32 v111, v126, v127
	v_cvt_pk_bf16_f32 v76, v84, v85
	v_cvt_pk_bf16_f32 v77, v86, v87
	v_cvt_pk_bf16_f32 v78, v92, v93
	v_cvt_pk_bf16_f32 v79, v94, v95
	v_cvt_pk_bf16_f32 v84, v100, v101
	v_cvt_pk_bf16_f32 v85, v102, v103
	v_cvt_pk_bf16_f32 v64, v64, v65
	v_cvt_pk_bf16_f32 v65, v66, v67
	v_add_u32_e32 v66, 0x7000, v144
	v_cvt_pk_bf16_f32 v46, v46, v47
	v_cvt_pk_bf16_f32 v47, v48, v49
	v_cvt_pk_bf16_f32 v0, v0, v1
	v_cvt_pk_bf16_f32 v1, v2, v3
	v_mov_b32_e32 v2, v218
	ds_write2_b64 v146, v[96:97], v[76:77] offset0:64 offset1:68
	ds_write2_b64 v147, v[98:99], v[78:79] offset0:96 offset1:100
	ds_write2_b64 v148, v[104:105], v[84:85] offset0:128 offset1:132
	ds_write2_b64 v66, v[110:111], v[64:65] offset0:224 offset1:228
	ds_write2_b64 v66, v[46:47], v[0:1] offset0:232 offset1:236
	s_waitcnt lgkmcnt(0)
	s_barrier
; DI int tidx() { int t = __builtin_amdgcn_workitem_id_x(); asm volatile("" : "+v"(t)); return t; }
; DI unsigned cvtpk(float lo, float hi) { const f32x2_ v = {lo, hi}; return __builtin_bit_cast(unsigned, __builtin_convertvector(v, bf16x2_)); }
; DI float bflo(unsigned w) { return __uint_as_float(w << 16); }
; DI float bfhi(unsigned w) { return __uint_as_float(w & 0xffff0000u); }
; DI void phase6(const Params& p, const Sched& sched, unsigned char* smem) {
;     ...
;       const int tid = tidx();
; #pragma unroll
;       for (int i = 0; i < 16; ++i) {
;         const int c = tid + 256 * i, row = c >> 4, ch = (c & 15) * 8;
;         const size_t gi = (size_t)(tm * 256 + row) * 1024 + tn * 128 + ch;
;         const u32x4 sv = *(const u32x4*)(Ls + row * EST + ch);
;         const f32x4 x0 = *(const f32x4*)(p.x + gi), x1 = *(const f32x4*)(p.x + gi + 4);
;         u32x4 w;
;         w.x = cvtpk(x0[0] + bflo(sv.x), x0[1] + bfhi(sv.x)); w.y = cvtpk(x0[2] + bflo(sv.y), x0[3] + bfhi(sv.y));
;         w.z = cvtpk(x1[0] + bflo(sv.z), x1[1] + bfhi(sv.z)); w.w = cvtpk(x1[2] + bflo(sv.w), x1[3] + bfhi(sv.w));
;         *(u32x4*)(x1b + gi) = w;
;       }
	s_nop 0
	v_ashrrev_i32_e32 v3, 4, v2
	v_add_u32_e32 v4, s33, v3
	v_lshlrev_b32_e32 v0, 3, v2
	v_ashrrev_i32_e32 v5, 31, v4
	v_and_b32_e32 v1, 0x78, v0
	v_lshlrev_b64 v[16:17], 10, v[4:5]
	v_or3_b32 v16, v16, s34, v1
	v_lshl_add_u64 v[8:9], v[16:17], 2, s[76:77]
	global_load_dwordx4 v[4:7], v[8:9], off
	v_lshlrev_b32_e32 v0, 1, v1
	global_load_dwordx4 v[8:11], v[8:9], off offset:16
	v_mad_u64_u32 v[12:13], s[36:37], v3, s27, v[0:1]
	ds_read_b128 v[12:15], v12
	v_add_u32_e32 v3, 0x100, v2
	v_ashrrev_i32_e32 v3, 4, v3
	s_waitcnt lgkmcnt(0)
	v_lshlrev_b32_e32 v18, 16, v12
	v_and_b32_e32 v19, 0xffff0000, v12
	v_lshlrev_b32_e32 v12, 16, v13
	v_and_b32_e32 v13, 0xffff0000, v13
	s_waitcnt vmcnt(1)
	v_pk_add_f32 v[4:5], v[4:5], v[18:19]
	v_pk_add_f32 v[6:7], v[6:7], v[12:13]
	v_cvt_pk_bf16_f32 v4, v4, v5
	v_cvt_pk_bf16_f32 v5, v6, v7
	v_lshlrev_b32_e32 v6, 16, v14
	v_and_b32_e32 v7, 0xffff0000, v14
	s_waitcnt vmcnt(0)
	v_pk_add_f32 v[6:7], v[8:9], v[6:7]
	v_lshlrev_b32_e32 v8, 16, v15
	v_and_b32_e32 v9, 0xffff0000, v15
	v_pk_add_f32 v[8:9], v[10:11], v[8:9]
	v_cvt_pk_bf16_f32 v6, v6, v7
	v_cvt_pk_bf16_f32 v7, v8, v9
	v_lshl_add_u64 v[8:9], v[16:17], 1, s[12:13]
	global_store_dwordx4 v[8:9], v[4:7], off
	v_add_u32_e32 v12, 0x200, v2
	v_ashrrev_i32_e32 v26, 4, v12
	v_add_u32_e32 v4, s33, v3
	v_ashrrev_i32_e32 v5, 31, v4
	v_lshlrev_b64 v[16:17], 10, v[4:5]
	v_or3_b32 v16, v16, s34, v1
	v_lshl_add_u64 v[8:9], v[16:17], 2, s[76:77]
	global_load_dwordx4 v[4:7], v[8:9], off
	v_mad_u64_u32 v[12:13], s[36:37], v3, s27, v[0:1]
	global_load_dwordx4 v[8:11], v[8:9], off offset:16
	ds_read_b128 v[12:15], v12
	v_add_u32_e32 v18, s33, v26
	v_ashrrev_i32_e32 v19, 31, v18
	v_lshlrev_b64 v[18:19], 10, v[18:19]
	v_or3_b32 v18, v18, s34, v1
	s_waitcnt lgkmcnt(0)
	v_lshlrev_b32_e32 v22, 16, v12
	v_and_b32_e32 v23, 0xffff0000, v12
	v_lshlrev_b32_e32 v12, 16, v13
	v_and_b32_e32 v13, 0xffff0000, v13
	v_lshlrev_b32_e32 v24, 16, v14
	v_and_b32_e32 v25, 0xffff0000, v14
	v_lshlrev_b32_e32 v14, 16, v15
	v_and_b32_e32 v15, 0xffff0000, v15
	v_lshl_add_u64 v[16:17], v[16:17], 1, s[12:13]
	v_lshl_add_u64 v[20:21], v[18:19], 2, s[76:77]
	v_add_u32_e32 v3, 0x300, v2
	v_ashrrev_i32_e32 v3, 4, v3
	v_lshl_add_u64 v[18:19], v[18:19], 1, s[12:13]
	s_waitcnt vmcnt(1)
	v_pk_add_f32 v[4:5], v[4:5], v[22:23]
	v_pk_add_f32 v[6:7], v[6:7], v[12:13]
	v_cvt_pk_bf16_f32 v4, v4, v5
	s_waitcnt vmcnt(0)
	v_pk_add_f32 v[8:9], v[8:9], v[24:25]
	v_pk_add_f32 v[10:11], v[10:11], v[14:15]
	v_cvt_pk_bf16_f32 v5, v6, v7
	v_cvt_pk_bf16_f32 v6, v8, v9
	v_cvt_pk_bf16_f32 v7, v10, v11
	global_store_dwordx4 v[16:17], v[4:7], off
	global_load_dwordx4 v[4:7], v[20:21], off
	v_mad_u64_u32 v[12:13], s[36:37], v26, s27, v[0:1]
	global_load_dwordx4 v[8:11], v[20:21], off offset:16
	ds_read_b128 v[12:15], v12
	v_add_u32_e32 v16, s33, v3
	v_ashrrev_i32_e32 v17, 31, v16
	v_lshlrev_b64 v[16:17], 10, v[16:17]
	v_or3_b32 v16, v16, s34, v1
	s_waitcnt lgkmcnt(0)
	v_lshlrev_b32_e32 v22, 16, v12
	v_and_b32_e32 v23, 0xffff0000, v12
	v_lshlrev_b32_e32 v12, 16, v13
	v_and_b32_e32 v13, 0xffff0000, v13
	v_lshlrev_b32_e32 v24, 16, v14
	v_and_b32_e32 v25, 0xffff0000, v14
	v_lshlrev_b32_e32 v14, 16, v15
	v_and_b32_e32 v15, 0xffff0000, v15
	v_lshl_add_u64 v[20:21], v[16:17], 2, s[76:77]
	v_lshl_add_u64 v[16:17], v[16:17], 1, s[12:13]
	s_waitcnt vmcnt(1)
	v_pk_add_f32 v[4:5], v[4:5], v[22:23]
	v_pk_add_f32 v[6:7], v[6:7], v[12:13]
	v_cvt_pk_bf16_f32 v4, v4, v5
	s_waitcnt vmcnt(0)
	v_pk_add_f32 v[8:9], v[8:9], v[24:25]
	v_pk_add_f32 v[10:11], v[10:11], v[14:15]
	v_cvt_pk_bf16_f32 v5, v6, v7
	v_cvt_pk_bf16_f32 v6, v8, v9
	v_cvt_pk_bf16_f32 v7, v10, v11
	global_store_dwordx4 v[18:19], v[4:7], off
	global_load_dwordx4 v[4:7], v[20:21], off
	v_add_u32_e32 v12, 0x400, v2
	global_load_dwordx4 v[8:11], v[20:21], off offset:16
	v_ashrrev_i32_e32 v26, 4, v12
	v_mad_u64_u32 v[12:13], s[36:37], v3, s27, v[0:1]
	ds_read_b128 v[12:15], v12
	v_add_u32_e32 v18, s33, v26
	v_ashrrev_i32_e32 v19, 31, v18
	v_lshlrev_b64 v[18:19], 10, v[18:19]
	v_or3_b32 v18, v18, s34, v1
	s_waitcnt lgkmcnt(0)
	v_lshlrev_b32_e32 v22, 16, v12
	v_and_b32_e32 v23, 0xffff0000, v12
	v_lshlrev_b32_e32 v12, 16, v13
	v_and_b32_e32 v13, 0xffff0000, v13
	v_lshlrev_b32_e32 v24, 16, v14
	v_and_b32_e32 v25, 0xffff0000, v14
	v_lshlrev_b32_e32 v14, 16, v15
	v_and_b32_e32 v15, 0xffff0000, v15
	v_lshl_add_u64 v[20:21], v[18:19], 2, s[76:77]
	v_add_u32_e32 v3, 0x500, v2
	v_ashrrev_i32_e32 v3, 4, v3
	v_lshl_add_u64 v[18:19], v[18:19], 1, s[12:13]
	s_waitcnt vmcnt(1)
	v_pk_add_f32 v[4:5], v[4:5], v[22:23]
	v_pk_add_f32 v[6:7], v[6:7], v[12:13]
	s_waitcnt vmcnt(0)
	v_pk_add_f32 v[8:9], v[8:9], v[24:25]
	v_pk_add_f32 v[10:11], v[10:11], v[14:15]
	v_cvt_pk_bf16_f32 v4, v4, v5
	v_cvt_pk_bf16_f32 v5, v6, v7
	v_cvt_pk_bf16_f32 v6, v8, v9
	v_cvt_pk_bf16_f32 v7, v10, v11
	global_store_dwordx4 v[16:17], v[4:7], off
	global_load_dwordx4 v[4:7], v[20:21], off
	v_mad_u64_u32 v[12:13], s[36:37], v26, s27, v[0:1]
	global_load_dwordx4 v[8:11], v[20:21], off offset:16
	ds_read_b128 v[12:15], v12
	v_add_u32_e32 v16, s33, v3
	v_ashrrev_i32_e32 v17, 31, v16
	v_lshlrev_b64 v[16:17], 10, v[16:17]
	v_or3_b32 v16, v16, s34, v1
	s_waitcnt lgkmcnt(0)
	v_lshlrev_b32_e32 v22, 16, v12
	v_and_b32_e32 v23, 0xffff0000, v12
	v_lshlrev_b32_e32 v12, 16, v13
	v_and_b32_e32 v13, 0xffff0000, v13
	v_lshlrev_b32_e32 v24, 16, v14
	v_and_b32_e32 v25, 0xffff0000, v14
	v_lshlrev_b32_e32 v14, 16, v15
	v_and_b32_e32 v15, 0xffff0000, v15
	v_lshl_add_u64 v[20:21], v[16:17], 2, s[76:77]
	v_lshl_add_u64 v[16:17], v[16:17], 1, s[12:13]
	s_waitcnt vmcnt(1)
	v_pk_add_f32 v[4:5], v[4:5], v[22:23]
	v_pk_add_f32 v[6:7], v[6:7], v[12:13]
	v_cvt_pk_bf16_f32 v4, v4, v5
	s_waitcnt vmcnt(0)
; DI unsigned cvtpk(float lo, float hi) { const f32x2_ v = {lo, hi}; return __builtin_bit_cast(unsigned, __builtin_convertvector(v, bf16x2_)); }
; DI float bflo(unsigned w) { return __uint_as_float(w << 16); }
; DI float bfhi(unsigned w) { return __uint_as_float(w & 0xffff0000u); }
; DI void phase6(const Params& p, const Sched& sched, unsigned char* smem) {
;     ...
; #pragma unroll
;       for (int i = 0; i < 16; ++i) {
;         const int c = tid + 256 * i, row = c >> 4, ch = (c & 15) * 8;
;         const size_t gi = (size_t)(tm * 256 + row) * 1024 + tn * 128 + ch;
;         const u32x4 sv = *(const u32x4*)(Ls + row * EST + ch);
;         const f32x4 x0 = *(const f32x4*)(p.x + gi), x1 = *(const f32x4*)(p.x + gi + 4);
;         u32x4 w;
;         w.x = cvtpk(x0[0] + bflo(sv.x), x0[1] + bfhi(sv.x)); w.y = cvtpk(x0[2] + bflo(sv.y), x0[3] + bfhi(sv.y));
;         w.z = cvtpk(x1[0] + bflo(sv.z), x1[1] + bfhi(sv.z)); w.w = cvtpk(x1[2] + bflo(sv.w), x1[3] + bfhi(sv.w));
;         *(u32x4*)(x1b + gi) = w;
;       }
	v_pk_add_f32 v[8:9], v[8:9], v[24:25]
	v_pk_add_f32 v[10:11], v[10:11], v[14:15]
	v_cvt_pk_bf16_f32 v5, v6, v7
	v_cvt_pk_bf16_f32 v6, v8, v9
	v_cvt_pk_bf16_f32 v7, v10, v11
	global_store_dwordx4 v[18:19], v[4:7], off
	global_load_dwordx4 v[4:7], v[20:21], off
	v_add_u32_e32 v12, 0x600, v2
	global_load_dwordx4 v[8:11], v[20:21], off offset:16
	v_ashrrev_i32_e32 v26, 4, v12
	v_mad_u64_u32 v[12:13], s[36:37], v3, s27, v[0:1]
	ds_read_b128 v[12:15], v12
	v_add_u32_e32 v18, s33, v26
	v_ashrrev_i32_e32 v19, 31, v18
	v_lshlrev_b64 v[18:19], 10, v[18:19]
	v_or3_b32 v18, v18, s34, v1
	s_waitcnt lgkmcnt(0)
	v_lshlrev_b32_e32 v22, 16, v12
	v_and_b32_e32 v23, 0xffff0000, v12
	v_lshlrev_b32_e32 v12, 16, v13
	v_and_b32_e32 v13, 0xffff0000, v13
	v_lshlrev_b32_e32 v24, 16, v14
	v_and_b32_e32 v25, 0xffff0000, v14
	v_lshlrev_b32_e32 v14, 16, v15
	v_and_b32_e32 v15, 0xffff0000, v15
	v_lshl_add_u64 v[20:21], v[18:19], 2, s[76:77]
	v_add_u32_e32 v3, 0x700, v2
	v_ashrrev_i32_e32 v3, 4, v3
	v_lshl_add_u64 v[18:19], v[18:19], 1, s[12:13]
	s_waitcnt vmcnt(1)
	v_pk_add_f32 v[4:5], v[4:5], v[22:23]
	v_pk_add_f32 v[6:7], v[6:7], v[12:13]
	s_waitcnt vmcnt(0)
	v_pk_add_f32 v[8:9], v[8:9], v[24:25]
	v_pk_add_f32 v[10:11], v[10:11], v[14:15]
	v_cvt_pk_bf16_f32 v4, v4, v5
	v_cvt_pk_bf16_f32 v5, v6, v7
	v_cvt_pk_bf16_f32 v6, v8, v9
	v_cvt_pk_bf16_f32 v7, v10, v11
	global_store_dwordx4 v[16:17], v[4:7], off
	global_load_dwordx4 v[4:7], v[20:21], off
	v_mad_u64_u32 v[12:13], s[36:37], v26, s27, v[0:1]
	global_load_dwordx4 v[8:11], v[20:21], off offset:16
	ds_read_b128 v[12:15], v12
	v_add_u32_e32 v16, s33, v3
	v_ashrrev_i32_e32 v17, 31, v16
	v_lshlrev_b64 v[16:17], 10, v[16:17]
	v_or3_b32 v16, v16, s34, v1
	s_waitcnt lgkmcnt(0)
	v_lshlrev_b32_e32 v22, 16, v12
	v_and_b32_e32 v23, 0xffff0000, v12
	v_lshlrev_b32_e32 v12, 16, v13
	v_and_b32_e32 v13, 0xffff0000, v13
	v_lshlrev_b32_e32 v24, 16, v14
	v_and_b32_e32 v25, 0xffff0000, v14
	v_lshlrev_b32_e32 v14, 16, v15
	v_and_b32_e32 v15, 0xffff0000, v15
	v_lshl_add_u64 v[20:21], v[16:17], 2, s[76:77]
	v_lshl_add_u64 v[16:17], v[16:17], 1, s[12:13]
	s_waitcnt vmcnt(1)
	v_pk_add_f32 v[4:5], v[4:5], v[22:23]
	v_pk_add_f32 v[6:7], v[6:7], v[12:13]
	v_cvt_pk_bf16_f32 v4, v4, v5
	s_waitcnt vmcnt(0)
	v_pk_add_f32 v[8:9], v[8:9], v[24:25]
	v_pk_add_f32 v[10:11], v[10:11], v[14:15]
	v_cvt_pk_bf16_f32 v5, v6, v7
	v_cvt_pk_bf16_f32 v6, v8, v9
	v_cvt_pk_bf16_f32 v7, v10, v11
	global_store_dwordx4 v[18:19], v[4:7], off
	global_load_dwordx4 v[4:7], v[20:21], off
	v_add_u32_e32 v12, 0x800, v2
	global_load_dwordx4 v[8:11], v[20:21], off offset:16
	v_ashrrev_i32_e32 v26, 4, v12
	v_mad_u64_u32 v[12:13], s[36:37], v3, s27, v[0:1]
	ds_read_b128 v[12:15], v12
	v_add_u32_e32 v18, s33, v26
	v_ashrrev_i32_e32 v19, 31, v18
	v_lshlrev_b64 v[18:19], 10, v[18:19]
	v_or3_b32 v18, v18, s34, v1
	s_waitcnt lgkmcnt(0)
	v_lshlrev_b32_e32 v22, 16, v12
	v_and_b32_e32 v23, 0xffff0000, v12
	v_lshlrev_b32_e32 v12, 16, v13
	v_and_b32_e32 v13, 0xffff0000, v13
	v_lshlrev_b32_e32 v24, 16, v14
	v_and_b32_e32 v25, 0xffff0000, v14
	v_lshlrev_b32_e32 v14, 16, v15
	v_and_b32_e32 v15, 0xffff0000, v15
	v_lshl_add_u64 v[20:21], v[18:19], 2, s[76:77]
	v_add_u32_e32 v3, 0x900, v2
	v_ashrrev_i32_e32 v3, 4, v3
	v_lshl_add_u64 v[18:19], v[18:19], 1, s[12:13]
	s_waitcnt vmcnt(1)
	v_pk_add_f32 v[4:5], v[4:5], v[22:23]
	v_pk_add_f32 v[6:7], v[6:7], v[12:13]
	s_waitcnt vmcnt(0)
	v_pk_add_f32 v[8:9], v[8:9], v[24:25]
	v_pk_add_f32 v[10:11], v[10:11], v[14:15]
	v_cvt_pk_bf16_f32 v4, v4, v5
	v_cvt_pk_bf16_f32 v5, v6, v7
	v_cvt_pk_bf16_f32 v6, v8, v9
	v_cvt_pk_bf16_f32 v7, v10, v11
	global_store_dwordx4 v[16:17], v[4:7], off
	global_load_dwordx4 v[4:7], v[20:21], off
	v_mad_u64_u32 v[12:13], s[36:37], v26, s27, v[0:1]
	global_load_dwordx4 v[8:11], v[20:21], off offset:16
	ds_read_b128 v[12:15], v12
	v_add_u32_e32 v16, s33, v3
	v_ashrrev_i32_e32 v17, 31, v16
	v_lshlrev_b64 v[16:17], 10, v[16:17]
	v_or3_b32 v16, v16, s34, v1
	s_waitcnt lgkmcnt(0)
	v_lshlrev_b32_e32 v22, 16, v12
	v_and_b32_e32 v23, 0xffff0000, v12
	v_lshlrev_b32_e32 v12, 16, v13
	v_and_b32_e32 v13, 0xffff0000, v13
	v_lshlrev_b32_e32 v24, 16, v14
	v_and_b32_e32 v25, 0xffff0000, v14
	v_lshlrev_b32_e32 v14, 16, v15
	v_and_b32_e32 v15, 0xffff0000, v15
	v_lshl_add_u64 v[20:21], v[16:17], 2, s[76:77]
	v_lshl_add_u64 v[16:17], v[16:17], 1, s[12:13]
	s_waitcnt vmcnt(1)
	v_pk_add_f32 v[4:5], v[4:5], v[22:23]
	v_pk_add_f32 v[6:7], v[6:7], v[12:13]
	v_cvt_pk_bf16_f32 v4, v4, v5
	s_waitcnt vmcnt(0)
	v_pk_add_f32 v[8:9], v[8:9], v[24:25]
	v_pk_add_f32 v[10:11], v[10:11], v[14:15]
	v_cvt_pk_bf16_f32 v5, v6, v7
	v_cvt_pk_bf16_f32 v6, v8, v9
	v_cvt_pk_bf16_f32 v7, v10, v11
	global_store_dwordx4 v[18:19], v[4:7], off
	global_load_dwordx4 v[4:7], v[20:21], off
	v_add_u32_e32 v12, 0xa00, v2
	global_load_dwordx4 v[8:11], v[20:21], off offset:16
	v_ashrrev_i32_e32 v26, 4, v12
	v_mad_u64_u32 v[12:13], s[36:37], v3, s27, v[0:1]
	ds_read_b128 v[12:15], v12
	v_add_u32_e32 v18, s33, v26
	v_ashrrev_i32_e32 v19, 31, v18
	v_lshlrev_b64 v[18:19], 10, v[18:19]
	v_or3_b32 v18, v18, s34, v1
	s_waitcnt lgkmcnt(0)
	v_lshlrev_b32_e32 v22, 16, v12
	v_and_b32_e32 v23, 0xffff0000, v12
	v_lshlrev_b32_e32 v12, 16, v13
	v_and_b32_e32 v13, 0xffff0000, v13
	v_lshlrev_b32_e32 v24, 16, v14
	v_and_b32_e32 v25, 0xffff0000, v14
	v_lshlrev_b32_e32 v14, 16, v15
	v_and_b32_e32 v15, 0xffff0000, v15
	v_lshl_add_u64 v[20:21], v[18:19], 2, s[76:77]
	v_add_u32_e32 v3, 0xb00, v2
	v_ashrrev_i32_e32 v3, 4, v3
	v_lshl_add_u64 v[18:19], v[18:19], 1, s[12:13]
	s_waitcnt vmcnt(1)
	v_pk_add_f32 v[4:5], v[4:5], v[22:23]
	v_pk_add_f32 v[6:7], v[6:7], v[12:13]
	s_waitcnt vmcnt(0)
; DI unsigned cvtpk(float lo, float hi) { const f32x2_ v = {lo, hi}; return __builtin_bit_cast(unsigned, __builtin_convertvector(v, bf16x2_)); }
; DI float bflo(unsigned w) { return __uint_as_float(w << 16); }
; DI float bfhi(unsigned w) { return __uint_as_float(w & 0xffff0000u); }
; DI void phase6(const Params& p, const Sched& sched, unsigned char* smem) {
;     ...
; #pragma unroll
;       for (int i = 0; i < 16; ++i) {
;         const int c = tid + 256 * i, row = c >> 4, ch = (c & 15) * 8;
;         const size_t gi = (size_t)(tm * 256 + row) * 1024 + tn * 128 + ch;
;         const u32x4 sv = *(const u32x4*)(Ls + row * EST + ch);
;         const f32x4 x0 = *(const f32x4*)(p.x + gi), x1 = *(const f32x4*)(p.x + gi + 4);
;         u32x4 w;
;         w.x = cvtpk(x0[0] + bflo(sv.x), x0[1] + bfhi(sv.x)); w.y = cvtpk(x0[2] + bflo(sv.y), x0[3] + bfhi(sv.y));
;         w.z = cvtpk(x1[0] + bflo(sv.z), x1[1] + bfhi(sv.z)); w.w = cvtpk(x1[2] + bflo(sv.w), x1[3] + bfhi(sv.w));
;         *(u32x4*)(x1b + gi) = w;
;       }
	v_pk_add_f32 v[8:9], v[8:9], v[24:25]
	v_pk_add_f32 v[10:11], v[10:11], v[14:15]
	v_cvt_pk_bf16_f32 v4, v4, v5
	v_cvt_pk_bf16_f32 v5, v6, v7
	v_cvt_pk_bf16_f32 v6, v8, v9
	v_cvt_pk_bf16_f32 v7, v10, v11
	global_store_dwordx4 v[16:17], v[4:7], off
	global_load_dwordx4 v[4:7], v[20:21], off
	v_mad_u64_u32 v[12:13], s[36:37], v26, s27, v[0:1]
	global_load_dwordx4 v[8:11], v[20:21], off offset:16
	ds_read_b128 v[12:15], v12
	v_add_u32_e32 v16, s33, v3
	v_ashrrev_i32_e32 v17, 31, v16
	v_lshlrev_b64 v[16:17], 10, v[16:17]
	v_or3_b32 v16, v16, s34, v1
	s_waitcnt lgkmcnt(0)
	v_lshlrev_b32_e32 v22, 16, v12
	v_and_b32_e32 v23, 0xffff0000, v12
	v_lshlrev_b32_e32 v12, 16, v13
	v_and_b32_e32 v13, 0xffff0000, v13
	v_lshlrev_b32_e32 v24, 16, v14
	v_and_b32_e32 v25, 0xffff0000, v14
	v_lshlrev_b32_e32 v14, 16, v15
	v_and_b32_e32 v15, 0xffff0000, v15
	v_lshl_add_u64 v[20:21], v[16:17], 2, s[76:77]
	v_lshl_add_u64 v[16:17], v[16:17], 1, s[12:13]
	s_waitcnt vmcnt(1)
	v_pk_add_f32 v[4:5], v[4:5], v[22:23]
	v_pk_add_f32 v[6:7], v[6:7], v[12:13]
	v_cvt_pk_bf16_f32 v4, v4, v5
	s_waitcnt vmcnt(0)
	v_pk_add_f32 v[8:9], v[8:9], v[24:25]
	v_pk_add_f32 v[10:11], v[10:11], v[14:15]
	v_cvt_pk_bf16_f32 v5, v6, v7
	v_cvt_pk_bf16_f32 v6, v8, v9
	v_cvt_pk_bf16_f32 v7, v10, v11
	global_store_dwordx4 v[18:19], v[4:7], off
	global_load_dwordx4 v[4:7], v[20:21], off
	v_add_u32_e32 v12, 0xc00, v2
	global_load_dwordx4 v[8:11], v[20:21], off offset:16
	v_ashrrev_i32_e32 v26, 4, v12
	v_mad_u64_u32 v[12:13], s[36:37], v3, s27, v[0:1]
	ds_read_b128 v[12:15], v12
	v_add_u32_e32 v18, s33, v26
	v_ashrrev_i32_e32 v19, 31, v18
	v_lshlrev_b64 v[18:19], 10, v[18:19]
	v_or3_b32 v18, v18, s34, v1
	s_waitcnt lgkmcnt(0)
	v_lshlrev_b32_e32 v22, 16, v12
	v_and_b32_e32 v23, 0xffff0000, v12
	v_lshlrev_b32_e32 v12, 16, v13
	v_and_b32_e32 v13, 0xffff0000, v13
	v_lshlrev_b32_e32 v24, 16, v14
	v_and_b32_e32 v25, 0xffff0000, v14
	v_lshlrev_b32_e32 v14, 16, v15
	v_and_b32_e32 v15, 0xffff0000, v15
	v_lshl_add_u64 v[20:21], v[18:19], 2, s[76:77]
	v_add_u32_e32 v3, 0xd00, v2
	v_ashrrev_i32_e32 v3, 4, v3
	v_lshl_add_u64 v[18:19], v[18:19], 1, s[12:13]
	s_waitcnt vmcnt(1)
	v_pk_add_f32 v[4:5], v[4:5], v[22:23]
	v_pk_add_f32 v[6:7], v[6:7], v[12:13]
	s_waitcnt vmcnt(0)
	v_pk_add_f32 v[8:9], v[8:9], v[24:25]
	v_pk_add_f32 v[10:11], v[10:11], v[14:15]
	v_cvt_pk_bf16_f32 v4, v4, v5
	v_cvt_pk_bf16_f32 v5, v6, v7
	v_cvt_pk_bf16_f32 v6, v8, v9
	v_cvt_pk_bf16_f32 v7, v10, v11
	global_store_dwordx4 v[16:17], v[4:7], off
	global_load_dwordx4 v[4:7], v[20:21], off
	v_mad_u64_u32 v[12:13], s[36:37], v26, s27, v[0:1]
	global_load_dwordx4 v[8:11], v[20:21], off offset:16
	ds_read_b128 v[12:15], v12
	v_add_u32_e32 v16, s33, v3
	v_ashrrev_i32_e32 v17, 31, v16
	v_lshlrev_b64 v[16:17], 10, v[16:17]
	v_or3_b32 v16, v16, s34, v1
	s_waitcnt lgkmcnt(0)
	v_lshlrev_b32_e32 v22, 16, v12
	v_and_b32_e32 v23, 0xffff0000, v12
	v_lshlrev_b32_e32 v12, 16, v13
	v_and_b32_e32 v13, 0xffff0000, v13
	v_lshlrev_b32_e32 v24, 16, v14
	v_and_b32_e32 v25, 0xffff0000, v14
	v_lshlrev_b32_e32 v14, 16, v15
	v_and_b32_e32 v15, 0xffff0000, v15
	v_lshl_add_u64 v[20:21], v[16:17], 2, s[76:77]
	v_lshl_add_u64 v[16:17], v[16:17], 1, s[12:13]
	s_waitcnt vmcnt(1)
	v_pk_add_f32 v[4:5], v[4:5], v[22:23]
	v_pk_add_f32 v[6:7], v[6:7], v[12:13]
	v_cvt_pk_bf16_f32 v4, v4, v5
	s_waitcnt vmcnt(0)
	v_pk_add_f32 v[8:9], v[8:9], v[24:25]
	v_pk_add_f32 v[10:11], v[10:11], v[14:15]
	v_cvt_pk_bf16_f32 v5, v6, v7
	v_cvt_pk_bf16_f32 v6, v8, v9
	v_cvt_pk_bf16_f32 v7, v10, v11
	global_store_dwordx4 v[18:19], v[4:7], off
	global_load_dwordx4 v[4:7], v[20:21], off
	v_add_u32_e32 v12, 0xe00, v2
	global_load_dwordx4 v[8:11], v[20:21], off offset:16
	v_ashrrev_i32_e32 v26, 4, v12
	v_mad_u64_u32 v[12:13], s[36:37], v3, s27, v[0:1]
	ds_read_b128 v[12:15], v12
	v_add_u32_e32 v18, s33, v26
	v_ashrrev_i32_e32 v19, 31, v18
	v_lshlrev_b64 v[18:19], 10, v[18:19]
	v_or3_b32 v18, v18, s34, v1
	s_waitcnt lgkmcnt(0)
	v_lshlrev_b32_e32 v22, 16, v12
	v_and_b32_e32 v23, 0xffff0000, v12
	v_lshlrev_b32_e32 v12, 16, v13
	v_and_b32_e32 v13, 0xffff0000, v13
	v_lshlrev_b32_e32 v24, 16, v14
	v_and_b32_e32 v25, 0xffff0000, v14
	v_lshlrev_b32_e32 v14, 16, v15
	v_and_b32_e32 v15, 0xffff0000, v15
	v_lshl_add_u64 v[20:21], v[18:19], 2, s[76:77]
	v_add_u32_e32 v2, 0xf00, v2
	v_lshl_add_u64 v[18:19], v[18:19], 1, s[12:13]
	s_waitcnt vmcnt(1)
	v_pk_add_f32 v[4:5], v[4:5], v[22:23]
	v_pk_add_f32 v[6:7], v[6:7], v[12:13]
	s_waitcnt vmcnt(0)
	v_pk_add_f32 v[8:9], v[8:9], v[24:25]
	v_pk_add_f32 v[10:11], v[10:11], v[14:15]
	v_cvt_pk_bf16_f32 v4, v4, v5
	v_cvt_pk_bf16_f32 v5, v6, v7
	v_cvt_pk_bf16_f32 v6, v8, v9
	v_cvt_pk_bf16_f32 v7, v10, v11
	global_store_dwordx4 v[16:17], v[4:7], off
	global_load_dwordx4 v[4:7], v[20:21], off
	v_mad_u64_u32 v[12:13], s[36:37], v26, s27, v[0:1]
	global_load_dwordx4 v[8:11], v[20:21], off offset:16
	ds_read_b128 v[12:15], v12
	v_ashrrev_i32_e32 v24, 4, v2
	v_add_u32_e32 v2, s33, v24
	v_ashrrev_i32_e32 v3, 31, v2
	v_lshlrev_b64 v[16:17], 10, v[2:3]
	s_waitcnt lgkmcnt(0)
	v_lshlrev_b32_e32 v2, 16, v12
	v_and_b32_e32 v3, 0xffff0000, v12
	v_lshlrev_b32_e32 v12, 16, v13
	v_and_b32_e32 v13, 0xffff0000, v13
	v_lshlrev_b32_e32 v22, 16, v14
	v_and_b32_e32 v23, 0xffff0000, v14
	v_lshlrev_b32_e32 v14, 16, v15
	v_and_b32_e32 v15, 0xffff0000, v15
	v_or3_b32 v16, v16, s34, v1
	v_lshl_add_u64 v[20:21], v[16:17], 2, s[76:77]
	v_mad_u64_u32 v[0:1], s[34:35], v24, s27, v[0:1]
	s_waitcnt vmcnt(1)
	v_pk_add_f32 v[2:3], v[4:5], v[2:3]
	v_pk_add_f32 v[4:5], v[6:7], v[12:13]
	v_cvt_pk_bf16_f32 v2, v2, v3
	s_waitcnt vmcnt(0)
	v_pk_add_f32 v[6:7], v[8:9], v[22:23]
	v_pk_add_f32 v[8:9], v[10:11], v[14:15]
	v_cvt_pk_bf16_f32 v3, v4, v5
	v_cvt_pk_bf16_f32 v4, v6, v7
	v_cvt_pk_bf16_f32 v5, v8, v9
	global_store_dwordx4 v[18:19], v[2:5], off
	global_load_dwordx4 v[2:5], v[20:21], off
	ds_read_b128 v[10:13], v0
	global_load_dwordx4 v[6:9], v[20:21], off offset:16
	v_lshl_add_u64 v[14:15], v[16:17], 1, s[12:13]
	s_waitcnt lgkmcnt(0)
	v_lshlrev_b32_e32 v0, 16, v10
	v_and_b32_e32 v1, 0xffff0000, v10
	v_lshlrev_b32_e32 v10, 16, v11
	v_and_b32_e32 v11, 0xffff0000, v11
	v_lshlrev_b32_e32 v16, 16, v12
	v_and_b32_e32 v17, 0xffff0000, v12
	v_lshlrev_b32_e32 v12, 16, v13
	v_and_b32_e32 v13, 0xffff0000, v13
	s_waitcnt vmcnt(1)
	v_pk_add_f32 v[0:1], v[2:3], v[0:1]
	v_pk_add_f32 v[2:3], v[4:5], v[10:11]
	s_waitcnt vmcnt(0)
	v_pk_add_f32 v[4:5], v[6:7], v[16:17]
	v_pk_add_f32 v[6:7], v[8:9], v[12:13]
	v_cvt_pk_bf16_f32 v0, v0, v1
	v_cvt_pk_bf16_f32 v1, v2, v3
	v_cvt_pk_bf16_f32 v2, v4, v5
	v_cvt_pk_bf16_f32 v3, v6, v7
	global_store_dwordx4 v[14:15], v[0:3], off
	v_mov_b32_e32 v243, 0x12000
	v_readfirstlane_b32 s98, v218
	s_cmp_lg_u32 s98, 0
	s_cbranch_scc1 .Lp6_dyn_skip_b
	s_waitcnt vmcnt(16)
	s_mov_b64 s[100:101], exec
	s_mov_b64 exec, 1
	ds_write_b32 v243, v240
	s_waitcnt lgkmcnt(0)
	s_mov_b64 exec, s[100:101]

; DI int tidx() { int t = __builtin_amdgcn_workitem_id_x(); asm volatile("" : "+v"(t)); return t; }
;   DI unsigned rowoff(int r, int sch) const { const int g = r & 3, bc = r >> 2, b = bc / NCMP, c = bc - b * NCMP; return (unsigned)(b * Sn + c * 16) * 512u + g * 64 + sch; }
; template <int NI, class XL, class EP>
; DI void gemm_tile(const u16* __restrict__ W, int ldw, int f0, int t0, int K, XL xl, EP ep, unsigned char* smem) {
;     ...
;   const int tid = tidx(), lane = tid & 63, wave = tid >> 6;
;   const int wf = wave >> 1, wt = wave & 1, lr = lane & 15, lq = lane >> 4;
;   const int srow = tid >> 2, sch = (tid & 3) * 8;
;   f32x4 acc[4][NI];
; #pragma unroll
;   for (int i = 0; i < 4; ++i)
; #pragma unroll
;     for (int j = 0; j < NI; ++j) acc[i][j] = (f32x4){0.f, 0.f, 0.f, 0.f};
;   u32x4 wr[2], xr[XR];
;   const unsigned wbyte = ((unsigned)(f0 + srow * 2) * 32u + sch) * 2u;
;   const unsigned xbyte = xl.rowoff(t0 + srow * XR, sch) * 2u;
;   const int xrs = xl.rstride();
;   const int nk = K >> 5;
;   auto gload = [&](int it) {
;     const int k = it * 32;
;     const char* wb = (const char*)(W + (size_t)(k >> 5) * ldw * 32);
;     const char* xb = (const char*)xl.kbase(k);
; #pragma unroll
;     for (int i = 0; i < 2; ++i) wr[i] = *(const u32x4*)(wb + wbyte + i * 64);
; #pragma unroll
;     for (int i = 0; i < XR; ++i) xr[i] = *(const u32x4*)(xb + xbyte + i * xrs);
;   };
;   auto lstore = [&](int buf) {
;     u16* Ws = S0 + buf * BUF; u16* Xs = Ws + 128 * LST;
; #pragma unroll
;     for (int i = 0; i < 2; ++i) *(u32x4*)(Ws + (srow * 2 + i) * LST + sch) = wr[i];
; #pragma unroll
;     for (int i = 0; i < XR; ++i) *(u32x4*)(Xs + (srow * XR + i) * LST + sch) = xr[i];
;   };
;   gload(0);
;   __syncthreads();
;   lstore(0);
;   __syncthreads();
;   if (nk > 1) gload(1);
.Lp8_dyn_skip_a:
	s_ashr_i32 s4, s55, 2
	v_mov_b32_e32 v48, v218
	s_add_i32 s30, s4, s51
	s_and_b32 s4, s55, 3
	s_or_b32 s56, s4, s52
	v_ashrrev_i32_e32 v49, 2, v48
	v_lshlrev_b32_e32 v0, 3, v48
	v_lshlrev_b32_e32 v51, 6, v49
	v_and_b32_e32 v50, 24, v0
	v_lshl_add_u32 v0, s56, 12, v51
	v_or_b32_e32 v0, v0, v50
	v_lshlrev_b32_e32 v54, 1, v0
	v_lshlrev_b32_e32 v0, 6, v48
	v_and_b32_e32 v0, 0xffffff00, v0
	v_lshl_add_u32 v0, s30, 14, v0
	v_lshlrev_b32_e32 v171, 1, v50
	v_readlane_b32 s4, v245, 25
	v_or_b32_e32 v152, v0, v171
	v_readlane_b32 s5, v245, 26
	global_load_dwordx4 v[16:19], v54, s[60:61]
	global_load_dwordx4 v[20:23], v54, s[60:61] offset:64
	s_nop 2
	global_load_dwordx4 v[24:27], v152, s[4:5]
	global_load_dwordx4 v[28:31], v152, s[4:5] offset:64
	global_load_dwordx4 v[32:35], v152, s[4:5] offset:128
	global_load_dwordx4 v[36:39], v152, s[4:5] offset:192
	v_mul_lo_u32 v174, v49, s37
	v_or_b32_e32 v170, v174, v171
	v_add_u32_e32 v169, v170, v174
	s_barrier
	s_and_b32 s5, s54, 3
	s_add_i32 s5, s53, s5
	v_bfe_u32 v168, v48, 4, 2
	v_ashrrev_i32_e32 v155, 7, v48
	v_and_b32_e32 v55, 15, v48
	v_lshlrev_b32_e32 v48, 1, v48
	v_and_or_b32 v154, v48, s44, v55
	v_lshl_add_u32 v48, s5, 12, v51
	v_mov_b32_e32 v0, 0
	v_lshl_or_b32 v49, v155, 6, v55
	v_or_b32_e32 v48, v48, v50
	s_mov_b32 s4, 1
	v_mov_b32_e32 v157, v153
	v_mov_b32_e32 v1, v0
	v_mov_b32_e32 v2, v0
	v_mov_b32_e32 v3, v0
	v_mov_b32_e32 v4, v0
	v_mov_b32_e32 v5, v0
	v_mov_b32_e32 v6, v0
	v_mov_b32_e32 v7, v0
	v_mov_b32_e32 v8, v0
	v_mov_b32_e32 v9, v0
	v_mov_b32_e32 v10, v0
	v_mov_b32_e32 v11, v0
	v_mov_b32_e32 v12, v0
	v_mov_b32_e32 v13, v0
	v_mov_b32_e32 v14, v0
	v_mov_b32_e32 v15, v0
	v_mov_b32_e32 v40, v0
	v_mov_b32_e32 v41, v0
	v_mov_b32_e32 v42, v0
	v_mov_b32_e32 v43, v0
	v_mov_b32_e32 v44, v0
	v_mov_b32_e32 v45, v0
	v_mov_b32_e32 v46, v0
	v_mov_b32_e32 v47, v0
	v_mov_b32_e32 v52, v0
	v_mov_b32_e32 v53, v0
	v_lshlrev_b32_e32 v172, 4, v168
	v_mul_lo_u32 v175, v49, 48
	v_mul_u32_u24_e32 v173, 48, v154
	v_lshlrev_b32_e32 v156, 1, v48
	v_mov_b64_e32 v[158:159], v[152:153]
	v_mov_b32_e32 v55, v0
	v_mov_b32_e32 v80, v0
	v_mov_b32_e32 v81, v0
	v_mov_b32_e32 v82, v0
	v_mov_b32_e32 v83, v0
	v_mov_b32_e32 v48, v0
	v_mov_b32_e32 v49, v0
	v_mov_b32_e32 v50, v0
	v_mov_b32_e32 v51, v0
	v_mov_b32_e32 v56, v0
	v_mov_b32_e32 v57, v0
	v_mov_b32_e32 v58, v0
	v_mov_b32_e32 v59, v0
	v_mov_b32_e32 v60, v0
	v_mov_b32_e32 v61, v0
	v_mov_b32_e32 v62, v0
	v_mov_b32_e32 v63, v0
	v_mov_b32_e32 v68, v0
	s_waitcnt vmcnt(5)
	ds_write_b128 v170, v[16:19]
	s_waitcnt vmcnt(4)
	ds_write_b128 v170, v[20:23] offset:96
	s_waitcnt vmcnt(3)
	ds_write_b128 v169, v[24:27] offset:12288
	s_waitcnt vmcnt(2)
	ds_write_b128 v169, v[28:31] offset:12384
	s_waitcnt vmcnt(1)
	ds_write_b128 v169, v[32:35] offset:12480
	s_waitcnt vmcnt(0)
	ds_write_b128 v169, v[36:39] offset:12576
	s_waitcnt lgkmcnt(0)
	global_load_dwordx4 v[20:23], v54, s[20:21]
	global_load_dwordx4 v[16:19], v54, s[20:21] offset:64
	global_load_dwordx4 v[36:39], v152, s[18:19]
	global_load_dwordx4 v[32:35], v152, s[18:19] offset:64
	global_load_dwordx4 v[28:31], v152, s[18:19] offset:128
	global_load_dwordx4 v[24:27], v152, s[18:19] offset:192
	s_add_u32 s98, s42, s45
	s_addc_u32 s99, s43, 0
	s_add_u32 s100, s42, s46
	s_addc_u32 s101, s43, 0
	global_load_dwordx4 v[200:203], v156, s[98:99]
	global_load_dwordx4 v[204:207], v156, s[98:99] offset:64
	global_load_dwordx4 v[208:211], v158, s[100:101] offset:2048
	global_load_dwordx4 v[212:215], v158, s[100:101] offset:2112
	global_load_dwordx4 v[220:223], v158, s[100:101] offset:2176
	global_load_dwordx4 v[224:227], v158, s[100:101] offset:2240
	s_add_u32 s98, s98, s28
	s_addc_u32 s99, s99, s29
	s_add_u32 s100, s100, s26
	s_addc_u32 s101, s101, s27
	v_mov_b32_e32 v54, v0
	v_mov_b32_e32 v69, v0
	v_mov_b32_e32 v70, v0
	v_mov_b32_e32 v71, v0
	v_mov_b32_e32 v76, v0
	v_mov_b32_e32 v77, v0
	v_mov_b32_e32 v78, v0
	v_mov_b32_e32 v79, v0
	v_mov_b32_e32 v88, v0
	v_mov_b32_e32 v89, v0
	v_mov_b32_e32 v90, v0
	v_mov_b32_e32 v91, v0
	v_mov_b32_e32 v100, v0
	v_mov_b32_e32 v101, v0
	v_mov_b32_e32 v102, v0
	v_mov_b32_e32 v103, v0
	v_mov_b32_e32 v112, v0
	v_mov_b32_e32 v113, v0
	v_mov_b32_e32 v114, v0
	v_mov_b32_e32 v115, v0
	v_mov_b32_e32 v64, v0
	v_mov_b32_e32 v65, v0
	v_mov_b32_e32 v66, v0
	v_mov_b32_e32 v67, v0
	v_mov_b32_e32 v72, v0
	v_mov_b32_e32 v73, v0
	v_mov_b32_e32 v74, v0
	v_mov_b32_e32 v75, v0
	v_mov_b32_e32 v84, v0
	v_mov_b32_e32 v85, v0
	v_mov_b32_e32 v86, v0
	v_mov_b32_e32 v87, v0
	v_mov_b32_e32 v96, v0
	v_mov_b32_e32 v97, v0
	v_mov_b32_e32 v98, v0
	v_mov_b32_e32 v99, v0
	v_mov_b32_e32 v108, v0
	v_mov_b32_e32 v109, v0
	v_mov_b32_e32 v110, v0
	v_mov_b32_e32 v111, v0
	v_mov_b32_e32 v120, v0
	v_mov_b32_e32 v121, v0
	v_mov_b32_e32 v122, v0
	v_mov_b32_e32 v123, v0
	v_mov_b32_e32 v128, v0
	v_mov_b32_e32 v129, v0
	v_mov_b32_e32 v130, v0
	v_mov_b32_e32 v131, v0
	v_mov_b32_e32 v136, v0
	v_mov_b32_e32 v137, v0
	v_mov_b32_e32 v138, v0
	v_mov_b32_e32 v139, v0
	v_mov_b32_e32 v92, v0
	v_mov_b32_e32 v93, v0
	v_mov_b32_e32 v94, v0
	v_mov_b32_e32 v95, v0
	v_mov_b32_e32 v104, v0
	v_mov_b32_e32 v105, v0
	v_mov_b32_e32 v106, v0
	v_mov_b32_e32 v107, v0
	v_mov_b32_e32 v116, v0
	v_mov_b32_e32 v117, v0
	v_mov_b32_e32 v118, v0
	v_mov_b32_e32 v119, v0
	v_mov_b32_e32 v124, v0
	v_mov_b32_e32 v125, v0
	v_mov_b32_e32 v126, v0
	v_mov_b32_e32 v127, v0
	v_mov_b32_e32 v132, v0
	v_mov_b32_e32 v133, v0
	v_mov_b32_e32 v134, v0
	v_mov_b32_e32 v135, v0
	v_mov_b32_e32 v140, v0
	v_mov_b32_e32 v141, v0
	v_mov_b32_e32 v142, v0
	v_mov_b32_e32 v143, v0
	v_mov_b32_e32 v144, v0
	v_mov_b32_e32 v145, v0
	v_mov_b32_e32 v146, v0
	v_mov_b32_e32 v147, v0
	v_mov_b32_e32 v148, v0
	v_mov_b32_e32 v149, v0
	v_mov_b32_e32 v150, v0
	v_mov_b32_e32 v151, v0
	v_lshl_add_u32 v228, v175, 1, v172
	v_lshl_add_u32 v152, v173, 1, v172
	v_add_u32_e32 v229, v174, v171
	v_add_u32_e32 v230, v229, v174
; DI f32x4 mfma16(bf16x8 a, bf16x8 b, f32x4 c) { return __builtin_amdgcn_mfma_f32_16x16x32_bf16(a, b, c, 0, 0, 0); }
; template <int NI, class XL, class EP>
; DI void gemm_tile(const u16* __restrict__ W, int ldw, int f0, int t0, int K, XL xl, EP ep, unsigned char* smem) {
;     ...
;   for (int it = 0; it < nk; ++it) {
;     const u16* Ws = S0 + (it & 1) * BUF; const u16* Xs = Ws + 128 * LST;
;     __builtin_amdgcn_s_setprio(1);
;     bf16x8 a[4];
; #pragma unroll
;     for (int mi = 0; mi < 4; ++mi) a[mi] = *(const bf16x8*)(Ws + (wf * 64 + mi * 16 + lr) * LST + lq * 8);
; #pragma unroll
;     for (int ni = 0; ni < NI; ++ni) {
;       const bf16x8 b = *(const bf16x8*)(Xs + (wt * (NI * 16) + ni * 16 + lr) * LST + lq * 8);
; #pragma unroll
;       for (int mi = 0; mi < 4; ++mi) acc[mi][ni] = mfma16(a[mi], b, acc[mi][ni]);
;     }
;     __builtin_amdgcn_sched_group_barrier(0x100, 6, 0);
; #pragma unroll
;     for (int ni = 0; ni < NI; ++ni) { __builtin_amdgcn_sched_group_barrier(0x008, 4, 0); if (ni + 2 < NI) __builtin_amdgcn_sched_group_barrier(0x100, 1, 0); }
;     __builtin_amdgcn_s_setprio(0);
;     if (it + 1 < nk) lstore((it + 1) & 1);
;     if (it + 2 < nk) gload(it + 2);
;     __syncthreads();
.LBB0_945:
	s_barrier
	s_setprio 1
	ds_read_b128 v[176:179], v228 offset:0
	ds_read_b128 v[180:183], v228 offset:1536
	ds_read_b128 v[188:191], v228 offset:3072
	ds_read_b128 v[192:195], v228 offset:4608
	ds_read_b128 v[184:187], v152 offset:12288
	ds_read_b128 v[196:199], v152 offset:13824
	s_waitcnt lgkmcnt(1)
	v_mfma_f32_16x16x32_bf16 v[148:151], v[176:179], v[184:187], v[148:151]
	v_mfma_f32_16x16x32_bf16 v[136:139], v[180:183], v[184:187], v[136:139]
	v_mfma_f32_16x16x32_bf16 v[112:115], v[188:191], v[184:187], v[112:115]
	v_mfma_f32_16x16x32_bf16 v[80:83], v[192:195], v[184:187], v[80:83]
	ds_read_b128 v[184:187], v152 offset:15360
	s_waitcnt vmcnt(6)
	ds_write_b128 v229, v[20:23] offset:36864
	s_waitcnt lgkmcnt(2)
	v_mfma_f32_16x16x32_bf16 v[144:147], v[176:179], v[196:199], v[144:147]
	v_mfma_f32_16x16x32_bf16 v[128:131], v[180:183], v[196:199], v[128:131]
	v_mfma_f32_16x16x32_bf16 v[100:103], v[188:191], v[196:199], v[100:103]
	v_mfma_f32_16x16x32_bf16 v[52:55], v[192:195], v[196:199], v[52:55]
	ds_read_b128 v[196:199], v152 offset:16896
	ds_write_b128 v229, v[16:19] offset:36960
	global_load_dwordx4 v[20:23], v156, s[98:99]
	global_load_dwordx4 v[16:19], v156, s[98:99] offset:64
	s_waitcnt lgkmcnt(3)
	v_mfma_f32_16x16x32_bf16 v[140:143], v[176:179], v[184:187], v[140:143]
	v_mfma_f32_16x16x32_bf16 v[120:123], v[180:183], v[184:187], v[120:123]
	v_mfma_f32_16x16x32_bf16 v[88:91], v[188:191], v[184:187], v[88:91]
	v_mfma_f32_16x16x32_bf16 v[44:47], v[192:195], v[184:187], v[44:47]
	ds_read_b128 v[184:187], v152 offset:18432
	ds_write_b128 v230, v[36:39] offset:49152
	global_load_dwordx4 v[36:39], v158, s[100:101] offset:2048
	s_waitcnt lgkmcnt(3)
	v_mfma_f32_16x16x32_bf16 v[132:135], v[176:179], v[196:199], v[132:135]
	v_mfma_f32_16x16x32_bf16 v[108:111], v[180:183], v[196:199], v[108:111]
	v_mfma_f32_16x16x32_bf16 v[76:79], v[188:191], v[196:199], v[76:79]
	v_mfma_f32_16x16x32_bf16 v[40:43], v[192:195], v[196:199], v[40:43]
	ds_read_b128 v[196:199], v152 offset:19968
	ds_write_b128 v230, v[32:35] offset:49248
	global_load_dwordx4 v[32:35], v158, s[100:101] offset:2112
	s_waitcnt lgkmcnt(3)
	v_mfma_f32_16x16x32_bf16 v[124:127], v[176:179], v[184:187], v[124:127]
	v_mfma_f32_16x16x32_bf16 v[96:99], v[180:183], v[184:187], v[96:99]
	v_mfma_f32_16x16x32_bf16 v[68:71], v[188:191], v[184:187], v[68:71]
	v_mfma_f32_16x16x32_bf16 v[12:15], v[192:195], v[184:187], v[12:15]
	ds_read_b128 v[184:187], v152 offset:21504
	ds_write_b128 v230, v[28:31] offset:49344
	global_load_dwordx4 v[28:31], v158, s[100:101] offset:2176
	s_waitcnt lgkmcnt(3)
	v_mfma_f32_16x16x32_bf16 v[116:119], v[176:179], v[196:199], v[116:119]
	v_mfma_f32_16x16x32_bf16 v[84:87], v[180:183], v[196:199], v[84:87]
	v_mfma_f32_16x16x32_bf16 v[60:63], v[188:191], v[196:199], v[60:63]
	v_mfma_f32_16x16x32_bf16 v[8:11], v[192:195], v[196:199], v[8:11]
	ds_read_b128 v[196:199], v152 offset:23040
	ds_write_b128 v230, v[24:27] offset:49440
	global_load_dwordx4 v[24:27], v158, s[100:101] offset:2240
	s_waitcnt lgkmcnt(3)
	v_mfma_f32_16x16x32_bf16 v[104:107], v[176:179], v[184:187], v[104:107]
	v_mfma_f32_16x16x32_bf16 v[72:75], v[180:183], v[184:187], v[72:75]
	v_mfma_f32_16x16x32_bf16 v[56:59], v[188:191], v[184:187], v[56:59]
	v_mfma_f32_16x16x32_bf16 v[4:7], v[192:195], v[184:187], v[4:7]
	s_add_u32 s98, s98, s28
	s_addc_u32 s99, s99, s29
	s_add_u32 s100, s100, s26
	s_addc_u32 s101, s101, s27
	s_waitcnt lgkmcnt(1)
	v_mfma_f32_16x16x32_bf16 v[92:95], v[176:179], v[196:199], v[92:95]
	v_mfma_f32_16x16x32_bf16 v[64:67], v[180:183], v[196:199], v[64:67]
	v_mfma_f32_16x16x32_bf16 v[48:51], v[188:191], v[196:199], v[48:51]
	v_mfma_f32_16x16x32_bf16 v[0:3], v[192:195], v[196:199], v[0:3]
	s_setprio 0
	s_waitcnt lgkmcnt(0)
	s_barrier
	s_setprio 1
	ds_read_b128 v[176:179], v228 offset:36864
	ds_read_b128 v[180:183], v228 offset:38400
	ds_read_b128 v[188:191], v228 offset:39936
	ds_read_b128 v[192:195], v228 offset:41472
	ds_read_b128 v[184:187], v152 offset:49152
	ds_read_b128 v[196:199], v152 offset:50688
	s_waitcnt lgkmcnt(1)
	v_mfma_f32_16x16x32_bf16 v[148:151], v[176:179], v[184:187], v[148:151]
	v_mfma_f32_16x16x32_bf16 v[136:139], v[180:183], v[184:187], v[136:139]
	v_mfma_f32_16x16x32_bf16 v[112:115], v[188:191], v[184:187], v[112:115]
	v_mfma_f32_16x16x32_bf16 v[80:83], v[192:195], v[184:187], v[80:83]
	ds_read_b128 v[184:187], v152 offset:52224
	s_waitcnt vmcnt(6)
	ds_write_b128 v229, v[200:203] offset:0
	s_waitcnt lgkmcnt(2)
	v_mfma_f32_16x16x32_bf16 v[144:147], v[176:179], v[196:199], v[144:147]
	v_mfma_f32_16x16x32_bf16 v[128:131], v[180:183], v[196:199], v[128:131]
	v_mfma_f32_16x16x32_bf16 v[100:103], v[188:191], v[196:199], v[100:103]
	v_mfma_f32_16x16x32_bf16 v[52:55], v[192:195], v[196:199], v[52:55]
	ds_read_b128 v[196:199], v152 offset:53760
	ds_write_b128 v229, v[204:207] offset:96
	global_load_dwordx4 v[200:203], v156, s[98:99]
	global_load_dwordx4 v[204:207], v156, s[98:99] offset:64
	s_waitcnt lgkmcnt(3)
	v_mfma_f32_16x16x32_bf16 v[140:143], v[176:179], v[184:187], v[140:143]
	v_mfma_f32_16x16x32_bf16 v[120:123], v[180:183], v[184:187], v[120:123]
	v_mfma_f32_16x16x32_bf16 v[88:91], v[188:191], v[184:187], v[88:91]
	v_mfma_f32_16x16x32_bf16 v[44:47], v[192:195], v[184:187], v[44:47]
	ds_read_b128 v[184:187], v152 offset:55296
	ds_write_b128 v230, v[208:211] offset:12288
	global_load_dwordx4 v[208:211], v158, s[100:101] offset:2048
	s_waitcnt lgkmcnt(3)
; DI f32x4 mfma16(bf16x8 a, bf16x8 b, f32x4 c) { return __builtin_amdgcn_mfma_f32_16x16x32_bf16(a, b, c, 0, 0, 0); }
; template <int NI, class XL, class EP>
; DI void gemm_tile(const u16* __restrict__ W, int ldw, int f0, int t0, int K, XL xl, EP ep, unsigned char* smem) {
;     ...
;   for (int it = 0; it < nk; ++it) {
;     const u16* Ws = S0 + (it & 1) * BUF; const u16* Xs = Ws + 128 * LST;
;     __builtin_amdgcn_s_setprio(1);
;     bf16x8 a[4];
; #pragma unroll
;     for (int mi = 0; mi < 4; ++mi) a[mi] = *(const bf16x8*)(Ws + (wf * 64 + mi * 16 + lr) * LST + lq * 8);
; #pragma unroll
;     for (int ni = 0; ni < NI; ++ni) {
;       const bf16x8 b = *(const bf16x8*)(Xs + (wt * (NI * 16) + ni * 16 + lr) * LST + lq * 8);
; #pragma unroll
;       for (int mi = 0; mi < 4; ++mi) acc[mi][ni] = mfma16(a[mi], b, acc[mi][ni]);
;     }
;     __builtin_amdgcn_sched_group_barrier(0x100, 6, 0);
; #pragma unroll
;     for (int ni = 0; ni < NI; ++ni) { __builtin_amdgcn_sched_group_barrier(0x008, 4, 0); if (ni + 2 < NI) __builtin_amdgcn_sched_group_barrier(0x100, 1, 0); }
;     __builtin_amdgcn_s_setprio(0);
;     if (it + 1 < nk) lstore((it + 1) & 1);
;     if (it + 2 < nk) gload(it + 2);
;     __syncthreads();
	v_mfma_f32_16x16x32_bf16 v[132:135], v[176:179], v[196:199], v[132:135]
	v_mfma_f32_16x16x32_bf16 v[108:111], v[180:183], v[196:199], v[108:111]
	v_mfma_f32_16x16x32_bf16 v[76:79], v[188:191], v[196:199], v[76:79]
	v_mfma_f32_16x16x32_bf16 v[40:43], v[192:195], v[196:199], v[40:43]
	ds_read_b128 v[196:199], v152 offset:56832
	ds_write_b128 v230, v[212:215] offset:12384
	global_load_dwordx4 v[212:215], v158, s[100:101] offset:2112
	s_waitcnt lgkmcnt(3)
	v_mfma_f32_16x16x32_bf16 v[124:127], v[176:179], v[184:187], v[124:127]
	v_mfma_f32_16x16x32_bf16 v[96:99], v[180:183], v[184:187], v[96:99]
	v_mfma_f32_16x16x32_bf16 v[68:71], v[188:191], v[184:187], v[68:71]
	v_mfma_f32_16x16x32_bf16 v[12:15], v[192:195], v[184:187], v[12:15]
	ds_read_b128 v[184:187], v152 offset:58368
	ds_write_b128 v230, v[220:223] offset:12480
	global_load_dwordx4 v[220:223], v158, s[100:101] offset:2176
	s_waitcnt lgkmcnt(3)
	v_mfma_f32_16x16x32_bf16 v[116:119], v[176:179], v[196:199], v[116:119]
	v_mfma_f32_16x16x32_bf16 v[84:87], v[180:183], v[196:199], v[84:87]
	v_mfma_f32_16x16x32_bf16 v[60:63], v[188:191], v[196:199], v[60:63]
	v_mfma_f32_16x16x32_bf16 v[8:11], v[192:195], v[196:199], v[8:11]
	ds_read_b128 v[196:199], v152 offset:59904
	ds_write_b128 v230, v[224:227] offset:12576
	global_load_dwordx4 v[224:227], v158, s[100:101] offset:2240
	s_waitcnt lgkmcnt(3)
	v_mfma_f32_16x16x32_bf16 v[104:107], v[176:179], v[184:187], v[104:107]
	v_mfma_f32_16x16x32_bf16 v[72:75], v[180:183], v[184:187], v[72:75]
	v_mfma_f32_16x16x32_bf16 v[56:59], v[188:191], v[184:187], v[56:59]
	v_mfma_f32_16x16x32_bf16 v[4:7], v[192:195], v[184:187], v[4:7]
	s_add_u32 s98, s98, s28
	s_addc_u32 s99, s99, s29
	s_add_u32 s100, s100, s26
	s_addc_u32 s101, s101, s27
	s_add_i32 s4, s4, 2
	s_waitcnt lgkmcnt(1)
	v_mfma_f32_16x16x32_bf16 v[92:95], v[176:179], v[196:199], v[92:95]
	v_mfma_f32_16x16x32_bf16 v[64:67], v[180:183], v[196:199], v[64:67]
	v_mfma_f32_16x16x32_bf16 v[48:51], v[188:191], v[196:199], v[48:51]
	v_mfma_f32_16x16x32_bf16 v[0:3], v[192:195], v[196:199], v[0:3]
	s_setprio 0
	s_cmp_eq_u32 s4, 29
	s_waitcnt lgkmcnt(0)
	s_cbranch_scc0 .LBB0_945
	s_barrier
	s_setprio 1
	ds_read_b128 v[176:179], v228 offset:0
	ds_read_b128 v[180:183], v228 offset:1536
	ds_read_b128 v[188:191], v228 offset:3072
	ds_read_b128 v[192:195], v228 offset:4608
	ds_read_b128 v[184:187], v152 offset:12288
	ds_read_b128 v[196:199], v152 offset:13824
	s_waitcnt lgkmcnt(1)
	v_mfma_f32_16x16x32_bf16 v[148:151], v[176:179], v[184:187], v[148:151]
	v_mfma_f32_16x16x32_bf16 v[136:139], v[180:183], v[184:187], v[136:139]
	v_mfma_f32_16x16x32_bf16 v[112:115], v[188:191], v[184:187], v[112:115]
	v_mfma_f32_16x16x32_bf16 v[80:83], v[192:195], v[184:187], v[80:83]
	ds_read_b128 v[184:187], v152 offset:15360
	s_waitcnt vmcnt(6)
	ds_write_b128 v229, v[20:23] offset:36864
	s_waitcnt lgkmcnt(2)
	v_mfma_f32_16x16x32_bf16 v[144:147], v[176:179], v[196:199], v[144:147]
	v_mfma_f32_16x16x32_bf16 v[128:131], v[180:183], v[196:199], v[128:131]
	v_mfma_f32_16x16x32_bf16 v[100:103], v[188:191], v[196:199], v[100:103]
	v_mfma_f32_16x16x32_bf16 v[52:55], v[192:195], v[196:199], v[52:55]
	ds_read_b128 v[196:199], v152 offset:16896
	ds_write_b128 v229, v[16:19] offset:36960
	global_load_dwordx4 v[20:23], v156, s[98:99]
	global_load_dwordx4 v[16:19], v156, s[98:99] offset:64
	s_waitcnt lgkmcnt(3)
	v_mfma_f32_16x16x32_bf16 v[140:143], v[176:179], v[184:187], v[140:143]
	v_mfma_f32_16x16x32_bf16 v[120:123], v[180:183], v[184:187], v[120:123]
	v_mfma_f32_16x16x32_bf16 v[88:91], v[188:191], v[184:187], v[88:91]
	v_mfma_f32_16x16x32_bf16 v[44:47], v[192:195], v[184:187], v[44:47]
	ds_read_b128 v[184:187], v152 offset:18432
	ds_write_b128 v230, v[36:39] offset:49152
	global_load_dwordx4 v[36:39], v158, s[100:101] offset:2048
	s_waitcnt lgkmcnt(3)
	v_mfma_f32_16x16x32_bf16 v[132:135], v[176:179], v[196:199], v[132:135]
	v_mfma_f32_16x16x32_bf16 v[108:111], v[180:183], v[196:199], v[108:111]
	v_mfma_f32_16x16x32_bf16 v[76:79], v[188:191], v[196:199], v[76:79]
	v_mfma_f32_16x16x32_bf16 v[40:43], v[192:195], v[196:199], v[40:43]
	ds_read_b128 v[196:199], v152 offset:19968
	ds_write_b128 v230, v[32:35] offset:49248
	global_load_dwordx4 v[32:35], v158, s[100:101] offset:2112
	s_waitcnt lgkmcnt(3)
	v_mfma_f32_16x16x32_bf16 v[124:127], v[176:179], v[184:187], v[124:127]
	v_mfma_f32_16x16x32_bf16 v[96:99], v[180:183], v[184:187], v[96:99]
	v_mfma_f32_16x16x32_bf16 v[68:71], v[188:191], v[184:187], v[68:71]
	v_mfma_f32_16x16x32_bf16 v[12:15], v[192:195], v[184:187], v[12:15]
	ds_read_b128 v[184:187], v152 offset:21504
	ds_write_b128 v230, v[28:31] offset:49344
	global_load_dwordx4 v[28:31], v158, s[100:101] offset:2176
	s_waitcnt lgkmcnt(3)
	v_mfma_f32_16x16x32_bf16 v[116:119], v[176:179], v[196:199], v[116:119]
	v_mfma_f32_16x16x32_bf16 v[84:87], v[180:183], v[196:199], v[84:87]
	v_mfma_f32_16x16x32_bf16 v[60:63], v[188:191], v[196:199], v[60:63]
	v_mfma_f32_16x16x32_bf16 v[8:11], v[192:195], v[196:199], v[8:11]
	ds_read_b128 v[196:199], v152 offset:23040
	ds_write_b128 v230, v[24:27] offset:49440
	global_load_dwordx4 v[24:27], v158, s[100:101] offset:2240
	s_waitcnt lgkmcnt(3)
	v_mfma_f32_16x16x32_bf16 v[104:107], v[176:179], v[184:187], v[104:107]
	v_mfma_f32_16x16x32_bf16 v[72:75], v[180:183], v[184:187], v[72:75]
	v_mfma_f32_16x16x32_bf16 v[56:59], v[188:191], v[184:187], v[56:59]
	v_mfma_f32_16x16x32_bf16 v[4:7], v[192:195], v[184:187], v[4:7]
	s_add_u32 s98, s98, s28
	s_addc_u32 s99, s99, s29
	s_add_u32 s100, s100, s26
	s_addc_u32 s101, s101, s27
	s_waitcnt lgkmcnt(1)
	v_mfma_f32_16x16x32_bf16 v[92:95], v[176:179], v[196:199], v[92:95]
	v_mfma_f32_16x16x32_bf16 v[64:67], v[180:183], v[196:199], v[64:67]
	v_mfma_f32_16x16x32_bf16 v[48:51], v[188:191], v[196:199], v[48:51]
	v_mfma_f32_16x16x32_bf16 v[0:3], v[192:195], v[196:199], v[0:3]
	s_setprio 0
	s_waitcnt lgkmcnt(0)
	s_barrier
; DI f32x4 mfma16(bf16x8 a, bf16x8 b, f32x4 c) { return __builtin_amdgcn_mfma_f32_16x16x32_bf16(a, b, c, 0, 0, 0); }
; template <int NI, class XL, class EP>
; DI void gemm_tile(const u16* __restrict__ W, int ldw, int f0, int t0, int K, XL xl, EP ep, unsigned char* smem) {
;     ...
;   for (int it = 0; it < nk; ++it) {
;     const u16* Ws = S0 + (it & 1) * BUF; const u16* Xs = Ws + 128 * LST;
;     __builtin_amdgcn_s_setprio(1);
;     bf16x8 a[4];
; #pragma unroll
;     for (int mi = 0; mi < 4; ++mi) a[mi] = *(const bf16x8*)(Ws + (wf * 64 + mi * 16 + lr) * LST + lq * 8);
; #pragma unroll
;     for (int ni = 0; ni < NI; ++ni) {
;       const bf16x8 b = *(const bf16x8*)(Xs + (wt * (NI * 16) + ni * 16 + lr) * LST + lq * 8);
; #pragma unroll
;       for (int mi = 0; mi < 4; ++mi) acc[mi][ni] = mfma16(a[mi], b, acc[mi][ni]);
;     }
;     __builtin_amdgcn_sched_group_barrier(0x100, 6, 0);
; #pragma unroll
;     for (int ni = 0; ni < NI; ++ni) { __builtin_amdgcn_sched_group_barrier(0x008, 4, 0); if (ni + 2 < NI) __builtin_amdgcn_sched_group_barrier(0x100, 1, 0); }
;     __builtin_amdgcn_s_setprio(0);
;     if (it + 1 < nk) lstore((it + 1) & 1);
;     if (it + 2 < nk) gload(it + 2);
;     __syncthreads();
	s_setprio 1
	ds_read_b128 v[176:179], v228 offset:36864
	ds_read_b128 v[180:183], v228 offset:38400
	ds_read_b128 v[188:191], v228 offset:39936
	ds_read_b128 v[192:195], v228 offset:41472
	ds_read_b128 v[184:187], v152 offset:49152
	ds_read_b128 v[196:199], v152 offset:50688
	s_waitcnt lgkmcnt(1)
	v_mfma_f32_16x16x32_bf16 v[148:151], v[176:179], v[184:187], v[148:151]
	v_mfma_f32_16x16x32_bf16 v[136:139], v[180:183], v[184:187], v[136:139]
	v_mfma_f32_16x16x32_bf16 v[112:115], v[188:191], v[184:187], v[112:115]
	v_mfma_f32_16x16x32_bf16 v[80:83], v[192:195], v[184:187], v[80:83]
	ds_read_b128 v[184:187], v152 offset:52224
	s_waitcnt vmcnt(6)
	ds_write_b128 v229, v[200:203] offset:0
	s_waitcnt lgkmcnt(2)
	v_mfma_f32_16x16x32_bf16 v[144:147], v[176:179], v[196:199], v[144:147]
	v_mfma_f32_16x16x32_bf16 v[128:131], v[180:183], v[196:199], v[128:131]
	v_mfma_f32_16x16x32_bf16 v[100:103], v[188:191], v[196:199], v[100:103]
	v_mfma_f32_16x16x32_bf16 v[52:55], v[192:195], v[196:199], v[52:55]
	ds_read_b128 v[196:199], v152 offset:53760
	ds_write_b128 v229, v[204:207] offset:96
	s_waitcnt lgkmcnt(3)
	v_mfma_f32_16x16x32_bf16 v[140:143], v[176:179], v[184:187], v[140:143]
	v_mfma_f32_16x16x32_bf16 v[120:123], v[180:183], v[184:187], v[120:123]
	v_mfma_f32_16x16x32_bf16 v[88:91], v[188:191], v[184:187], v[88:91]
	v_mfma_f32_16x16x32_bf16 v[44:47], v[192:195], v[184:187], v[44:47]
	ds_read_b128 v[184:187], v152 offset:55296
	ds_write_b128 v230, v[208:211] offset:12288
	s_waitcnt lgkmcnt(3)
	v_mfma_f32_16x16x32_bf16 v[132:135], v[176:179], v[196:199], v[132:135]
	v_mfma_f32_16x16x32_bf16 v[108:111], v[180:183], v[196:199], v[108:111]
	v_mfma_f32_16x16x32_bf16 v[76:79], v[188:191], v[196:199], v[76:79]
	v_mfma_f32_16x16x32_bf16 v[40:43], v[192:195], v[196:199], v[40:43]
	ds_read_b128 v[196:199], v152 offset:56832
	ds_write_b128 v230, v[212:215] offset:12384
	s_waitcnt lgkmcnt(3)
	v_mfma_f32_16x16x32_bf16 v[124:127], v[176:179], v[184:187], v[124:127]
	v_mfma_f32_16x16x32_bf16 v[96:99], v[180:183], v[184:187], v[96:99]
	v_mfma_f32_16x16x32_bf16 v[68:71], v[188:191], v[184:187], v[68:71]
	v_mfma_f32_16x16x32_bf16 v[12:15], v[192:195], v[184:187], v[12:15]
	ds_read_b128 v[184:187], v152 offset:58368
	ds_write_b128 v230, v[220:223] offset:12480
	s_waitcnt lgkmcnt(3)
	v_mfma_f32_16x16x32_bf16 v[116:119], v[176:179], v[196:199], v[116:119]
	v_mfma_f32_16x16x32_bf16 v[84:87], v[180:183], v[196:199], v[84:87]
	v_mfma_f32_16x16x32_bf16 v[60:63], v[188:191], v[196:199], v[60:63]
	v_mfma_f32_16x16x32_bf16 v[8:11], v[192:195], v[196:199], v[8:11]
	ds_read_b128 v[196:199], v152 offset:59904
	ds_write_b128 v230, v[224:227] offset:12576
	s_waitcnt lgkmcnt(3)
	v_mfma_f32_16x16x32_bf16 v[104:107], v[176:179], v[184:187], v[104:107]
	v_mfma_f32_16x16x32_bf16 v[72:75], v[180:183], v[184:187], v[72:75]
	v_mfma_f32_16x16x32_bf16 v[56:59], v[188:191], v[184:187], v[56:59]
	v_mfma_f32_16x16x32_bf16 v[4:7], v[192:195], v[184:187], v[4:7]
	s_add_i32 s4, s4, 2
	s_waitcnt lgkmcnt(1)
	v_mfma_f32_16x16x32_bf16 v[92:95], v[176:179], v[196:199], v[92:95]
	v_mfma_f32_16x16x32_bf16 v[64:67], v[180:183], v[196:199], v[64:67]
	v_mfma_f32_16x16x32_bf16 v[48:51], v[188:191], v[196:199], v[48:51]
	v_mfma_f32_16x16x32_bf16 v[0:3], v[192:195], v[196:199], v[0:3]
	s_setprio 0
	s_waitcnt lgkmcnt(0)
	s_barrier
	s_setprio 1
	v_lshl_add_u32 v152, v175, 1, v172
	ds_read_b128 v[156:159], v152
	v_lshl_add_u32 v171, v173, 1, v172
	ds_read_b128 v[172:175], v152 offset:1536
	ds_read_b128 v[180:183], v152 offset:3072
	ds_read_b128 v[184:187], v152 offset:4608
	ds_read_b128 v[176:179], v171 offset:12288
	ds_read_b128 v[188:191], v171 offset:13824
	s_waitcnt lgkmcnt(1)
	v_mfma_f32_16x16x32_bf16 v[148:151], v[156:159], v[176:179], v[148:151]
	v_mfma_f32_16x16x32_bf16 v[136:139], v[172:175], v[176:179], v[136:139]
	v_mfma_f32_16x16x32_bf16 v[112:115], v[180:183], v[176:179], v[112:115]
	v_mfma_f32_16x16x32_bf16 v[80:83], v[184:187], v[176:179], v[80:83]
	ds_read_b128 v[176:179], v171 offset:15360
	s_waitcnt vmcnt(5)
	ds_write_b128 v170, v[20:23] offset:36864
	s_waitcnt lgkmcnt(2)
	v_mfma_f32_16x16x32_bf16 v[144:147], v[156:159], v[188:191], v[144:147]
	v_mfma_f32_16x16x32_bf16 v[128:131], v[172:175], v[188:191], v[128:131]
	v_mfma_f32_16x16x32_bf16 v[100:103], v[180:183], v[188:191], v[100:103]
	v_mfma_f32_16x16x32_bf16 v[188:191], v[184:187], v[188:191], v[52:55]
	s_nop 2
	ds_read_b128 v[52:55], v171 offset:16896
	s_waitcnt vmcnt(4)
	ds_write_b128 v170, v[16:19] offset:36960
	s_waitcnt lgkmcnt(3)
	v_mfma_f32_16x16x32_bf16 v[192:195], v[156:159], v[176:179], v[140:143]
	v_mfma_f32_16x16x32_bf16 v[120:123], v[172:175], v[176:179], v[120:123]
	v_mfma_f32_16x16x32_bf16 v[88:91], v[180:183], v[176:179], v[88:91]
	v_mfma_f32_16x16x32_bf16 v[176:179], v[184:187], v[176:179], v[44:47]
	s_nop 2
	ds_read_b128 v[44:47], v171 offset:18432
	s_waitcnt vmcnt(3)
	ds_write_b128 v169, v[36:39] offset:49152
	s_waitcnt lgkmcnt(3)
	v_mfma_f32_16x16x32_bf16 v[196:199], v[156:159], v[52:55], v[132:135]
	v_mfma_f32_16x16x32_bf16 v[108:111], v[172:175], v[52:55], v[108:111]
	v_mfma_f32_16x16x32_bf16 v[76:79], v[180:183], v[52:55], v[76:79]
	v_mfma_f32_16x16x32_bf16 v[200:203], v[184:187], v[52:55], v[40:43]
	s_nop 2
	ds_read_b128 v[40:43], v171 offset:19968
	s_waitcnt vmcnt(2)
	ds_write_b128 v169, v[32:35] offset:49248
	s_waitcnt lgkmcnt(3)
	v_mfma_f32_16x16x32_bf16 v[204:207], v[156:159], v[44:47], v[124:127]
	v_mfma_f32_16x16x32_bf16 v[96:99], v[172:175], v[44:47], v[96:99]
	v_mfma_f32_16x16x32_bf16 v[68:71], v[180:183], v[44:47], v[68:71]
	v_mfma_f32_16x16x32_bf16 v[12:15], v[184:187], v[44:47], v[12:15]
	ds_read_b128 v[44:47], v171 offset:21504
	s_waitcnt vmcnt(1)
	ds_write_b128 v169, v[28:31] offset:49344
	s_waitcnt lgkmcnt(3)
	v_mfma_f32_16x16x32_bf16 v[208:211], v[156:159], v[40:43], v[116:119]
	v_mfma_f32_16x16x32_bf16 v[84:87], v[172:175], v[40:43], v[84:87]
	v_mfma_f32_16x16x32_bf16 v[212:215], v[180:183], v[40:43], v[60:63]
	v_mfma_f32_16x16x32_bf16 v[8:11], v[184:187], v[40:43], v[8:11]
	ds_read_b128 v[40:43], v171 offset:23040
	s_waitcnt vmcnt(0)
	ds_write_b128 v169, v[24:27] offset:49440
	s_waitcnt lgkmcnt(3)
	v_mfma_f32_16x16x32_bf16 v[220:223], v[156:159], v[44:47], v[104:107]
	v_mfma_f32_16x16x32_bf16 v[72:75], v[172:175], v[44:47], v[72:75]
	v_mfma_f32_16x16x32_bf16 v[224:227], v[180:183], v[44:47], v[56:59]
	v_mfma_f32_16x16x32_bf16 v[4:7], v[184:187], v[44:47], v[4:7]
	s_waitcnt lgkmcnt(1)
	v_mfma_f32_16x16x32_bf16 v[156:159], v[156:159], v[40:43], v[92:95]
	v_mfma_f32_16x16x32_bf16 v[172:175], v[172:175], v[40:43], v[64:67]
	v_mfma_f32_16x16x32_bf16 v[180:183], v[180:183], v[40:43], v[48:51]
	v_mfma_f32_16x16x32_bf16 v[184:187], v[184:187], v[40:43], v[0:3]
	s_setprio 0
	s_waitcnt lgkmcnt(0)
	s_barrier
; template <int NI, class XL, class EP>
; DI void gemm_tile(const u16* __restrict__ W, int ldw, int f0, int t0, int K, XL xl, EP ep, unsigned char* smem) {
;     ...
; #pragma unroll
;     for (int mi = 0; mi < 4; ++mi) a[mi] = *(const bf16x8*)(Ws + (wf * 64 + mi * 16 + lr) * LST + lq * 8);
; #pragma unroll
;     for (int ni = 0; ni < NI; ++ni) {
;       const bf16x8 b = *(const bf16x8*)(Xs + (wt * (NI * 16) + ni * 16 + lr) * LST + lq * 8);
; #pragma unroll
;       for (int mi = 0; mi < 4; ++mi) acc[mi][ni] = mfma16(a[mi], b, acc[mi][ni]);
;     }
;     __builtin_amdgcn_sched_group_barrier(0x100, 6, 0);
; #pragma unroll
;     for (int ni = 0; ni < NI; ++ni) { __builtin_amdgcn_sched_group_barrier(0x008, 4, 0); if (ni + 2 < NI) __builtin_amdgcn_sched_group_barrier(0x100, 1, 0); }
;     __builtin_amdgcn_s_setprio(0);
; DI void phase8(const Params& p, const Sched& sched, unsigned char* smem) {
;     ...
;       u16* Ls = (u16*)(smem + 36864);
; #pragma unroll
;       for (int h2 = 0; h2 < 2; ++h2) {
;         const int fl = wf * 16 + lq * 4, fc = (2 * wf + h2) * 16 + lq * 4, F = tn * 64 + fc;
;         __syncthreads();
; #pragma unroll
;         for (int ni = 0; ni < 8; ++ni) *(f32x4*)(gl + (wt * 128 + ni * 16 + lr) * 36 + fl) = acc[2 * h2][ni];
;         __syncthreads();
;         const float4 w0 = *(const float4*)(p.conv_w + F), w1 = *(const float4*)(p.conv_w + FF + F), w2 = *(const float4*)(p.conv_w + 2 * FF + F), cb = *(const float4*)(p.conv_b + F);
; #pragma unroll
;         for (int ni = 0; ni < 8; ++ni) {
;           const int row = wt * 128 + ni * 16 + lr;
;           const f32x4 gv = acc[2 * h2][ni], uv = acc[2 * h2 + 1][ni];
;           if (row >= 2) {
;             const f32x4 g1 = *(const f32x4*)(gl + (row - 1) * 36 + fl), g2 = *(const f32x4*)(gl + (row - 2) * 36 + fl);
;             f32x4 o;
;             o[0] = cb.x + w0.x * g2[0] + w1.x * g1[0] + w2.x * gv[0];
;             o[1] = cb.y + w0.y * g2[1] + w1.y * g1[1] + w2.y * gv[1];
;             o[2] = cb.z + w0.z * g2[2] + w1.z * g1[2] + w2.z * gv[2];
;             o[3] = cb.w + w0.w * g2[3] + w1.w * g1[3] + w2.w * gv[3];
; #pragma unroll
;             for (int j = 0; j < 4; ++j) o[j] = o[j] * sigmoidf_(o[j]) * uv[j];
;             store4(Ls + row * 72 + fc, o);
;           } else {
;             *(f32x4*)(gside + ((size_t)tm * 4 + row) * FF + F) = gv;
	s_setprio 1
	ds_read_b128 v[0:3], v152 offset:36864
	ds_read_b128 v[228:231], v152 offset:38400
	ds_read_b128 v[232:235], v152 offset:39936
	ds_read_b128 v[236:239], v152 offset:41472
	ds_read_b128 v[16:19], v171 offset:49152
	ds_read_b128 v[20:23], v171 offset:50688
	s_waitcnt lgkmcnt(1)
	v_mfma_f32_16x16x32_bf16 v[140:143], v[0:3], v[16:19], v[148:151]
	v_mfma_f32_16x16x32_bf16 v[136:139], v[228:231], v[16:19], v[136:139]
	v_mfma_f32_16x16x32_bf16 v[60:63], v[232:235], v[16:19], v[112:115]
	v_mfma_f32_16x16x32_bf16 v[56:59], v[236:239], v[16:19], v[80:83]
	ds_read_b128 v[16:19], v171 offset:52224
	s_waitcnt lgkmcnt(1)
	v_mfma_f32_16x16x32_bf16 v[132:135], v[0:3], v[20:23], v[144:147]
	v_mfma_f32_16x16x32_bf16 v[128:131], v[228:231], v[20:23], v[128:131]
	v_mfma_f32_16x16x32_bf16 v[52:55], v[232:235], v[20:23], v[100:103]
	v_mfma_f32_16x16x32_bf16 v[48:51], v[236:239], v[20:23], v[188:191]
	ds_read_b128 v[20:23], v171 offset:53760
	s_waitcnt lgkmcnt(1)
	v_mfma_f32_16x16x32_bf16 v[124:127], v[0:3], v[16:19], v[192:195]
	v_mfma_f32_16x16x32_bf16 v[120:123], v[228:231], v[16:19], v[120:123]
	v_mfma_f32_16x16x32_bf16 v[44:47], v[232:235], v[16:19], v[88:91]
	v_mfma_f32_16x16x32_bf16 v[40:43], v[236:239], v[16:19], v[176:179]
	ds_read_b128 v[16:19], v171 offset:55296
	s_waitcnt lgkmcnt(1)
	v_mfma_f32_16x16x32_bf16 v[116:119], v[0:3], v[20:23], v[196:199]
	v_mfma_f32_16x16x32_bf16 v[112:115], v[228:231], v[20:23], v[108:111]
	v_mfma_f32_16x16x32_bf16 v[36:39], v[232:235], v[20:23], v[76:79]
	v_mfma_f32_16x16x32_bf16 v[32:35], v[236:239], v[20:23], v[200:203]
	ds_read_b128 v[64:67], v171 offset:56832
	s_waitcnt lgkmcnt(1)
	v_mfma_f32_16x16x32_bf16 v[108:111], v[0:3], v[16:19], v[204:207]
	v_mfma_f32_16x16x32_bf16 v[104:107], v[228:231], v[16:19], v[96:99]
	v_mfma_f32_16x16x32_bf16 v[28:31], v[232:235], v[16:19], v[68:71]
	v_mfma_f32_16x16x32_bf16 v[24:27], v[236:239], v[16:19], v[12:15]
	s_nop 1
	ds_read_b128 v[68:71], v171 offset:58368
	s_waitcnt lgkmcnt(1)
	v_mfma_f32_16x16x32_bf16 v[100:103], v[0:3], v[64:67], v[208:211]
	v_mfma_f32_16x16x32_bf16 v[96:99], v[228:231], v[64:67], v[84:87]
	v_mfma_f32_16x16x32_bf16 v[20:23], v[232:235], v[64:67], v[212:215]
	v_mfma_f32_16x16x32_bf16 v[16:19], v[236:239], v[64:67], v[8:11]
	ds_read_b128 v[76:79], v171 offset:59904
	s_waitcnt lgkmcnt(1)
	v_mfma_f32_16x16x32_bf16 v[92:95], v[0:3], v[68:71], v[220:223]
	v_mfma_f32_16x16x32_bf16 v[72:75], v[228:231], v[68:71], v[72:75]
	v_mfma_f32_16x16x32_bf16 v[12:15], v[232:235], v[68:71], v[224:227]
	v_mfma_f32_16x16x32_bf16 v[8:11], v[236:239], v[68:71], v[4:7]
	s_waitcnt lgkmcnt(0)
	v_mfma_f32_16x16x32_bf16 v[64:67], v[0:3], v[76:79], v[156:159]
	v_mfma_f32_16x16x32_bf16 v[68:71], v[228:231], v[76:79], v[172:175]
	v_mfma_f32_16x16x32_bf16 v[0:3], v[232:235], v[76:79], v[180:183]
	v_mfma_f32_16x16x32_bf16 v[4:7], v[236:239], v[76:79], v[184:187]
	s_setprio 0
	v_lshlrev_b32_e32 v76, 2, v168
	v_lshl_or_b32 v152, v155, 4, v76
	v_lshl_or_b32 v156, v155, 5, v76
	v_lshlrev_b32_e32 v76, 2, v152
	v_mad_u32_u24 v77, v154, s47, v160
	v_add_u32_e32 v159, v77, v76
	v_mad_u32_u24 v77, v154, s47, v161
	v_add_u32_e32 v168, v77, v76
	v_mad_u32_u24 v77, v154, s47, v162
	s_lshl_b32 s57, s56, 6
	v_add_u32_e32 v169, v77, v76
	v_mad_u32_u24 v77, v154, s47, v163
	v_add_u32_e32 v170, v77, v76
	v_mad_u32_u24 v77, v154, s47, v164
	v_add_u32_e32 v144, s57, v156
	v_add_u32_e32 v171, v77, v76
	v_mad_u32_u24 v77, v154, s47, v165
	v_ashrrev_i32_e32 v145, 31, v144
	v_add_u32_e32 v172, v77, v76
	v_mad_u32_u24 v77, v154, s47, v166
	v_lshlrev_b64 v[146:147], 2, v[144:145]
	v_mad_u32_u24 v158, v154, s47, v76
	v_add_u32_e32 v173, v77, v76
	v_lshl_add_u64 v[148:149], s[68:69], 0, v[146:147]
	v_lshl_add_u64 v[76:77], s[22:23], 0, v[146:147]
	v_lshl_add_u64 v[78:79], s[24:25], 0, v[146:147]
	v_lshl_add_u64 v[150:151], s[70:71], 0, v[146:147]
	global_load_dwordx4 v[84:87], v[148:149], off
	global_load_dwordx4 v[80:83], v[76:77], off
	global_load_dwordx4 v[88:91], v[150:151], off
	global_load_dwordx4 v[76:79], v[78:79], off
	s_barrier
	ds_write_b128 v158, v[140:143]
	ds_write_b128 v159, v[132:135]
	ds_write_b128 v168, v[124:127]
	ds_write_b128 v169, v[116:119]
	ds_write_b128 v170, v[108:111]
	ds_write_b128 v171, v[100:103]
	ds_write_b128 v172, v[92:95]
	ds_write_b128 v173, v[64:67]
	s_waitcnt lgkmcnt(0)
	s_barrier
	v_cmp_gt_u32_e64 s[4:5], 2, v154
	v_lshl_or_b32 v157, s30, 1, v154
	s_and_saveexec_b64 s[6:7], s[4:5]
	s_xor_b64 s[6:7], exec, s[6:7]
	s_cbranch_execz .LBB0_948
	s_ashr_i32 s31, s30, 31
	s_lshl_b64 s[34:35], s[30:31], 2
	v_or_b32_e32 v155, s34, v154
	v_mov_b64_e32 v[174:175], s[16:17]
	v_mad_u64_u32 v[174:175], s[58:59], v155, s48, v[174:175]
	v_mad_i32_i24 v175, s35, v167, v175
	v_lshl_add_u64 v[174:175], v[174:175], 0, v[146:147]
	global_store_dwordx4 v[174:175], v[140:143], off
	s_nop 1
	v_mov_b64_e32 v[140:141], s[10:11]
	v_mad_u64_u32 v[140:141], s[34:35], v157, s48, v[140:141]
	v_mad_i32_i24 v141, s31, v167, v141
	v_lshl_add_u64 v[140:141], v[140:141], 0, v[146:147]
	global_store_dwordx4 v[140:141], v[136:139], off

; DI int tidx() { int t = __builtin_amdgcn_workitem_id_x(); asm volatile("" : "+v"(t)); return t; }
;   DI unsigned rowoff(int r, int sch) const { const int g = r & 3, bc = r >> 2, b = bc / NCMP, c = bc - b * NCMP; return (unsigned)(b * Sn + c * 16) * 512u + g * 64 + sch; }
; template <int NI, class XL, class EP>
; DI void gemm_tile(const u16* __restrict__ W, int ldw, int f0, int t0, int K, XL xl, EP ep, unsigned char* smem) {
;     ...
;   const int tid = tidx(), lane = tid & 63, wave = tid >> 6;
;   const int wf = wave >> 1, wt = wave & 1, lr = lane & 15, lq = lane >> 4;
;   const int srow = tid >> 2, sch = (tid & 3) * 8;
;   f32x4 acc[4][NI];
; #pragma unroll
;   for (int i = 0; i < 4; ++i)
; #pragma unroll
;     for (int j = 0; j < NI; ++j) acc[i][j] = (f32x4){0.f, 0.f, 0.f, 0.f};
;   u32x4 wr[2], xr[XR];
;   const unsigned wbyte = ((unsigned)(f0 + srow * 2) * 32u + sch) * 2u;
;   const unsigned xbyte = xl.rowoff(t0 + srow * XR, sch) * 2u;
;   const int xrs = xl.rstride();
;   const int nk = K >> 5;
;   auto gload = [&](int it) {
;     const int k = it * 32;
;     const char* wb = (const char*)(W + (size_t)(k >> 5) * ldw * 32);
;     const char* xb = (const char*)xl.kbase(k);
; #pragma unroll
;     for (int i = 0; i < 2; ++i) wr[i] = *(const u32x4*)(wb + wbyte + i * 64);
; #pragma unroll
;     for (int i = 0; i < XR; ++i) xr[i] = *(const u32x4*)(xb + xbyte + i * xrs);
;   };
;   auto lstore = [&](int buf) {
;     u16* Ws = S0 + buf * BUF; u16* Xs = Ws + 128 * LST;
; #pragma unroll
;     for (int i = 0; i < 2; ++i) *(u32x4*)(Ws + (srow * 2 + i) * LST + sch) = wr[i];
; #pragma unroll
;     for (int i = 0; i < XR; ++i) *(u32x4*)(Xs + (srow * XR + i) * LST + sch) = xr[i];
;   };
;   gload(0);
;   __syncthreads();
;   lstore(0);
;   __syncthreads();
;   if (nk > 1) gload(1);
.Lp9_dyn_skip_a:
	v_mov_b32_e32 v46, v218
	s_and_b32 s30, s28, 7
	v_ashrrev_i32_e32 v47, 2, v46
	v_lshlrev_b32_e32 v0, 3, v46
	v_lshlrev_b32_e32 v49, 6, v47
	s_ashr_i32 s34, s28, 3
	v_and_b32_e32 v48, 24, v0
	v_lshl_add_u32 v0, s30, 12, v49
	s_add_i32 s31, s34, s26
	v_or_b32_e32 v0, v0, v48
	s_lshl_b32 s29, s31, 8
	v_lshlrev_b32_e32 v50, 1, v0
	v_and_b32_e32 v0, 0x3fffffc, v46
	v_add_u32_e32 v0, s29, v0
	v_lshlrev_b32_e32 v161, 1, v48
	v_lshl_or_b32 v51, v0, 6, v161
	global_load_dwordx4 v[16:19], v50, s[4:5]
	global_load_dwordx4 v[20:23], v50, s[4:5] offset:64
	global_load_dwordx4 v[24:27], v51, s[8:9]
	global_load_dwordx4 v[28:31], v51, s[8:9] offset:64
	global_load_dwordx4 v[32:35], v51, s[8:9] offset:128
	global_load_dwordx4 v[36:39], v51, s[8:9] offset:192
	v_mul_lo_u32 v166, v47, s20
	v_or_b32_e32 v162, v166, v161
	v_add_u32_e32 v163, v162, v166
	s_barrier
	v_bfe_u32 v158, v46, 4, 2
	v_and_b32_e32 v52, 15, v46
	v_ashrrev_i32_e32 v53, 1, v46
	v_lshlrev_b32_e32 v54, 1, v46
	v_lshlrev_b32_e32 v46, 6, v46
	s_and_b32 s35, s27, 7
	s_add_i32 s34, s18, s34
	v_and_b32_e32 v46, 0xffffff00, v46
	v_and_b32_e32 v160, 0xffffffc0, v53
	v_lshl_add_u32 v46, s34, 14, v46
	v_lshl_add_u32 v49, s35, 12, v49
	v_mov_b32_e32 v0, 0
	v_and_or_b32 v159, v54, s21, v52
	v_or_b32_e32 v47, v160, v52
	v_or_b32_e32 v152, v46, v161
	v_or_b32_e32 v46, v49, v48
	s_mov_b32 s33, 1
	v_mov_b32_e32 v155, v153
	v_mov_b32_e32 v1, v0
	v_mov_b32_e32 v2, v0
	v_mov_b32_e32 v3, v0
	v_mov_b32_e32 v4, v0
	v_mov_b32_e32 v5, v0
	v_mov_b32_e32 v6, v0
	v_mov_b32_e32 v7, v0
	v_mov_b32_e32 v8, v0
	v_mov_b32_e32 v9, v0
	v_mov_b32_e32 v10, v0
	v_mov_b32_e32 v11, v0
	v_mov_b32_e32 v12, v0
	v_mov_b32_e32 v13, v0
	v_mov_b32_e32 v14, v0
	v_mov_b32_e32 v15, v0
	v_mov_b32_e32 v40, v0
	v_mov_b32_e32 v41, v0
	v_mov_b32_e32 v42, v0
	v_mov_b32_e32 v43, v0
	v_mov_b32_e32 v44, v0
	v_mov_b32_e32 v45, v0
	v_lshlrev_b32_e32 v164, 4, v158
	v_mul_u32_u24_e32 v165, 48, v159
	v_mul_lo_u32 v167, v47, 48
	v_lshlrev_b32_e32 v154, 1, v46
	v_mov_b64_e32 v[156:157], v[152:153]
	v_mov_b32_e32 v46, v0
	v_mov_b32_e32 v47, v0
	v_mov_b32_e32 v68, v0
	v_mov_b32_e32 v69, v0
	v_mov_b32_e32 v70, v0
	v_mov_b32_e32 v71, v0
	v_mov_b32_e32 v80, v0
	v_mov_b32_e32 v81, v0
	v_mov_b32_e32 v82, v0
	v_mov_b32_e32 v83, v0
	v_mov_b32_e32 v48, v0
	v_mov_b32_e32 v49, v0
	v_mov_b32_e32 v52, v0
	v_mov_b32_e32 v53, v0
	v_mov_b32_e32 v54, v0
	v_mov_b32_e32 v55, v0
	v_mov_b32_e32 v56, v0
	v_mov_b32_e32 v57, v0
	v_mov_b32_e32 v58, v0
	s_waitcnt vmcnt(5)
	ds_write_b128 v162, v[16:19]
	s_waitcnt vmcnt(4)
	ds_write_b128 v162, v[20:23] offset:96
	s_waitcnt vmcnt(3)
	ds_write_b128 v163, v[24:27] offset:12288
	s_waitcnt vmcnt(2)
	ds_write_b128 v163, v[28:31] offset:12384
	s_waitcnt vmcnt(1)
	ds_write_b128 v163, v[32:35] offset:12480
	s_waitcnt vmcnt(0)
	ds_write_b128 v163, v[36:39] offset:12576
	s_waitcnt lgkmcnt(0)
	global_load_dwordx4 v[20:23], v50, s[10:11]
	global_load_dwordx4 v[16:19], v50, s[10:11] offset:64
	global_load_dwordx4 v[36:39], v51, s[6:7]
	global_load_dwordx4 v[32:35], v51, s[6:7] offset:64
	global_load_dwordx4 v[28:31], v51, s[6:7] offset:128
	global_load_dwordx4 v[24:27], v51, s[6:7] offset:192
	s_add_u32 s98, s42, s22
	s_addc_u32 s99, s43, 0
	s_add_u32 s100, s42, s23
	s_addc_u32 s101, s43, 0
	global_load_dwordx4 v[200:203], v154, s[98:99]
	global_load_dwordx4 v[204:207], v154, s[98:99] offset:64
	global_load_dwordx4 v[208:211], v156, s[100:101] offset:2048
	global_load_dwordx4 v[212:215], v156, s[100:101] offset:2112
	global_load_dwordx4 v[220:223], v156, s[100:101] offset:2176
	global_load_dwordx4 v[224:227], v156, s[100:101] offset:2240
	s_add_u32 s98, s98, s16
	s_addc_u32 s99, s99, s17
	s_add_u32 s100, s100, s14
	s_addc_u32 s101, s101, s15
	v_mov_b32_e32 v50, v0
	v_mov_b32_e32 v51, v0
	v_mov_b32_e32 v59, v0
	v_mov_b32_e32 v64, v0
	v_mov_b32_e32 v65, v0
	v_mov_b32_e32 v66, v0
	v_mov_b32_e32 v67, v0
	v_mov_b32_e32 v76, v0
	v_mov_b32_e32 v77, v0
	v_mov_b32_e32 v78, v0
	v_mov_b32_e32 v79, v0
	v_mov_b32_e32 v88, v0
	v_mov_b32_e32 v89, v0
	v_mov_b32_e32 v90, v0
	v_mov_b32_e32 v91, v0
	v_mov_b32_e32 v100, v0
	v_mov_b32_e32 v101, v0
	v_mov_b32_e32 v102, v0
	v_mov_b32_e32 v103, v0
	v_mov_b32_e32 v112, v0
	v_mov_b32_e32 v113, v0
	v_mov_b32_e32 v114, v0
	v_mov_b32_e32 v115, v0
	v_mov_b32_e32 v60, v0
	v_mov_b32_e32 v61, v0
	v_mov_b32_e32 v62, v0
	v_mov_b32_e32 v63, v0
	v_mov_b32_e32 v72, v0
	v_mov_b32_e32 v73, v0
	v_mov_b32_e32 v74, v0
	v_mov_b32_e32 v75, v0
	v_mov_b32_e32 v84, v0
	v_mov_b32_e32 v85, v0
	v_mov_b32_e32 v86, v0
	v_mov_b32_e32 v87, v0
	v_mov_b32_e32 v96, v0
	v_mov_b32_e32 v97, v0
	v_mov_b32_e32 v98, v0
	v_mov_b32_e32 v99, v0
	v_mov_b32_e32 v108, v0
	v_mov_b32_e32 v109, v0
	v_mov_b32_e32 v110, v0
	v_mov_b32_e32 v111, v0
	v_mov_b32_e32 v120, v0
	v_mov_b32_e32 v121, v0
	v_mov_b32_e32 v122, v0
	v_mov_b32_e32 v123, v0
	v_mov_b32_e32 v128, v0
	v_mov_b32_e32 v129, v0
	v_mov_b32_e32 v130, v0
	v_mov_b32_e32 v131, v0
	v_mov_b32_e32 v136, v0
	v_mov_b32_e32 v137, v0
	v_mov_b32_e32 v138, v0
	v_mov_b32_e32 v139, v0
	v_mov_b32_e32 v92, v0
	v_mov_b32_e32 v93, v0
	v_mov_b32_e32 v94, v0
	v_mov_b32_e32 v95, v0
	v_mov_b32_e32 v104, v0
	v_mov_b32_e32 v105, v0
	v_mov_b32_e32 v106, v0
	v_mov_b32_e32 v107, v0
	v_mov_b32_e32 v116, v0
	v_mov_b32_e32 v117, v0
	v_mov_b32_e32 v118, v0
	v_mov_b32_e32 v119, v0
	v_mov_b32_e32 v124, v0
	v_mov_b32_e32 v125, v0
	v_mov_b32_e32 v126, v0
	v_mov_b32_e32 v127, v0
	v_mov_b32_e32 v132, v0
	v_mov_b32_e32 v133, v0
	v_mov_b32_e32 v134, v0
	v_mov_b32_e32 v135, v0
	v_mov_b32_e32 v140, v0
	v_mov_b32_e32 v141, v0
	v_mov_b32_e32 v142, v0
	v_mov_b32_e32 v143, v0
	v_mov_b32_e32 v144, v0
	v_mov_b32_e32 v145, v0
	v_mov_b32_e32 v146, v0
	v_mov_b32_e32 v147, v0
	v_mov_b32_e32 v148, v0
	v_mov_b32_e32 v149, v0
	v_mov_b32_e32 v150, v0
	v_mov_b32_e32 v151, v0
	v_lshl_add_u32 v228, v167, 1, v164
	v_lshl_add_u32 v152, v165, 1, v164
	v_add_u32_e32 v229, v166, v161
	v_add_u32_e32 v230, v229, v166
; DI f32x4 mfma16(bf16x8 a, bf16x8 b, f32x4 c) { return __builtin_amdgcn_mfma_f32_16x16x32_bf16(a, b, c, 0, 0, 0); }
; template <int NI, class XL, class EP>
; DI void gemm_tile(const u16* __restrict__ W, int ldw, int f0, int t0, int K, XL xl, EP ep, unsigned char* smem) {
;     ...
;   for (int it = 0; it < nk; ++it) {
;     const u16* Ws = S0 + (it & 1) * BUF; const u16* Xs = Ws + 128 * LST;
;     __builtin_amdgcn_s_setprio(1);
;     bf16x8 a[4];
; #pragma unroll
;     for (int mi = 0; mi < 4; ++mi) a[mi] = *(const bf16x8*)(Ws + (wf * 64 + mi * 16 + lr) * LST + lq * 8);
; #pragma unroll
;     for (int ni = 0; ni < NI; ++ni) {
;       const bf16x8 b = *(const bf16x8*)(Xs + (wt * (NI * 16) + ni * 16 + lr) * LST + lq * 8);
; #pragma unroll
;       for (int mi = 0; mi < 4; ++mi) acc[mi][ni] = mfma16(a[mi], b, acc[mi][ni]);
;     }
;     __builtin_amdgcn_sched_group_barrier(0x100, 6, 0);
; #pragma unroll
;     for (int ni = 0; ni < NI; ++ni) { __builtin_amdgcn_sched_group_barrier(0x008, 4, 0); if (ni + 2 < NI) __builtin_amdgcn_sched_group_barrier(0x100, 1, 0); }
;     __builtin_amdgcn_s_setprio(0);
;     if (it + 1 < nk) lstore((it + 1) & 1);
;     if (it + 2 < nk) gload(it + 2);
;     __syncthreads();
.LBB0_1095:
	s_barrier
	s_setprio 1
	ds_read_b128 v[168:171], v228 offset:0
	ds_read_b128 v[172:175], v228 offset:1536
	ds_read_b128 v[180:183], v228 offset:3072
	ds_read_b128 v[184:187], v228 offset:4608
	ds_read_b128 v[176:179], v152 offset:12288
	ds_read_b128 v[188:191], v152 offset:13824
	s_waitcnt lgkmcnt(1)
	v_mfma_f32_16x16x32_bf16 v[148:151], v[168:171], v[176:179], v[148:151]
	v_mfma_f32_16x16x32_bf16 v[136:139], v[172:175], v[176:179], v[136:139]
	v_mfma_f32_16x16x32_bf16 v[112:115], v[180:183], v[176:179], v[112:115]
	v_mfma_f32_16x16x32_bf16 v[80:83], v[184:187], v[176:179], v[80:83]
	ds_read_b128 v[176:179], v152 offset:15360
	s_waitcnt vmcnt(6)
	ds_write_b128 v229, v[20:23] offset:36864
	s_waitcnt lgkmcnt(2)
	v_mfma_f32_16x16x32_bf16 v[144:147], v[168:171], v[188:191], v[144:147]
	v_mfma_f32_16x16x32_bf16 v[128:131], v[172:175], v[188:191], v[128:131]
	v_mfma_f32_16x16x32_bf16 v[100:103], v[180:183], v[188:191], v[100:103]
	v_mfma_f32_16x16x32_bf16 v[68:71], v[184:187], v[188:191], v[68:71]
	ds_read_b128 v[188:191], v152 offset:16896
	ds_write_b128 v229, v[16:19] offset:36960
	global_load_dwordx4 v[20:23], v154, s[98:99]
	global_load_dwordx4 v[16:19], v154, s[98:99] offset:64
	s_waitcnt lgkmcnt(3)
	v_mfma_f32_16x16x32_bf16 v[140:143], v[168:171], v[176:179], v[140:143]
	v_mfma_f32_16x16x32_bf16 v[120:123], v[172:175], v[176:179], v[120:123]
	v_mfma_f32_16x16x32_bf16 v[88:91], v[180:183], v[176:179], v[88:91]
	v_mfma_f32_16x16x32_bf16 v[44:47], v[184:187], v[176:179], v[44:47]
	ds_read_b128 v[176:179], v152 offset:18432
	ds_write_b128 v230, v[36:39] offset:49152
	global_load_dwordx4 v[36:39], v156, s[100:101] offset:2048
	s_waitcnt lgkmcnt(3)
	v_mfma_f32_16x16x32_bf16 v[132:135], v[168:171], v[188:191], v[132:135]
	v_mfma_f32_16x16x32_bf16 v[108:111], v[172:175], v[188:191], v[108:111]
	v_mfma_f32_16x16x32_bf16 v[76:79], v[180:183], v[188:191], v[76:79]
	v_mfma_f32_16x16x32_bf16 v[40:43], v[184:187], v[188:191], v[40:43]
	ds_read_b128 v[188:191], v152 offset:19968
	ds_write_b128 v230, v[32:35] offset:49248
	global_load_dwordx4 v[32:35], v156, s[100:101] offset:2112
	s_waitcnt lgkmcnt(3)
	v_mfma_f32_16x16x32_bf16 v[124:127], v[168:171], v[176:179], v[124:127]
	v_mfma_f32_16x16x32_bf16 v[96:99], v[172:175], v[176:179], v[96:99]
	v_mfma_f32_16x16x32_bf16 v[64:67], v[180:183], v[176:179], v[64:67]
	v_mfma_f32_16x16x32_bf16 v[12:15], v[184:187], v[176:179], v[12:15]
	ds_read_b128 v[176:179], v152 offset:21504
	ds_write_b128 v230, v[28:31] offset:49344
	global_load_dwordx4 v[28:31], v156, s[100:101] offset:2176
	s_waitcnt lgkmcnt(3)
	v_mfma_f32_16x16x32_bf16 v[116:119], v[168:171], v[188:191], v[116:119]
	v_mfma_f32_16x16x32_bf16 v[84:87], v[172:175], v[188:191], v[84:87]
	v_mfma_f32_16x16x32_bf16 v[56:59], v[180:183], v[188:191], v[56:59]
	v_mfma_f32_16x16x32_bf16 v[8:11], v[184:187], v[188:191], v[8:11]
	ds_read_b128 v[188:191], v152 offset:23040
	ds_write_b128 v230, v[24:27] offset:49440
	global_load_dwordx4 v[24:27], v156, s[100:101] offset:2240
	s_waitcnt lgkmcnt(3)
	v_mfma_f32_16x16x32_bf16 v[104:107], v[168:171], v[176:179], v[104:107]
	v_mfma_f32_16x16x32_bf16 v[72:75], v[172:175], v[176:179], v[72:75]
	v_mfma_f32_16x16x32_bf16 v[52:55], v[180:183], v[176:179], v[52:55]
	v_mfma_f32_16x16x32_bf16 v[4:7], v[184:187], v[176:179], v[4:7]
	s_add_u32 s98, s98, s16
	s_addc_u32 s99, s99, s17
	s_add_u32 s100, s100, s14
	s_addc_u32 s101, s101, s15
	s_waitcnt lgkmcnt(1)
	v_mfma_f32_16x16x32_bf16 v[92:95], v[168:171], v[188:191], v[92:95]
	v_mfma_f32_16x16x32_bf16 v[60:63], v[172:175], v[188:191], v[60:63]
	v_mfma_f32_16x16x32_bf16 v[48:51], v[180:183], v[188:191], v[48:51]
	v_mfma_f32_16x16x32_bf16 v[0:3], v[184:187], v[188:191], v[0:3]
	s_setprio 0
	s_waitcnt lgkmcnt(0)
	s_barrier
	s_setprio 1
	ds_read_b128 v[168:171], v228 offset:36864
	ds_read_b128 v[172:175], v228 offset:38400
	ds_read_b128 v[180:183], v228 offset:39936
	ds_read_b128 v[184:187], v228 offset:41472
	ds_read_b128 v[176:179], v152 offset:49152
	ds_read_b128 v[188:191], v152 offset:50688
	s_waitcnt lgkmcnt(1)
	v_mfma_f32_16x16x32_bf16 v[148:151], v[168:171], v[176:179], v[148:151]
	v_mfma_f32_16x16x32_bf16 v[136:139], v[172:175], v[176:179], v[136:139]
	v_mfma_f32_16x16x32_bf16 v[112:115], v[180:183], v[176:179], v[112:115]
	v_mfma_f32_16x16x32_bf16 v[80:83], v[184:187], v[176:179], v[80:83]
	ds_read_b128 v[176:179], v152 offset:52224
	s_waitcnt vmcnt(6)
	ds_write_b128 v229, v[200:203] offset:0
	s_waitcnt lgkmcnt(2)
	v_mfma_f32_16x16x32_bf16 v[144:147], v[168:171], v[188:191], v[144:147]
	v_mfma_f32_16x16x32_bf16 v[128:131], v[172:175], v[188:191], v[128:131]
	v_mfma_f32_16x16x32_bf16 v[100:103], v[180:183], v[188:191], v[100:103]
	v_mfma_f32_16x16x32_bf16 v[68:71], v[184:187], v[188:191], v[68:71]
	ds_read_b128 v[188:191], v152 offset:53760
	ds_write_b128 v229, v[204:207] offset:96
	global_load_dwordx4 v[200:203], v154, s[98:99]
	global_load_dwordx4 v[204:207], v154, s[98:99] offset:64
	s_waitcnt lgkmcnt(3)
	v_mfma_f32_16x16x32_bf16 v[140:143], v[168:171], v[176:179], v[140:143]
	v_mfma_f32_16x16x32_bf16 v[120:123], v[172:175], v[176:179], v[120:123]
	v_mfma_f32_16x16x32_bf16 v[88:91], v[180:183], v[176:179], v[88:91]
	v_mfma_f32_16x16x32_bf16 v[44:47], v[184:187], v[176:179], v[44:47]
	ds_read_b128 v[176:179], v152 offset:55296
	ds_write_b128 v230, v[208:211] offset:12288
	global_load_dwordx4 v[208:211], v156, s[100:101] offset:2048
	s_waitcnt lgkmcnt(3)
; DI f32x4 mfma16(bf16x8 a, bf16x8 b, f32x4 c) { return __builtin_amdgcn_mfma_f32_16x16x32_bf16(a, b, c, 0, 0, 0); }
; template <int NI, class XL, class EP>
; DI void gemm_tile(const u16* __restrict__ W, int ldw, int f0, int t0, int K, XL xl, EP ep, unsigned char* smem) {
;     ...
;   for (int it = 0; it < nk; ++it) {
;     const u16* Ws = S0 + (it & 1) * BUF; const u16* Xs = Ws + 128 * LST;
;     __builtin_amdgcn_s_setprio(1);
;     bf16x8 a[4];
; #pragma unroll
;     for (int mi = 0; mi < 4; ++mi) a[mi] = *(const bf16x8*)(Ws + (wf * 64 + mi * 16 + lr) * LST + lq * 8);
; #pragma unroll
;     for (int ni = 0; ni < NI; ++ni) {
;       const bf16x8 b = *(const bf16x8*)(Xs + (wt * (NI * 16) + ni * 16 + lr) * LST + lq * 8);
; #pragma unroll
;       for (int mi = 0; mi < 4; ++mi) acc[mi][ni] = mfma16(a[mi], b, acc[mi][ni]);
;     }
;     __builtin_amdgcn_sched_group_barrier(0x100, 6, 0);
; #pragma unroll
;     for (int ni = 0; ni < NI; ++ni) { __builtin_amdgcn_sched_group_barrier(0x008, 4, 0); if (ni + 2 < NI) __builtin_amdgcn_sched_group_barrier(0x100, 1, 0); }
;     __builtin_amdgcn_s_setprio(0);
;     if (it + 1 < nk) lstore((it + 1) & 1);
;     if (it + 2 < nk) gload(it + 2);
;     __syncthreads();
	v_mfma_f32_16x16x32_bf16 v[132:135], v[168:171], v[188:191], v[132:135]
	v_mfma_f32_16x16x32_bf16 v[108:111], v[172:175], v[188:191], v[108:111]
	v_mfma_f32_16x16x32_bf16 v[76:79], v[180:183], v[188:191], v[76:79]
	v_mfma_f32_16x16x32_bf16 v[40:43], v[184:187], v[188:191], v[40:43]
	ds_read_b128 v[188:191], v152 offset:56832
	ds_write_b128 v230, v[212:215] offset:12384
	global_load_dwordx4 v[212:215], v156, s[100:101] offset:2112
	s_waitcnt lgkmcnt(3)
	v_mfma_f32_16x16x32_bf16 v[124:127], v[168:171], v[176:179], v[124:127]
	v_mfma_f32_16x16x32_bf16 v[96:99], v[172:175], v[176:179], v[96:99]
	v_mfma_f32_16x16x32_bf16 v[64:67], v[180:183], v[176:179], v[64:67]
	v_mfma_f32_16x16x32_bf16 v[12:15], v[184:187], v[176:179], v[12:15]
	ds_read_b128 v[176:179], v152 offset:58368
	ds_write_b128 v230, v[220:223] offset:12480
	global_load_dwordx4 v[220:223], v156, s[100:101] offset:2176
	s_waitcnt lgkmcnt(3)
	v_mfma_f32_16x16x32_bf16 v[116:119], v[168:171], v[188:191], v[116:119]
	v_mfma_f32_16x16x32_bf16 v[84:87], v[172:175], v[188:191], v[84:87]
	v_mfma_f32_16x16x32_bf16 v[56:59], v[180:183], v[188:191], v[56:59]
	v_mfma_f32_16x16x32_bf16 v[8:11], v[184:187], v[188:191], v[8:11]
	ds_read_b128 v[188:191], v152 offset:59904
	ds_write_b128 v230, v[224:227] offset:12576
	global_load_dwordx4 v[224:227], v156, s[100:101] offset:2240
	s_waitcnt lgkmcnt(3)
	v_mfma_f32_16x16x32_bf16 v[104:107], v[168:171], v[176:179], v[104:107]
	v_mfma_f32_16x16x32_bf16 v[72:75], v[172:175], v[176:179], v[72:75]
	v_mfma_f32_16x16x32_bf16 v[52:55], v[180:183], v[176:179], v[52:55]
	v_mfma_f32_16x16x32_bf16 v[4:7], v[184:187], v[176:179], v[4:7]
	s_add_u32 s98, s98, s16
	s_addc_u32 s99, s99, s17
	s_add_u32 s100, s100, s14
	s_addc_u32 s101, s101, s15
	s_add_i32 s33, s33, 2
	s_waitcnt lgkmcnt(1)
	v_mfma_f32_16x16x32_bf16 v[92:95], v[168:171], v[188:191], v[92:95]
	v_mfma_f32_16x16x32_bf16 v[60:63], v[172:175], v[188:191], v[60:63]
	v_mfma_f32_16x16x32_bf16 v[48:51], v[180:183], v[188:191], v[48:51]
	v_mfma_f32_16x16x32_bf16 v[0:3], v[184:187], v[188:191], v[0:3]
	s_setprio 0
	s_cmpk_lg_i32 s33, 85
	s_waitcnt lgkmcnt(0)
	s_cbranch_scc1 .LBB0_1095
	s_barrier
	s_setprio 1
	ds_read_b128 v[168:171], v228 offset:0
	ds_read_b128 v[172:175], v228 offset:1536
	ds_read_b128 v[180:183], v228 offset:3072
	ds_read_b128 v[184:187], v228 offset:4608
	ds_read_b128 v[176:179], v152 offset:12288
	ds_read_b128 v[188:191], v152 offset:13824
	s_waitcnt lgkmcnt(1)
	v_mfma_f32_16x16x32_bf16 v[148:151], v[168:171], v[176:179], v[148:151]
	v_mfma_f32_16x16x32_bf16 v[136:139], v[172:175], v[176:179], v[136:139]
	v_mfma_f32_16x16x32_bf16 v[112:115], v[180:183], v[176:179], v[112:115]
	v_mfma_f32_16x16x32_bf16 v[80:83], v[184:187], v[176:179], v[80:83]
	ds_read_b128 v[176:179], v152 offset:15360
	s_waitcnt vmcnt(6)
	ds_write_b128 v229, v[20:23] offset:36864
	s_waitcnt lgkmcnt(2)
	v_mfma_f32_16x16x32_bf16 v[144:147], v[168:171], v[188:191], v[144:147]
	v_mfma_f32_16x16x32_bf16 v[128:131], v[172:175], v[188:191], v[128:131]
	v_mfma_f32_16x16x32_bf16 v[100:103], v[180:183], v[188:191], v[100:103]
	v_mfma_f32_16x16x32_bf16 v[68:71], v[184:187], v[188:191], v[68:71]
	ds_read_b128 v[188:191], v152 offset:16896
	ds_write_b128 v229, v[16:19] offset:36960
	global_load_dwordx4 v[20:23], v154, s[98:99]
	global_load_dwordx4 v[16:19], v154, s[98:99] offset:64
	s_waitcnt lgkmcnt(3)
	v_mfma_f32_16x16x32_bf16 v[140:143], v[168:171], v[176:179], v[140:143]
	v_mfma_f32_16x16x32_bf16 v[120:123], v[172:175], v[176:179], v[120:123]
	v_mfma_f32_16x16x32_bf16 v[88:91], v[180:183], v[176:179], v[88:91]
	v_mfma_f32_16x16x32_bf16 v[44:47], v[184:187], v[176:179], v[44:47]
	ds_read_b128 v[176:179], v152 offset:18432
	ds_write_b128 v230, v[36:39] offset:49152
	global_load_dwordx4 v[36:39], v156, s[100:101] offset:2048
	s_waitcnt lgkmcnt(3)
	v_mfma_f32_16x16x32_bf16 v[132:135], v[168:171], v[188:191], v[132:135]
	v_mfma_f32_16x16x32_bf16 v[108:111], v[172:175], v[188:191], v[108:111]
	v_mfma_f32_16x16x32_bf16 v[76:79], v[180:183], v[188:191], v[76:79]
	v_mfma_f32_16x16x32_bf16 v[40:43], v[184:187], v[188:191], v[40:43]
	ds_read_b128 v[188:191], v152 offset:19968
	ds_write_b128 v230, v[32:35] offset:49248
	global_load_dwordx4 v[32:35], v156, s[100:101] offset:2112
	s_waitcnt lgkmcnt(3)
	v_mfma_f32_16x16x32_bf16 v[124:127], v[168:171], v[176:179], v[124:127]
	v_mfma_f32_16x16x32_bf16 v[96:99], v[172:175], v[176:179], v[96:99]
	v_mfma_f32_16x16x32_bf16 v[64:67], v[180:183], v[176:179], v[64:67]
	v_mfma_f32_16x16x32_bf16 v[12:15], v[184:187], v[176:179], v[12:15]
	ds_read_b128 v[176:179], v152 offset:21504
	ds_write_b128 v230, v[28:31] offset:49344
	global_load_dwordx4 v[28:31], v156, s[100:101] offset:2176
	s_waitcnt lgkmcnt(3)
	v_mfma_f32_16x16x32_bf16 v[116:119], v[168:171], v[188:191], v[116:119]
	v_mfma_f32_16x16x32_bf16 v[84:87], v[172:175], v[188:191], v[84:87]
	v_mfma_f32_16x16x32_bf16 v[56:59], v[180:183], v[188:191], v[56:59]
	v_mfma_f32_16x16x32_bf16 v[8:11], v[184:187], v[188:191], v[8:11]
	ds_read_b128 v[188:191], v152 offset:23040
	ds_write_b128 v230, v[24:27] offset:49440
	global_load_dwordx4 v[24:27], v156, s[100:101] offset:2240
	s_waitcnt lgkmcnt(3)
	v_mfma_f32_16x16x32_bf16 v[104:107], v[168:171], v[176:179], v[104:107]
	v_mfma_f32_16x16x32_bf16 v[72:75], v[172:175], v[176:179], v[72:75]
	v_mfma_f32_16x16x32_bf16 v[52:55], v[180:183], v[176:179], v[52:55]
	v_mfma_f32_16x16x32_bf16 v[4:7], v[184:187], v[176:179], v[4:7]
	s_add_u32 s98, s98, s16
	s_addc_u32 s99, s99, s17
	s_add_u32 s100, s100, s14
	s_addc_u32 s101, s101, s15
	s_waitcnt lgkmcnt(1)
	v_mfma_f32_16x16x32_bf16 v[92:95], v[168:171], v[188:191], v[92:95]
	v_mfma_f32_16x16x32_bf16 v[60:63], v[172:175], v[188:191], v[60:63]
	v_mfma_f32_16x16x32_bf16 v[48:51], v[180:183], v[188:191], v[48:51]
	v_mfma_f32_16x16x32_bf16 v[0:3], v[184:187], v[188:191], v[0:3]
	s_setprio 0
	s_waitcnt lgkmcnt(0)
	s_barrier
; DI f32x4 mfma16(bf16x8 a, bf16x8 b, f32x4 c) { return __builtin_amdgcn_mfma_f32_16x16x32_bf16(a, b, c, 0, 0, 0); }
; template <int NI, class XL, class EP>
; DI void gemm_tile(const u16* __restrict__ W, int ldw, int f0, int t0, int K, XL xl, EP ep, unsigned char* smem) {
;     ...
;   for (int it = 0; it < nk; ++it) {
;     const u16* Ws = S0 + (it & 1) * BUF; const u16* Xs = Ws + 128 * LST;
;     __builtin_amdgcn_s_setprio(1);
;     bf16x8 a[4];
; #pragma unroll
;     for (int mi = 0; mi < 4; ++mi) a[mi] = *(const bf16x8*)(Ws + (wf * 64 + mi * 16 + lr) * LST + lq * 8);
; #pragma unroll
;     for (int ni = 0; ni < NI; ++ni) {
;       const bf16x8 b = *(const bf16x8*)(Xs + (wt * (NI * 16) + ni * 16 + lr) * LST + lq * 8);
; #pragma unroll
;       for (int mi = 0; mi < 4; ++mi) acc[mi][ni] = mfma16(a[mi], b, acc[mi][ni]);
;     }
;     __builtin_amdgcn_sched_group_barrier(0x100, 6, 0);
; #pragma unroll
;     for (int ni = 0; ni < NI; ++ni) { __builtin_amdgcn_sched_group_barrier(0x008, 4, 0); if (ni + 2 < NI) __builtin_amdgcn_sched_group_barrier(0x100, 1, 0); }
;     __builtin_amdgcn_s_setprio(0);
;     if (it + 1 < nk) lstore((it + 1) & 1);
;     if (it + 2 < nk) gload(it + 2);
;     __syncthreads();
	s_setprio 1
	ds_read_b128 v[168:171], v228 offset:36864
	ds_read_b128 v[172:175], v228 offset:38400
	ds_read_b128 v[180:183], v228 offset:39936
	ds_read_b128 v[184:187], v228 offset:41472
	ds_read_b128 v[176:179], v152 offset:49152
	ds_read_b128 v[188:191], v152 offset:50688
	s_waitcnt lgkmcnt(1)
	v_mfma_f32_16x16x32_bf16 v[148:151], v[168:171], v[176:179], v[148:151]
	v_mfma_f32_16x16x32_bf16 v[136:139], v[172:175], v[176:179], v[136:139]
	v_mfma_f32_16x16x32_bf16 v[112:115], v[180:183], v[176:179], v[112:115]
	v_mfma_f32_16x16x32_bf16 v[80:83], v[184:187], v[176:179], v[80:83]
	ds_read_b128 v[176:179], v152 offset:52224
	s_waitcnt vmcnt(6)
	ds_write_b128 v229, v[200:203] offset:0
	s_waitcnt lgkmcnt(2)
	v_mfma_f32_16x16x32_bf16 v[144:147], v[168:171], v[188:191], v[144:147]
	v_mfma_f32_16x16x32_bf16 v[128:131], v[172:175], v[188:191], v[128:131]
	v_mfma_f32_16x16x32_bf16 v[100:103], v[180:183], v[188:191], v[100:103]
	v_mfma_f32_16x16x32_bf16 v[68:71], v[184:187], v[188:191], v[68:71]
	ds_read_b128 v[188:191], v152 offset:53760
	ds_write_b128 v229, v[204:207] offset:96
	s_waitcnt lgkmcnt(3)
	v_mfma_f32_16x16x32_bf16 v[140:143], v[168:171], v[176:179], v[140:143]
	v_mfma_f32_16x16x32_bf16 v[120:123], v[172:175], v[176:179], v[120:123]
	v_mfma_f32_16x16x32_bf16 v[88:91], v[180:183], v[176:179], v[88:91]
	v_mfma_f32_16x16x32_bf16 v[44:47], v[184:187], v[176:179], v[44:47]
	ds_read_b128 v[176:179], v152 offset:55296
	ds_write_b128 v230, v[208:211] offset:12288
	s_waitcnt lgkmcnt(3)
	v_mfma_f32_16x16x32_bf16 v[132:135], v[168:171], v[188:191], v[132:135]
	v_mfma_f32_16x16x32_bf16 v[108:111], v[172:175], v[188:191], v[108:111]
	v_mfma_f32_16x16x32_bf16 v[76:79], v[180:183], v[188:191], v[76:79]
	v_mfma_f32_16x16x32_bf16 v[40:43], v[184:187], v[188:191], v[40:43]
	ds_read_b128 v[188:191], v152 offset:56832
	ds_write_b128 v230, v[212:215] offset:12384
	s_waitcnt lgkmcnt(3)
	v_mfma_f32_16x16x32_bf16 v[124:127], v[168:171], v[176:179], v[124:127]
	v_mfma_f32_16x16x32_bf16 v[96:99], v[172:175], v[176:179], v[96:99]
	v_mfma_f32_16x16x32_bf16 v[64:67], v[180:183], v[176:179], v[64:67]
	v_mfma_f32_16x16x32_bf16 v[12:15], v[184:187], v[176:179], v[12:15]
	ds_read_b128 v[176:179], v152 offset:58368
	ds_write_b128 v230, v[220:223] offset:12480
	s_waitcnt lgkmcnt(3)
	v_mfma_f32_16x16x32_bf16 v[116:119], v[168:171], v[188:191], v[116:119]
	v_mfma_f32_16x16x32_bf16 v[84:87], v[172:175], v[188:191], v[84:87]
	v_mfma_f32_16x16x32_bf16 v[56:59], v[180:183], v[188:191], v[56:59]
	v_mfma_f32_16x16x32_bf16 v[8:11], v[184:187], v[188:191], v[8:11]
	ds_read_b128 v[188:191], v152 offset:59904
	ds_write_b128 v230, v[224:227] offset:12576
	s_waitcnt lgkmcnt(3)
	v_mfma_f32_16x16x32_bf16 v[104:107], v[168:171], v[176:179], v[104:107]
	v_mfma_f32_16x16x32_bf16 v[72:75], v[172:175], v[176:179], v[72:75]
	v_mfma_f32_16x16x32_bf16 v[52:55], v[180:183], v[176:179], v[52:55]
	v_mfma_f32_16x16x32_bf16 v[4:7], v[184:187], v[176:179], v[4:7]
	s_add_i32 s33, s33, 2
	s_waitcnt lgkmcnt(1)
	v_mfma_f32_16x16x32_bf16 v[92:95], v[168:171], v[188:191], v[92:95]
	v_mfma_f32_16x16x32_bf16 v[60:63], v[172:175], v[188:191], v[60:63]
	v_mfma_f32_16x16x32_bf16 v[48:51], v[180:183], v[188:191], v[48:51]
	v_mfma_f32_16x16x32_bf16 v[0:3], v[184:187], v[188:191], v[0:3]
	s_setprio 0
	s_waitcnt lgkmcnt(0)
	s_barrier
	s_setprio 1
	v_lshl_add_u32 v152, v167, 1, v164
	ds_read_b128 v[154:157], v152
	v_lshl_add_u32 v161, v165, 1, v164
	ds_read_b128 v[164:167], v152 offset:1536
	ds_read_b128 v[172:175], v152 offset:3072
	ds_read_b128 v[176:179], v152 offset:4608
	ds_read_b128 v[168:171], v161 offset:12288
	ds_read_b128 v[180:183], v161 offset:13824
	s_waitcnt lgkmcnt(1)
	v_mfma_f32_16x16x32_bf16 v[148:151], v[154:157], v[168:171], v[148:151]
	v_mfma_f32_16x16x32_bf16 v[136:139], v[164:167], v[168:171], v[136:139]
	v_mfma_f32_16x16x32_bf16 v[112:115], v[172:175], v[168:171], v[112:115]
	v_mfma_f32_16x16x32_bf16 v[80:83], v[176:179], v[168:171], v[80:83]
	ds_read_b128 v[168:171], v161 offset:15360
	s_waitcnt vmcnt(5)
	ds_write_b128 v162, v[20:23] offset:36864
	s_waitcnt lgkmcnt(2)
	v_mfma_f32_16x16x32_bf16 v[144:147], v[154:157], v[180:183], v[144:147]
	v_mfma_f32_16x16x32_bf16 v[128:131], v[164:167], v[180:183], v[128:131]
	v_mfma_f32_16x16x32_bf16 v[100:103], v[172:175], v[180:183], v[100:103]
	v_mfma_f32_16x16x32_bf16 v[68:71], v[176:179], v[180:183], v[68:71]
	ds_read_b128 v[180:183], v161 offset:16896
	s_waitcnt vmcnt(4)
	ds_write_b128 v162, v[16:19] offset:36960
	s_waitcnt lgkmcnt(3)
	v_mfma_f32_16x16x32_bf16 v[140:143], v[154:157], v[168:171], v[140:143]
	v_mfma_f32_16x16x32_bf16 v[120:123], v[164:167], v[168:171], v[120:123]
	v_mfma_f32_16x16x32_bf16 v[184:187], v[172:175], v[168:171], v[88:91]
	v_mfma_f32_16x16x32_bf16 v[44:47], v[176:179], v[168:171], v[44:47]
	s_nop 1
	ds_read_b128 v[88:91], v161 offset:18432
	s_waitcnt vmcnt(3)
	ds_write_b128 v163, v[36:39] offset:49152
	s_waitcnt lgkmcnt(3)
	v_mfma_f32_16x16x32_bf16 v[132:135], v[154:157], v[180:183], v[132:135]
	v_mfma_f32_16x16x32_bf16 v[168:171], v[164:167], v[180:183], v[108:111]
	v_mfma_f32_16x16x32_bf16 v[188:191], v[172:175], v[180:183], v[76:79]
	v_mfma_f32_16x16x32_bf16 v[180:183], v[176:179], v[180:183], v[40:43]
	s_nop 2
	ds_read_b128 v[40:43], v161 offset:19968
	s_waitcnt vmcnt(2)
	ds_write_b128 v163, v[32:35] offset:49248
	s_waitcnt lgkmcnt(3)
	v_mfma_f32_16x16x32_bf16 v[124:127], v[154:157], v[88:91], v[124:127]
	v_mfma_f32_16x16x32_bf16 v[192:195], v[164:167], v[88:91], v[96:99]
	v_mfma_f32_16x16x32_bf16 v[196:199], v[172:175], v[88:91], v[64:67]
	v_mfma_f32_16x16x32_bf16 v[200:203], v[176:179], v[88:91], v[12:15]
	s_nop 2
	ds_read_b128 v[12:15], v161 offset:21504
	s_waitcnt vmcnt(1)
	ds_write_b128 v163, v[28:31] offset:49344
	s_waitcnt lgkmcnt(3)
	v_mfma_f32_16x16x32_bf16 v[116:119], v[154:157], v[40:43], v[116:119]
	v_mfma_f32_16x16x32_bf16 v[204:207], v[164:167], v[40:43], v[84:87]
	v_mfma_f32_16x16x32_bf16 v[56:59], v[172:175], v[40:43], v[56:59]
	v_mfma_f32_16x16x32_bf16 v[208:211], v[176:179], v[40:43], v[8:11]
	s_nop 2
	ds_read_b128 v[8:11], v161 offset:23040
	s_waitcnt vmcnt(0)
	ds_write_b128 v163, v[24:27] offset:49440
	s_waitcnt lgkmcnt(3)
	v_mfma_f32_16x16x32_bf16 v[212:215], v[154:157], v[12:15], v[104:107]
	v_mfma_f32_16x16x32_bf16 v[72:75], v[164:167], v[12:15], v[72:75]
	v_mfma_f32_16x16x32_bf16 v[220:223], v[172:175], v[12:15], v[52:55]
	v_mfma_f32_16x16x32_bf16 v[224:227], v[176:179], v[12:15], v[4:7]
	s_waitcnt lgkmcnt(1)
	v_mfma_f32_16x16x32_bf16 v[154:157], v[154:157], v[8:11], v[92:95]
	v_mfma_f32_16x16x32_bf16 v[60:63], v[164:167], v[8:11], v[60:63]
	v_mfma_f32_16x16x32_bf16 v[164:167], v[172:175], v[8:11], v[48:51]
	v_mfma_f32_16x16x32_bf16 v[172:175], v[176:179], v[8:11], v[0:3]
	s_setprio 0
	s_waitcnt lgkmcnt(0)
	s_barrier
; DI void store4(u16* dst, f32x4 v) { uint2 w; w.x = cvtpk(v[0], v[1]); w.y = cvtpk(v[2], v[3]); *(uint2*)dst = w; }
; DI f32x4 mfma16(bf16x8 a, bf16x8 b, f32x4 c) { return __builtin_amdgcn_mfma_f32_16x16x32_bf16(a, b, c, 0, 0, 0); }
; template <int NI, class XL, class EP>
; DI void gemm_tile(const u16* __restrict__ W, int ldw, int f0, int t0, int K, XL xl, EP ep, unsigned char* smem) {
;     ...
; #pragma unroll
;     for (int mi = 0; mi < 4; ++mi) a[mi] = *(const bf16x8*)(Ws + (wf * 64 + mi * 16 + lr) * LST + lq * 8);
; #pragma unroll
;     for (int ni = 0; ni < NI; ++ni) {
;       const bf16x8 b = *(const bf16x8*)(Xs + (wt * (NI * 16) + ni * 16 + lr) * LST + lq * 8);
; #pragma unroll
;       for (int mi = 0; mi < 4; ++mi) acc[mi][ni] = mfma16(a[mi], b, acc[mi][ni]);
;     }
;     __builtin_amdgcn_sched_group_barrier(0x100, 6, 0);
; #pragma unroll
;     for (int ni = 0; ni < NI; ++ni) { __builtin_amdgcn_sched_group_barrier(0x008, 4, 0); if (ni + 2 < NI) __builtin_amdgcn_sched_group_barrier(0x100, 1, 0); }
;     __builtin_amdgcn_s_setprio(0);
; DI void phase9(const Params& p, const Sched& sched, unsigned char* smem) {
;     ...
;       constexpr int EST = 136;
;       u16* Ls = (u16*)smem;
;       const int b = tb >> 11;
;       __syncthreads();
; #pragma unroll
;       for (int mi = 0; mi < 4; ++mi) {
;         const int f = fb + mi * 16 + lq * 4; const float4 gm = *(const float4*)(mod + (size_t)b * 6144 + 5120 + f);
; #pragma unroll
;         for (int ni = 0; ni < 8; ++ni) {
;           const f32x4 o = {gm.x * acc[mi][ni][0], gm.y * acc[mi][ni][1], gm.z * acc[mi][ni][2], gm.w * acc[mi][ni][3]};
;           store4(Ls + (wt * 128 + ni * 16 + lr) * EST + wf * 64 + mi * 16 + lq * 4, o);
;         }
;       }
	s_lshl_b32 s30, s30, 7
	s_setprio 1
	ds_read_b128 v[28:31], v152 offset:36864
	ds_read_b128 v[176:179], v152 offset:38400
	ds_read_b128 v[228:231], v152 offset:39936
	ds_read_b128 v[232:235], v152 offset:41472
	ds_read_b128 v[0:3], v161 offset:49152
	ds_read_b128 v[4:7], v161 offset:50688
	s_waitcnt lgkmcnt(1)
	v_mfma_f32_16x16x32_bf16 v[88:91], v[28:31], v[0:3], v[148:151]
	v_mfma_f32_16x16x32_bf16 v[64:67], v[176:179], v[0:3], v[136:139]
	v_mfma_f32_16x16x32_bf16 v[32:35], v[228:231], v[0:3], v[112:115]
	v_mfma_f32_16x16x32_bf16 v[0:3], v[232:235], v[0:3], v[80:83]
	ds_read_b128 v[8:11], v161 offset:52224
	s_waitcnt lgkmcnt(1)
	v_mfma_f32_16x16x32_bf16 v[96:99], v[28:31], v[4:7], v[144:147]
	v_mfma_f32_16x16x32_bf16 v[76:79], v[176:179], v[4:7], v[128:131]
	v_mfma_f32_16x16x32_bf16 v[36:39], v[228:231], v[4:7], v[100:103]
	v_mfma_f32_16x16x32_bf16 v[4:7], v[232:235], v[4:7], v[68:71]
	ds_read_b128 v[12:15], v161 offset:53760
	s_waitcnt lgkmcnt(1)
	v_mfma_f32_16x16x32_bf16 v[104:107], v[28:31], v[8:11], v[140:143]
	v_mfma_f32_16x16x32_bf16 v[84:87], v[176:179], v[8:11], v[120:123]
	v_mfma_f32_16x16x32_bf16 v[40:43], v[228:231], v[8:11], v[184:187]
	v_mfma_f32_16x16x32_bf16 v[8:11], v[232:235], v[8:11], v[44:47]
	ds_read_b128 v[16:19], v161 offset:55296
	s_waitcnt lgkmcnt(1)
	v_mfma_f32_16x16x32_bf16 v[108:111], v[28:31], v[12:15], v[132:135]
	v_mfma_f32_16x16x32_bf16 v[92:95], v[176:179], v[12:15], v[168:171]
	v_mfma_f32_16x16x32_bf16 v[44:47], v[228:231], v[12:15], v[188:191]
	v_mfma_f32_16x16x32_bf16 v[12:15], v[232:235], v[12:15], v[180:183]
	ds_read_b128 v[20:23], v161 offset:56832
	s_waitcnt lgkmcnt(1)
	v_mfma_f32_16x16x32_bf16 v[112:115], v[28:31], v[16:19], v[124:127]
	v_mfma_f32_16x16x32_bf16 v[100:103], v[176:179], v[16:19], v[192:195]
	v_mfma_f32_16x16x32_bf16 v[48:51], v[228:231], v[16:19], v[196:199]
	v_mfma_f32_16x16x32_bf16 v[16:19], v[232:235], v[16:19], v[200:203]
	ds_read_b128 v[24:27], v161 offset:58368
	s_waitcnt lgkmcnt(1)
	v_mfma_f32_16x16x32_bf16 v[116:119], v[28:31], v[20:23], v[116:119]
	v_mfma_f32_16x16x32_bf16 v[68:71], v[176:179], v[20:23], v[204:207]
	v_mfma_f32_16x16x32_bf16 v[52:55], v[228:231], v[20:23], v[56:59]
	v_mfma_f32_16x16x32_bf16 v[20:23], v[232:235], v[20:23], v[208:211]
	ds_read_b128 v[128:131], v161 offset:59904
	s_waitcnt lgkmcnt(1)
	v_mfma_f32_16x16x32_bf16 v[120:123], v[28:31], v[24:27], v[212:215]
	v_mfma_f32_16x16x32_bf16 v[80:83], v[176:179], v[24:27], v[72:75]
	v_mfma_f32_16x16x32_bf16 v[56:59], v[228:231], v[24:27], v[220:223]
	v_mfma_f32_16x16x32_bf16 v[24:27], v[232:235], v[24:27], v[224:227]
	s_waitcnt lgkmcnt(0)
	v_mfma_f32_16x16x32_bf16 v[124:127], v[28:31], v[128:131], v[154:157]
	v_mfma_f32_16x16x32_bf16 v[72:75], v[176:179], v[128:131], v[60:63]
	v_mfma_f32_16x16x32_bf16 v[60:63], v[228:231], v[128:131], v[164:167]
	v_mfma_f32_16x16x32_bf16 v[28:31], v[232:235], v[128:131], v[172:175]
	s_setprio 0
	s_ashr_i32 s31, s31, 3
	v_add_u32_e32 v128, s30, v160
	s_mul_hi_i32 s33, s31, 0x6000
	s_mulk_i32 s31, 0x6000
	v_lshl_or_b32 v128, v158, 2, v128
	s_add_u32 s34, s72, s31
	s_addc_u32 s35, s73, s33
	v_ashrrev_i32_e32 v129, 31, v128
	v_lshl_add_u64 v[128:129], v[128:129], 2, s[34:35]
	v_add_co_u32_e32 v140, vcc, s24, v128
	v_mul_u32_u24_e32 v138, 0x88, v159
	s_nop 0
	v_addc_co_u32_e32 v141, vcc, 0, v129, vcc
	v_lshlrev_b32_e32 v136, 1, v160
	v_lshlrev_b32_e32 v137, 3, v158
	v_lshlrev_b32_e32 v138, 1, v138
	s_barrier
	global_load_dwordx4 v[128:131], v[140:141], off
	global_load_dwordx4 v[132:135], v[140:141], off offset:64
	v_add3_u32 v144, v136, v137, v138
	global_load_dwordx4 v[136:139], v[140:141], off offset:128
	v_add_u32_e32 v145, 0x1000, v144
	global_load_dwordx4 v[140:143], v[140:141], off offset:192
	v_add_u32_e32 v146, 0x2000, v144
	v_add_u32_e32 v147, 0x3000, v144
	v_add_u32_e32 v148, 0x4000, v144
	s_waitcnt vmcnt(3)
	v_pk_mul_f32 v[88:89], v[88:89], v[128:129]
	v_pk_mul_f32 v[90:91], v[90:91], v[130:131]
	v_pk_mul_f32 v[96:97], v[96:97], v[128:129]
	s_waitcnt vmcnt(1)
	v_pk_mul_f32 v[32:33], v[32:33], v[136:137]
	v_pk_mul_f32 v[34:35], v[34:35], v[138:139]
	s_waitcnt vmcnt(0)
	v_pk_mul_f32 v[0:1], v[0:1], v[140:141]
	v_pk_mul_f32 v[2:3], v[2:3], v[142:143]
	v_cvt_pk_bf16_f32 v32, v32, v33
	v_cvt_pk_bf16_f32 v33, v34, v35
	v_cvt_pk_bf16_f32 v0, v0, v1
	v_cvt_pk_bf16_f32 v1, v2, v3
	v_pk_mul_f32 v[34:35], v[36:37], v[136:137]
	v_pk_mul_f32 v[36:37], v[38:39], v[138:139]
	ds_write2_b64 v144, v[32:33], v[0:1] offset0:8 offset1:12
	v_pk_mul_f32 v[0:1], v[4:5], v[140:141]
	v_pk_mul_f32 v[2:3], v[6:7], v[142:143]
	v_cvt_pk_bf16_f32 v34, v34, v35
	v_cvt_pk_bf16_f32 v35, v36, v37
	v_cvt_pk_bf16_f32 v0, v0, v1
	v_cvt_pk_bf16_f32 v1, v2, v3
	v_pk_mul_f32 v[36:37], v[40:41], v[136:137]
	v_pk_mul_f32 v[38:39], v[42:43], v[138:139]
	ds_write2_b64 v145, v[34:35], v[0:1] offset0:40 offset1:44
	v_pk_mul_f32 v[0:1], v[8:9], v[140:141]
	v_pk_mul_f32 v[2:3], v[10:11], v[142:143]
	v_cvt_pk_bf16_f32 v36, v36, v37
	v_cvt_pk_bf16_f32 v37, v38, v39
	v_cvt_pk_bf16_f32 v0, v0, v1
	v_cvt_pk_bf16_f32 v1, v2, v3
	v_pk_mul_f32 v[38:39], v[44:45], v[136:137]
	v_pk_mul_f32 v[40:41], v[46:47], v[138:139]
	ds_write2_b64 v146, v[36:37], v[0:1] offset0:72 offset1:76
	v_pk_mul_f32 v[0:1], v[12:13], v[140:141]
	v_pk_mul_f32 v[2:3], v[14:15], v[142:143]
	v_cvt_pk_bf16_f32 v38, v38, v39
	v_cvt_pk_bf16_f32 v39, v40, v41
	v_cvt_pk_bf16_f32 v0, v0, v1
	v_cvt_pk_bf16_f32 v1, v2, v3
	v_pk_mul_f32 v[98:99], v[98:99], v[130:131]
	v_pk_mul_f32 v[64:65], v[64:65], v[132:133]
	v_pk_mul_f32 v[66:67], v[66:67], v[134:135]
	v_pk_mul_f32 v[76:77], v[76:77], v[132:133]
	v_pk_mul_f32 v[78:79], v[78:79], v[134:135]
; DI void store4(u16* dst, f32x4 v) { uint2 w; w.x = cvtpk(v[0], v[1]); w.y = cvtpk(v[2], v[3]); *(uint2*)dst = w; }
; DI void phase9(const Params& p, const Sched& sched, unsigned char* smem) {
;     ...
;       __syncthreads();
; #pragma unroll
;       for (int mi = 0; mi < 4; ++mi) {
;         const int f = fb + mi * 16 + lq * 4; const float4 gm = *(const float4*)(mod + (size_t)b * 6144 + 5120 + f);
; #pragma unroll
;         for (int ni = 0; ni < 8; ++ni) {
;           const f32x4 o = {gm.x * acc[mi][ni][0], gm.y * acc[mi][ni][1], gm.z * acc[mi][ni][2], gm.w * acc[mi][ni][3]};
;           store4(Ls + (wt * 128 + ni * 16 + lr) * EST + wf * 64 + mi * 16 + lq * 4, o);
;         }
;       }
;       __syncthreads();
	v_pk_mul_f32 v[40:41], v[48:49], v[136:137]
	v_pk_mul_f32 v[42:43], v[50:51], v[138:139]
	ds_write2_b64 v147, v[38:39], v[0:1] offset0:104 offset1:108
	v_pk_mul_f32 v[0:1], v[16:17], v[140:141]
	v_pk_mul_f32 v[2:3], v[18:19], v[142:143]
	v_cvt_pk_bf16_f32 v88, v88, v89
	v_cvt_pk_bf16_f32 v89, v90, v91
	v_cvt_pk_bf16_f32 v90, v96, v97
	v_cvt_pk_bf16_f32 v91, v98, v99
	v_cvt_pk_bf16_f32 v64, v64, v65
	v_cvt_pk_bf16_f32 v65, v66, v67
	v_cvt_pk_bf16_f32 v66, v76, v77
	v_cvt_pk_bf16_f32 v67, v78, v79
	v_cvt_pk_bf16_f32 v40, v40, v41
	v_cvt_pk_bf16_f32 v41, v42, v43
	v_cvt_pk_bf16_f32 v0, v0, v1
	v_cvt_pk_bf16_f32 v1, v2, v3
	v_pk_mul_f32 v[106:107], v[106:107], v[130:131]
	v_pk_mul_f32 v[116:117], v[116:117], v[128:129]
	v_pk_mul_f32 v[118:119], v[118:119], v[130:131]
	ds_write2_b64 v144, v[88:89], v[64:65] offset1:4
	ds_write2_b64 v145, v[90:91], v[66:67] offset0:32 offset1:36
	v_pk_mul_f32 v[64:65], v[68:69], v[132:133]
	v_pk_mul_f32 v[66:67], v[70:71], v[134:135]
	v_pk_mul_f32 v[42:43], v[52:53], v[136:137]
	v_pk_mul_f32 v[44:45], v[54:55], v[138:139]
	ds_write2_b64 v148, v[40:41], v[0:1] offset0:136 offset1:140
	v_pk_mul_f32 v[0:1], v[20:21], v[140:141]
	v_pk_mul_f32 v[2:3], v[22:23], v[142:143]
	v_cvt_pk_bf16_f32 v97, v106, v107
	v_cvt_pk_bf16_f32 v106, v116, v117
	v_cvt_pk_bf16_f32 v107, v118, v119
	v_cvt_pk_bf16_f32 v64, v64, v65
	v_cvt_pk_bf16_f32 v65, v66, v67
	v_add_u32_e32 v68, 0x5000, v144
	v_cvt_pk_bf16_f32 v42, v42, v43
	v_cvt_pk_bf16_f32 v43, v44, v45
	v_cvt_pk_bf16_f32 v0, v0, v1
	v_cvt_pk_bf16_f32 v1, v2, v3
	v_pk_mul_f32 v[108:109], v[108:109], v[128:129]
	v_pk_mul_f32 v[120:121], v[120:121], v[128:129]
	v_pk_mul_f32 v[122:123], v[122:123], v[130:131]
	ds_write2_b64 v68, v[106:107], v[64:65] offset0:160 offset1:164
	v_pk_mul_f32 v[64:65], v[80:81], v[132:133]
	v_pk_mul_f32 v[66:67], v[82:83], v[134:135]
	v_pk_mul_f32 v[44:45], v[56:57], v[136:137]
	v_pk_mul_f32 v[46:47], v[58:59], v[138:139]
	ds_write2_b64 v68, v[42:43], v[0:1] offset0:168 offset1:172
	v_pk_mul_f32 v[0:1], v[24:25], v[140:141]
	v_pk_mul_f32 v[2:3], v[26:27], v[142:143]
	v_cvt_pk_bf16_f32 v98, v108, v109
	v_cvt_pk_bf16_f32 v108, v120, v121
	v_cvt_pk_bf16_f32 v109, v122, v123
	v_cvt_pk_bf16_f32 v64, v64, v65
	v_cvt_pk_bf16_f32 v65, v66, v67
	v_add_u32_e32 v69, 0x6000, v144
	v_cvt_pk_bf16_f32 v44, v44, v45
	v_cvt_pk_bf16_f32 v45, v46, v47
	v_cvt_pk_bf16_f32 v0, v0, v1
	v_cvt_pk_bf16_f32 v1, v2, v3
	v_pk_mul_f32 v[104:105], v[104:105], v[128:129]
	v_pk_mul_f32 v[110:111], v[110:111], v[130:131]
	v_pk_mul_f32 v[112:113], v[112:113], v[128:129]
	v_pk_mul_f32 v[114:115], v[114:115], v[130:131]
	v_pk_mul_f32 v[124:125], v[124:125], v[128:129]
	v_pk_mul_f32 v[126:127], v[126:127], v[130:131]
	v_pk_mul_f32 v[84:85], v[84:85], v[132:133]
	v_pk_mul_f32 v[86:87], v[86:87], v[134:135]
	v_pk_mul_f32 v[92:93], v[92:93], v[132:133]
	v_pk_mul_f32 v[94:95], v[94:95], v[134:135]
	v_pk_mul_f32 v[100:101], v[100:101], v[132:133]
	v_pk_mul_f32 v[102:103], v[102:103], v[134:135]
	ds_write2_b64 v69, v[108:109], v[64:65] offset0:192 offset1:196
	v_pk_mul_f32 v[64:65], v[72:73], v[132:133]
	v_pk_mul_f32 v[66:67], v[74:75], v[134:135]
	v_pk_mul_f32 v[46:47], v[60:61], v[136:137]
	v_pk_mul_f32 v[48:49], v[62:63], v[138:139]
	ds_write2_b64 v69, v[44:45], v[0:1] offset0:200 offset1:204
	v_pk_mul_f32 v[0:1], v[28:29], v[140:141]
	v_pk_mul_f32 v[2:3], v[30:31], v[142:143]
	v_cvt_pk_bf16_f32 v96, v104, v105
	v_cvt_pk_bf16_f32 v99, v110, v111
	v_cvt_pk_bf16_f32 v104, v112, v113
	v_cvt_pk_bf16_f32 v105, v114, v115
	v_cvt_pk_bf16_f32 v110, v124, v125
	v_cvt_pk_bf16_f32 v111, v126, v127
	v_cvt_pk_bf16_f32 v76, v84, v85
	v_cvt_pk_bf16_f32 v77, v86, v87
	v_cvt_pk_bf16_f32 v78, v92, v93
	v_cvt_pk_bf16_f32 v79, v94, v95
	v_cvt_pk_bf16_f32 v84, v100, v101
	v_cvt_pk_bf16_f32 v85, v102, v103
	v_cvt_pk_bf16_f32 v64, v64, v65
	v_cvt_pk_bf16_f32 v65, v66, v67
	v_add_u32_e32 v66, 0x7000, v144
	v_cvt_pk_bf16_f32 v46, v46, v47
	v_cvt_pk_bf16_f32 v47, v48, v49
	v_cvt_pk_bf16_f32 v0, v0, v1
	v_cvt_pk_bf16_f32 v1, v2, v3
	v_mov_b32_e32 v2, v218
	ds_write2_b64 v146, v[96:97], v[76:77] offset0:64 offset1:68
	ds_write2_b64 v147, v[98:99], v[78:79] offset0:96 offset1:100
	ds_write2_b64 v148, v[104:105], v[84:85] offset0:128 offset1:132
	ds_write2_b64 v66, v[110:111], v[64:65] offset0:224 offset1:228
	ds_write2_b64 v66, v[46:47], v[0:1] offset0:232 offset1:236
	s_waitcnt lgkmcnt(0)
	s_barrier
; DI int tidx() { int t = __builtin_amdgcn_workitem_id_x(); asm volatile("" : "+v"(t)); return t; }
; DI unsigned cvtpk(float lo, float hi) { const f32x2_ v = {lo, hi}; return __builtin_bit_cast(unsigned, __builtin_convertvector(v, bf16x2_)); }
; DI float bflo(unsigned w) { return __uint_as_float(w << 16); }
; DI float bfhi(unsigned w) { return __uint_as_float(w & 0xffff0000u); }
; DI void phase9(const Params& p, const Sched& sched, unsigned char* smem) {
;     ...
;       const int tid = tidx();
; #pragma unroll
;       for (int i = 0; i < 16; ++i) {
;         const int c = tid + 256 * i, row = c >> 4, ch = (c & 15) * 8;
;         const size_t gi = (size_t)(tm * 256 + row) * 1024 + tn * 128 + ch;
;         const u32x4 sv = *(const u32x4*)(Ls + row * EST + ch), xv = *(const u32x4*)(x1b + gi);
;         u32x4 w;
;         w.x = cvtpk(bflo(xv.x) + bflo(sv.x), bfhi(xv.x) + bfhi(sv.x)); w.y = cvtpk(bflo(xv.y) + bflo(sv.y), bfhi(xv.y) + bfhi(sv.y));
;         w.z = cvtpk(bflo(xv.z) + bflo(sv.z), bfhi(xv.z) + bfhi(sv.z)); w.w = cvtpk(bflo(xv.w) + bflo(sv.w), bfhi(xv.w) + bfhi(sv.w));
;         *(u32x4*)(x2b + gi) = w;
;       }
	s_nop 0
	v_ashrrev_i32_e32 v3, 4, v2
	v_add_u32_e32 v4, s29, v3
	v_lshlrev_b32_e32 v0, 3, v2
	v_ashrrev_i32_e32 v5, 31, v4
	v_and_b32_e32 v1, 0x78, v0
	v_lshlrev_b64 v[4:5], 10, v[4:5]
	v_or3_b32 v4, v4, s30, v1
	v_lshlrev_b64 v[12:13], 1, v[4:5]
	v_lshl_add_u64 v[4:5], s[12:13], 0, v[12:13]
	global_load_dwordx4 v[4:7], v[4:5], off
	v_lshlrev_b32_e32 v0, 1, v1
	v_mad_u64_u32 v[8:9], s[34:35], v3, s25, v[0:1]
	ds_read_b128 v[8:11], v8
	v_add_u32_e32 v3, 0x100, v2
	v_ashrrev_i32_e32 v3, 4, v3
	s_waitcnt lgkmcnt(0)
	v_lshlrev_b32_e32 v16, 16, v8
	v_and_b32_e32 v17, 0xffff0000, v8
	v_lshlrev_b32_e32 v8, 16, v9
	v_and_b32_e32 v9, 0xffff0000, v9
	s_waitcnt vmcnt(0)
	v_lshlrev_b32_e32 v14, 16, v4
	v_and_b32_e32 v15, 0xffff0000, v4
	v_pk_add_f32 v[14:15], v[16:17], v[14:15]
	s_nop 0
	v_cvt_pk_bf16_f32 v4, v14, v15
	v_lshlrev_b32_e32 v14, 16, v5
	v_and_b32_e32 v15, 0xffff0000, v5
	v_pk_add_f32 v[8:9], v[8:9], v[14:15]
	v_lshlrev_b32_e32 v14, 16, v10
	v_cvt_pk_bf16_f32 v5, v8, v9
	v_lshlrev_b32_e32 v8, 16, v6
	v_and_b32_e32 v9, 0xffff0000, v6
	v_and_b32_e32 v15, 0xffff0000, v10
	v_pk_add_f32 v[8:9], v[14:15], v[8:9]
	v_lshlrev_b32_e32 v10, 16, v11
	v_cvt_pk_bf16_f32 v6, v8, v9
	v_lshlrev_b32_e32 v8, 16, v7
	v_and_b32_e32 v9, 0xffff0000, v7
	v_and_b32_e32 v11, 0xffff0000, v11
	v_pk_add_f32 v[8:9], v[10:11], v[8:9]
	s_nop 0
	v_cvt_pk_bf16_f32 v7, v8, v9
	v_lshl_add_u64 v[8:9], s[2:3], 0, v[12:13]
	global_store_dwordx4 v[8:9], v[4:7], off
	v_mad_u64_u32 v[8:9], s[34:35], v3, s25, v[0:1]
	s_nop 0
	v_add_u32_e32 v4, s29, v3
	v_ashrrev_i32_e32 v5, 31, v4
	v_lshlrev_b64 v[4:5], 10, v[4:5]
	v_or3_b32 v4, v4, s30, v1
	v_lshlrev_b64 v[12:13], 1, v[4:5]
	v_lshl_add_u64 v[4:5], s[12:13], 0, v[12:13]
	global_load_dwordx4 v[4:7], v[4:5], off
	ds_read_b128 v[8:11], v8
	v_add_u32_e32 v3, 0x200, v2
	v_ashrrev_i32_e32 v3, 4, v3
	v_lshl_add_u64 v[12:13], s[2:3], 0, v[12:13]
	s_waitcnt lgkmcnt(0)
	v_lshlrev_b32_e32 v14, 16, v8
	v_and_b32_e32 v15, 0xffff0000, v8
	v_lshlrev_b32_e32 v8, 16, v9
	v_and_b32_e32 v9, 0xffff0000, v9
	v_lshlrev_b32_e32 v16, 16, v10
	v_and_b32_e32 v17, 0xffff0000, v10
	v_lshlrev_b32_e32 v10, 16, v11
	v_and_b32_e32 v11, 0xffff0000, v11
	s_waitcnt vmcnt(0)
	v_lshlrev_b32_e32 v18, 16, v4
	v_and_b32_e32 v19, 0xffff0000, v4
	v_lshlrev_b32_e32 v4, 16, v5
	v_and_b32_e32 v5, 0xffff0000, v5
	v_lshlrev_b32_e32 v20, 16, v6
	v_and_b32_e32 v21, 0xffff0000, v6
	v_lshlrev_b32_e32 v6, 16, v7
	v_and_b32_e32 v7, 0xffff0000, v7
	v_pk_add_f32 v[14:15], v[14:15], v[18:19]
	v_pk_add_f32 v[8:9], v[8:9], v[4:5]
	v_pk_add_f32 v[16:17], v[16:17], v[20:21]
	v_pk_add_f32 v[10:11], v[10:11], v[6:7]
	v_cvt_pk_bf16_f32 v4, v14, v15
	v_cvt_pk_bf16_f32 v5, v8, v9
	v_cvt_pk_bf16_f32 v6, v16, v17
	v_cvt_pk_bf16_f32 v7, v10, v11
	global_store_dwordx4 v[12:13], v[4:7], off
	v_add_u32_e32 v8, 0x300, v2
	v_ashrrev_i32_e32 v26, 4, v8
	v_add_u32_e32 v4, s29, v3
	v_ashrrev_i32_e32 v5, 31, v4
	v_lshlrev_b64 v[4:5], 10, v[4:5]
	v_or3_b32 v4, v4, s30, v1
	v_lshlrev_b64 v[12:13], 1, v[4:5]
	v_lshl_add_u64 v[4:5], s[12:13], 0, v[12:13]
	global_load_dwordx4 v[4:7], v[4:5], off
	v_mad_u64_u32 v[8:9], s[34:35], v3, s25, v[0:1]
	ds_read_b128 v[8:11], v8
	v_add_u32_e32 v14, s29, v26
	v_ashrrev_i32_e32 v15, 31, v14
	v_lshlrev_b64 v[14:15], 10, v[14:15]
	v_or3_b32 v14, v14, s30, v1
	s_waitcnt lgkmcnt(0)
	v_lshlrev_b32_e32 v18, 16, v8
	v_and_b32_e32 v19, 0xffff0000, v8
	v_lshlrev_b32_e32 v8, 16, v9
	v_and_b32_e32 v9, 0xffff0000, v9
	v_lshlrev_b32_e32 v20, 16, v10
	v_and_b32_e32 v21, 0xffff0000, v10
	v_lshlrev_b32_e32 v10, 16, v11
	v_and_b32_e32 v11, 0xffff0000, v11
	v_lshlrev_b64 v[14:15], 1, v[14:15]
	v_lshl_add_u64 v[12:13], s[2:3], 0, v[12:13]
	v_lshl_add_u64 v[16:17], s[12:13], 0, v[14:15]
	v_add_u32_e32 v3, 0x400, v2
	v_ashrrev_i32_e32 v3, 4, v3
	v_lshl_add_u64 v[14:15], s[2:3], 0, v[14:15]
	s_waitcnt vmcnt(0)
	v_lshlrev_b32_e32 v22, 16, v4
	v_and_b32_e32 v23, 0xffff0000, v4
	v_lshlrev_b32_e32 v4, 16, v5
	v_and_b32_e32 v5, 0xffff0000, v5
	v_lshlrev_b32_e32 v24, 16, v6
	v_and_b32_e32 v25, 0xffff0000, v6
	v_lshlrev_b32_e32 v6, 16, v7
	v_and_b32_e32 v7, 0xffff0000, v7
	v_pk_add_f32 v[18:19], v[18:19], v[22:23]
	v_pk_add_f32 v[8:9], v[8:9], v[4:5]
	v_pk_add_f32 v[20:21], v[20:21], v[24:25]
	v_pk_add_f32 v[10:11], v[10:11], v[6:7]
	v_cvt_pk_bf16_f32 v4, v18, v19
	v_cvt_pk_bf16_f32 v5, v8, v9
	v_cvt_pk_bf16_f32 v6, v20, v21
	v_cvt_pk_bf16_f32 v7, v10, v11
	global_store_dwordx4 v[12:13], v[4:7], off
	global_load_dwordx4 v[4:7], v[16:17], off
	v_mad_u64_u32 v[8:9], s[34:35], v26, s25, v[0:1]
	ds_read_b128 v[8:11], v8
	v_add_u32_e32 v12, s29, v3
	v_ashrrev_i32_e32 v13, 31, v12
	v_lshlrev_b64 v[12:13], 10, v[12:13]
	v_or3_b32 v12, v12, s30, v1
	s_waitcnt lgkmcnt(0)
	v_lshlrev_b32_e32 v18, 16, v8
	v_and_b32_e32 v19, 0xffff0000, v8
	v_lshlrev_b32_e32 v8, 16, v9
	v_and_b32_e32 v9, 0xffff0000, v9
	v_lshlrev_b32_e32 v20, 16, v10
	v_and_b32_e32 v21, 0xffff0000, v10
	v_lshlrev_b32_e32 v10, 16, v11
	v_and_b32_e32 v11, 0xffff0000, v11
	v_lshlrev_b64 v[12:13], 1, v[12:13]
	v_lshl_add_u64 v[16:17], s[12:13], 0, v[12:13]
	v_lshl_add_u64 v[12:13], s[2:3], 0, v[12:13]
	s_waitcnt vmcnt(0)
	v_lshlrev_b32_e32 v22, 16, v4
	v_and_b32_e32 v23, 0xffff0000, v4
	v_lshlrev_b32_e32 v4, 16, v5
	v_and_b32_e32 v5, 0xffff0000, v5
	v_lshlrev_b32_e32 v24, 16, v6
	v_and_b32_e32 v25, 0xffff0000, v6
	v_lshlrev_b32_e32 v6, 16, v7
	v_and_b32_e32 v7, 0xffff0000, v7
	v_pk_add_f32 v[18:19], v[18:19], v[22:23]
	v_pk_add_f32 v[8:9], v[8:9], v[4:5]
	v_pk_add_f32 v[20:21], v[20:21], v[24:25]
	v_pk_add_f32 v[10:11], v[10:11], v[6:7]
	v_cvt_pk_bf16_f32 v4, v18, v19
	v_cvt_pk_bf16_f32 v5, v8, v9
	v_cvt_pk_bf16_f32 v6, v20, v21
	v_cvt_pk_bf16_f32 v7, v10, v11
	global_store_dwordx4 v[14:15], v[4:7], off
	global_load_dwordx4 v[4:7], v[16:17], off
	v_add_u32_e32 v8, 0x500, v2
	v_ashrrev_i32_e32 v26, 4, v8
	v_mad_u64_u32 v[8:9], s[34:35], v3, s25, v[0:1]
	ds_read_b128 v[8:11], v8
	v_add_u32_e32 v14, s29, v26
	v_ashrrev_i32_e32 v15, 31, v14
	v_lshlrev_b64 v[14:15], 10, v[14:15]
	v_or3_b32 v14, v14, s30, v1
	s_waitcnt lgkmcnt(0)
; DI unsigned cvtpk(float lo, float hi) { const f32x2_ v = {lo, hi}; return __builtin_bit_cast(unsigned, __builtin_convertvector(v, bf16x2_)); }
; DI float bflo(unsigned w) { return __uint_as_float(w << 16); }
; DI float bfhi(unsigned w) { return __uint_as_float(w & 0xffff0000u); }
; DI void phase9(const Params& p, const Sched& sched, unsigned char* smem) {
;     ...
; #pragma unroll
;       for (int i = 0; i < 16; ++i) {
;         const int c = tid + 256 * i, row = c >> 4, ch = (c & 15) * 8;
;         const size_t gi = (size_t)(tm * 256 + row) * 1024 + tn * 128 + ch;
;         const u32x4 sv = *(const u32x4*)(Ls + row * EST + ch), xv = *(const u32x4*)(x1b + gi);
;         u32x4 w;
;         w.x = cvtpk(bflo(xv.x) + bflo(sv.x), bfhi(xv.x) + bfhi(sv.x)); w.y = cvtpk(bflo(xv.y) + bflo(sv.y), bfhi(xv.y) + bfhi(sv.y));
;         w.z = cvtpk(bflo(xv.z) + bflo(sv.z), bfhi(xv.z) + bfhi(sv.z)); w.w = cvtpk(bflo(xv.w) + bflo(sv.w), bfhi(xv.w) + bfhi(sv.w));
;         *(u32x4*)(x2b + gi) = w;
	v_lshlrev_b32_e32 v18, 16, v8
	v_and_b32_e32 v19, 0xffff0000, v8
	v_lshlrev_b32_e32 v8, 16, v9
	v_and_b32_e32 v9, 0xffff0000, v9
	v_lshlrev_b32_e32 v20, 16, v10
	v_and_b32_e32 v21, 0xffff0000, v10
	v_lshlrev_b32_e32 v10, 16, v11
	v_and_b32_e32 v11, 0xffff0000, v11
	v_lshlrev_b64 v[14:15], 1, v[14:15]
	v_lshl_add_u64 v[16:17], s[12:13], 0, v[14:15]
	v_add_u32_e32 v3, 0x600, v2
	v_ashrrev_i32_e32 v3, 4, v3
	v_lshl_add_u64 v[14:15], s[2:3], 0, v[14:15]
	s_waitcnt vmcnt(0)
	v_lshlrev_b32_e32 v22, 16, v4
	v_and_b32_e32 v23, 0xffff0000, v4
	v_lshlrev_b32_e32 v4, 16, v5
	v_and_b32_e32 v5, 0xffff0000, v5
	v_lshlrev_b32_e32 v24, 16, v6
	v_and_b32_e32 v25, 0xffff0000, v6
	v_lshlrev_b32_e32 v6, 16, v7
	v_and_b32_e32 v7, 0xffff0000, v7
	v_pk_add_f32 v[18:19], v[18:19], v[22:23]
	v_pk_add_f32 v[8:9], v[8:9], v[4:5]
	v_pk_add_f32 v[20:21], v[20:21], v[24:25]
	v_pk_add_f32 v[10:11], v[10:11], v[6:7]
	v_cvt_pk_bf16_f32 v4, v18, v19
	v_cvt_pk_bf16_f32 v5, v8, v9
	v_cvt_pk_bf16_f32 v6, v20, v21
	v_cvt_pk_bf16_f32 v7, v10, v11
	global_store_dwordx4 v[12:13], v[4:7], off
	global_load_dwordx4 v[4:7], v[16:17], off
	v_mad_u64_u32 v[8:9], s[34:35], v26, s25, v[0:1]
	ds_read_b128 v[8:11], v8
	v_add_u32_e32 v12, s29, v3
	v_ashrrev_i32_e32 v13, 31, v12
	v_lshlrev_b64 v[12:13], 10, v[12:13]
	v_or3_b32 v12, v12, s30, v1
	s_waitcnt lgkmcnt(0)
	v_lshlrev_b32_e32 v18, 16, v8
	v_and_b32_e32 v19, 0xffff0000, v8
	v_lshlrev_b32_e32 v8, 16, v9
	v_and_b32_e32 v9, 0xffff0000, v9
	v_lshlrev_b32_e32 v20, 16, v10
	v_and_b32_e32 v21, 0xffff0000, v10
	v_lshlrev_b32_e32 v10, 16, v11
	v_and_b32_e32 v11, 0xffff0000, v11
	v_lshlrev_b64 v[12:13], 1, v[12:13]
	v_lshl_add_u64 v[16:17], s[12:13], 0, v[12:13]
	v_lshl_add_u64 v[12:13], s[2:3], 0, v[12:13]
	s_waitcnt vmcnt(0)
	v_lshlrev_b32_e32 v22, 16, v4
	v_and_b32_e32 v23, 0xffff0000, v4
	v_lshlrev_b32_e32 v4, 16, v5
	v_and_b32_e32 v5, 0xffff0000, v5
	v_lshlrev_b32_e32 v24, 16, v6
	v_and_b32_e32 v25, 0xffff0000, v6
	v_lshlrev_b32_e32 v6, 16, v7
	v_and_b32_e32 v7, 0xffff0000, v7
	v_pk_add_f32 v[18:19], v[18:19], v[22:23]
	v_pk_add_f32 v[8:9], v[8:9], v[4:5]
	v_pk_add_f32 v[20:21], v[20:21], v[24:25]
	v_pk_add_f32 v[10:11], v[10:11], v[6:7]
	v_cvt_pk_bf16_f32 v4, v18, v19
	v_cvt_pk_bf16_f32 v5, v8, v9
	v_cvt_pk_bf16_f32 v6, v20, v21
	v_cvt_pk_bf16_f32 v7, v10, v11
	global_store_dwordx4 v[14:15], v[4:7], off
	global_load_dwordx4 v[4:7], v[16:17], off
	v_add_u32_e32 v8, 0x700, v2
	v_ashrrev_i32_e32 v26, 4, v8
	v_mad_u64_u32 v[8:9], s[34:35], v3, s25, v[0:1]
	ds_read_b128 v[8:11], v8
	v_add_u32_e32 v14, s29, v26
	v_ashrrev_i32_e32 v15, 31, v14
	v_lshlrev_b64 v[14:15], 10, v[14:15]
	v_or3_b32 v14, v14, s30, v1
	s_waitcnt lgkmcnt(0)
	v_lshlrev_b32_e32 v18, 16, v8
	v_and_b32_e32 v19, 0xffff0000, v8
	v_lshlrev_b32_e32 v8, 16, v9
	v_and_b32_e32 v9, 0xffff0000, v9
	v_lshlrev_b32_e32 v20, 16, v10
	v_and_b32_e32 v21, 0xffff0000, v10
	v_lshlrev_b32_e32 v10, 16, v11
	v_and_b32_e32 v11, 0xffff0000, v11
	v_lshlrev_b64 v[14:15], 1, v[14:15]
	v_lshl_add_u64 v[16:17], s[12:13], 0, v[14:15]
	v_add_u32_e32 v3, 0x800, v2
	v_ashrrev_i32_e32 v3, 4, v3
	v_lshl_add_u64 v[14:15], s[2:3], 0, v[14:15]
	s_waitcnt vmcnt(0)
	v_lshlrev_b32_e32 v22, 16, v4
	v_and_b32_e32 v23, 0xffff0000, v4
	v_lshlrev_b32_e32 v4, 16, v5
	v_and_b32_e32 v5, 0xffff0000, v5
	v_lshlrev_b32_e32 v24, 16, v6
	v_and_b32_e32 v25, 0xffff0000, v6
	v_lshlrev_b32_e32 v6, 16, v7
	v_and_b32_e32 v7, 0xffff0000, v7
	v_pk_add_f32 v[18:19], v[18:19], v[22:23]
	v_pk_add_f32 v[8:9], v[8:9], v[4:5]
	v_pk_add_f32 v[20:21], v[20:21], v[24:25]
	v_pk_add_f32 v[10:11], v[10:11], v[6:7]
	v_cvt_pk_bf16_f32 v4, v18, v19
	v_cvt_pk_bf16_f32 v5, v8, v9
	v_cvt_pk_bf16_f32 v6, v20, v21
	v_cvt_pk_bf16_f32 v7, v10, v11
	global_store_dwordx4 v[12:13], v[4:7], off
	global_load_dwordx4 v[4:7], v[16:17], off
	v_mad_u64_u32 v[8:9], s[34:35], v26, s25, v[0:1]
	ds_read_b128 v[8:11], v8
	v_add_u32_e32 v12, s29, v3
	v_ashrrev_i32_e32 v13, 31, v12
	v_lshlrev_b64 v[12:13], 10, v[12:13]
	v_or3_b32 v12, v12, s30, v1
	s_waitcnt lgkmcnt(0)
	v_lshlrev_b32_e32 v18, 16, v8
	v_and_b32_e32 v19, 0xffff0000, v8
	v_lshlrev_b32_e32 v8, 16, v9
	v_and_b32_e32 v9, 0xffff0000, v9
	v_lshlrev_b32_e32 v20, 16, v10
	v_and_b32_e32 v21, 0xffff0000, v10
	v_lshlrev_b32_e32 v10, 16, v11
	v_and_b32_e32 v11, 0xffff0000, v11
	v_lshlrev_b64 v[12:13], 1, v[12:13]
	v_lshl_add_u64 v[16:17], s[12:13], 0, v[12:13]
	v_lshl_add_u64 v[12:13], s[2:3], 0, v[12:13]
	s_waitcnt vmcnt(0)
	v_lshlrev_b32_e32 v22, 16, v4
	v_and_b32_e32 v23, 0xffff0000, v4
	v_lshlrev_b32_e32 v4, 16, v5
	v_and_b32_e32 v5, 0xffff0000, v5
	v_lshlrev_b32_e32 v24, 16, v6
	v_and_b32_e32 v25, 0xffff0000, v6
	v_lshlrev_b32_e32 v6, 16, v7
	v_and_b32_e32 v7, 0xffff0000, v7
	v_pk_add_f32 v[18:19], v[18:19], v[22:23]
	v_pk_add_f32 v[8:9], v[8:9], v[4:5]
	v_pk_add_f32 v[20:21], v[20:21], v[24:25]
	v_pk_add_f32 v[10:11], v[10:11], v[6:7]
	v_cvt_pk_bf16_f32 v4, v18, v19
	v_cvt_pk_bf16_f32 v5, v8, v9
	v_cvt_pk_bf16_f32 v6, v20, v21
	v_cvt_pk_bf16_f32 v7, v10, v11
	global_store_dwordx4 v[14:15], v[4:7], off
	global_load_dwordx4 v[4:7], v[16:17], off
	v_add_u32_e32 v8, 0x900, v2
	v_ashrrev_i32_e32 v26, 4, v8
	v_mad_u64_u32 v[8:9], s[34:35], v3, s25, v[0:1]
	ds_read_b128 v[8:11], v8
	v_add_u32_e32 v14, s29, v26
	v_ashrrev_i32_e32 v15, 31, v14
	v_lshlrev_b64 v[14:15], 10, v[14:15]
	v_or3_b32 v14, v14, s30, v1
	s_waitcnt lgkmcnt(0)
	v_lshlrev_b32_e32 v18, 16, v8
	v_and_b32_e32 v19, 0xffff0000, v8
	v_lshlrev_b32_e32 v8, 16, v9
	v_and_b32_e32 v9, 0xffff0000, v9
	v_lshlrev_b32_e32 v20, 16, v10
	v_and_b32_e32 v21, 0xffff0000, v10
	v_lshlrev_b32_e32 v10, 16, v11
	v_and_b32_e32 v11, 0xffff0000, v11
	v_lshlrev_b64 v[14:15], 1, v[14:15]
	v_lshl_add_u64 v[16:17], s[12:13], 0, v[14:15]
	v_add_u32_e32 v3, 0xa00, v2
	v_ashrrev_i32_e32 v3, 4, v3
	v_lshl_add_u64 v[14:15], s[2:3], 0, v[14:15]
	s_waitcnt vmcnt(0)
; DI unsigned cvtpk(float lo, float hi) { const f32x2_ v = {lo, hi}; return __builtin_bit_cast(unsigned, __builtin_convertvector(v, bf16x2_)); }
; DI float bflo(unsigned w) { return __uint_as_float(w << 16); }
; DI float bfhi(unsigned w) { return __uint_as_float(w & 0xffff0000u); }
; DI void phase9(const Params& p, const Sched& sched, unsigned char* smem) {
;     ...
; #pragma unroll
;       for (int i = 0; i < 16; ++i) {
;         const int c = tid + 256 * i, row = c >> 4, ch = (c & 15) * 8;
;         const size_t gi = (size_t)(tm * 256 + row) * 1024 + tn * 128 + ch;
;         const u32x4 sv = *(const u32x4*)(Ls + row * EST + ch), xv = *(const u32x4*)(x1b + gi);
;         u32x4 w;
;         w.x = cvtpk(bflo(xv.x) + bflo(sv.x), bfhi(xv.x) + bfhi(sv.x)); w.y = cvtpk(bflo(xv.y) + bflo(sv.y), bfhi(xv.y) + bfhi(sv.y));
;         w.z = cvtpk(bflo(xv.z) + bflo(sv.z), bfhi(xv.z) + bfhi(sv.z)); w.w = cvtpk(bflo(xv.w) + bflo(sv.w), bfhi(xv.w) + bfhi(sv.w));
;         *(u32x4*)(x2b + gi) = w;
	v_lshlrev_b32_e32 v22, 16, v4
	v_and_b32_e32 v23, 0xffff0000, v4
	v_lshlrev_b32_e32 v4, 16, v5
	v_and_b32_e32 v5, 0xffff0000, v5
	v_lshlrev_b32_e32 v24, 16, v6
	v_and_b32_e32 v25, 0xffff0000, v6
	v_lshlrev_b32_e32 v6, 16, v7
	v_and_b32_e32 v7, 0xffff0000, v7
	v_pk_add_f32 v[18:19], v[18:19], v[22:23]
	v_pk_add_f32 v[8:9], v[8:9], v[4:5]
	v_pk_add_f32 v[20:21], v[20:21], v[24:25]
	v_pk_add_f32 v[10:11], v[10:11], v[6:7]
	v_cvt_pk_bf16_f32 v4, v18, v19
	v_cvt_pk_bf16_f32 v5, v8, v9
	v_cvt_pk_bf16_f32 v6, v20, v21
	v_cvt_pk_bf16_f32 v7, v10, v11
	global_store_dwordx4 v[12:13], v[4:7], off
	global_load_dwordx4 v[4:7], v[16:17], off
	v_mad_u64_u32 v[8:9], s[34:35], v26, s25, v[0:1]
	ds_read_b128 v[8:11], v8
	v_add_u32_e32 v12, s29, v3
	v_ashrrev_i32_e32 v13, 31, v12
	v_lshlrev_b64 v[12:13], 10, v[12:13]
	v_or3_b32 v12, v12, s30, v1
	s_waitcnt lgkmcnt(0)
	v_lshlrev_b32_e32 v18, 16, v8
	v_and_b32_e32 v19, 0xffff0000, v8
	v_lshlrev_b32_e32 v8, 16, v9
	v_and_b32_e32 v9, 0xffff0000, v9
	v_lshlrev_b32_e32 v20, 16, v10
	v_and_b32_e32 v21, 0xffff0000, v10
	v_lshlrev_b32_e32 v10, 16, v11
	v_and_b32_e32 v11, 0xffff0000, v11
	v_lshlrev_b64 v[12:13], 1, v[12:13]
	v_lshl_add_u64 v[16:17], s[12:13], 0, v[12:13]
	v_lshl_add_u64 v[12:13], s[2:3], 0, v[12:13]
	s_waitcnt vmcnt(0)
	v_lshlrev_b32_e32 v22, 16, v4
	v_and_b32_e32 v23, 0xffff0000, v4
	v_lshlrev_b32_e32 v4, 16, v5
	v_and_b32_e32 v5, 0xffff0000, v5
	v_lshlrev_b32_e32 v24, 16, v6
	v_and_b32_e32 v25, 0xffff0000, v6
	v_lshlrev_b32_e32 v6, 16, v7
	v_and_b32_e32 v7, 0xffff0000, v7
	v_pk_add_f32 v[18:19], v[18:19], v[22:23]
	v_pk_add_f32 v[8:9], v[8:9], v[4:5]
	v_pk_add_f32 v[20:21], v[20:21], v[24:25]
	v_pk_add_f32 v[10:11], v[10:11], v[6:7]
	v_cvt_pk_bf16_f32 v4, v18, v19
	v_cvt_pk_bf16_f32 v5, v8, v9
	v_cvt_pk_bf16_f32 v6, v20, v21
	v_cvt_pk_bf16_f32 v7, v10, v11
	global_store_dwordx4 v[14:15], v[4:7], off
	global_load_dwordx4 v[4:7], v[16:17], off
	v_add_u32_e32 v8, 0xb00, v2
	v_ashrrev_i32_e32 v26, 4, v8
	v_mad_u64_u32 v[8:9], s[34:35], v3, s25, v[0:1]
	ds_read_b128 v[8:11], v8
	v_add_u32_e32 v14, s29, v26
	v_ashrrev_i32_e32 v15, 31, v14
	v_lshlrev_b64 v[14:15], 10, v[14:15]
	v_or3_b32 v14, v14, s30, v1
	s_waitcnt lgkmcnt(0)
	v_lshlrev_b32_e32 v18, 16, v8
	v_and_b32_e32 v19, 0xffff0000, v8
	v_lshlrev_b32_e32 v8, 16, v9
	v_and_b32_e32 v9, 0xffff0000, v9
	v_lshlrev_b32_e32 v20, 16, v10
	v_and_b32_e32 v21, 0xffff0000, v10
	v_lshlrev_b32_e32 v10, 16, v11
	v_and_b32_e32 v11, 0xffff0000, v11
	v_lshlrev_b64 v[14:15], 1, v[14:15]
	v_lshl_add_u64 v[16:17], s[12:13], 0, v[14:15]
	v_add_u32_e32 v3, 0xc00, v2
	v_ashrrev_i32_e32 v3, 4, v3
	v_lshl_add_u64 v[14:15], s[2:3], 0, v[14:15]
	s_waitcnt vmcnt(0)
	v_lshlrev_b32_e32 v22, 16, v4
	v_and_b32_e32 v23, 0xffff0000, v4
	v_lshlrev_b32_e32 v4, 16, v5
	v_and_b32_e32 v5, 0xffff0000, v5
	v_lshlrev_b32_e32 v24, 16, v6
	v_and_b32_e32 v25, 0xffff0000, v6
	v_lshlrev_b32_e32 v6, 16, v7
	v_and_b32_e32 v7, 0xffff0000, v7
	v_pk_add_f32 v[18:19], v[18:19], v[22:23]
	v_pk_add_f32 v[8:9], v[8:9], v[4:5]
	v_pk_add_f32 v[20:21], v[20:21], v[24:25]
	v_pk_add_f32 v[10:11], v[10:11], v[6:7]
	v_cvt_pk_bf16_f32 v4, v18, v19
	v_cvt_pk_bf16_f32 v5, v8, v9
	v_cvt_pk_bf16_f32 v6, v20, v21
	v_cvt_pk_bf16_f32 v7, v10, v11
	global_store_dwordx4 v[12:13], v[4:7], off
	global_load_dwordx4 v[4:7], v[16:17], off
	v_mad_u64_u32 v[8:9], s[34:35], v26, s25, v[0:1]
	ds_read_b128 v[8:11], v8
	v_add_u32_e32 v12, s29, v3
	v_ashrrev_i32_e32 v13, 31, v12
	v_lshlrev_b64 v[12:13], 10, v[12:13]
	v_or3_b32 v12, v12, s30, v1
	s_waitcnt lgkmcnt(0)
	v_lshlrev_b32_e32 v18, 16, v8
	v_and_b32_e32 v19, 0xffff0000, v8
	v_lshlrev_b32_e32 v8, 16, v9
	v_and_b32_e32 v9, 0xffff0000, v9
	v_lshlrev_b32_e32 v20, 16, v10
	v_and_b32_e32 v21, 0xffff0000, v10
	v_lshlrev_b32_e32 v10, 16, v11
	v_and_b32_e32 v11, 0xffff0000, v11
	v_lshlrev_b64 v[12:13], 1, v[12:13]
	v_lshl_add_u64 v[16:17], s[12:13], 0, v[12:13]
	v_lshl_add_u64 v[12:13], s[2:3], 0, v[12:13]
	s_waitcnt vmcnt(0)
	v_lshlrev_b32_e32 v22, 16, v4
	v_and_b32_e32 v23, 0xffff0000, v4
	v_lshlrev_b32_e32 v4, 16, v5
	v_and_b32_e32 v5, 0xffff0000, v5
	v_lshlrev_b32_e32 v24, 16, v6
	v_and_b32_e32 v25, 0xffff0000, v6
	v_lshlrev_b32_e32 v6, 16, v7
	v_and_b32_e32 v7, 0xffff0000, v7
	v_pk_add_f32 v[18:19], v[18:19], v[22:23]
	v_pk_add_f32 v[8:9], v[8:9], v[4:5]
	v_pk_add_f32 v[20:21], v[20:21], v[24:25]
	v_pk_add_f32 v[10:11], v[10:11], v[6:7]
	v_cvt_pk_bf16_f32 v4, v18, v19
	v_cvt_pk_bf16_f32 v5, v8, v9
	v_cvt_pk_bf16_f32 v6, v20, v21
	v_cvt_pk_bf16_f32 v7, v10, v11
	global_store_dwordx4 v[14:15], v[4:7], off
	global_load_dwordx4 v[4:7], v[16:17], off
	v_add_u32_e32 v8, 0xd00, v2
	v_ashrrev_i32_e32 v26, 4, v8
	v_mad_u64_u32 v[8:9], s[34:35], v3, s25, v[0:1]
	ds_read_b128 v[8:11], v8
	v_add_u32_e32 v14, s29, v26
	v_ashrrev_i32_e32 v15, 31, v14
	v_lshlrev_b64 v[14:15], 10, v[14:15]
	v_or3_b32 v14, v14, s30, v1
	s_waitcnt lgkmcnt(0)
; DI unsigned cvtpk(float lo, float hi) { const f32x2_ v = {lo, hi}; return __builtin_bit_cast(unsigned, __builtin_convertvector(v, bf16x2_)); }
; DI float bflo(unsigned w) { return __uint_as_float(w << 16); }
; DI float bfhi(unsigned w) { return __uint_as_float(w & 0xffff0000u); }
; DI void phase9(const Params& p, const Sched& sched, unsigned char* smem) {
;     ...
; #pragma unroll
;       for (int i = 0; i < 16; ++i) {
;         const int c = tid + 256 * i, row = c >> 4, ch = (c & 15) * 8;
;         const size_t gi = (size_t)(tm * 256 + row) * 1024 + tn * 128 + ch;
;         const u32x4 sv = *(const u32x4*)(Ls + row * EST + ch), xv = *(const u32x4*)(x1b + gi);
;         u32x4 w;
;         w.x = cvtpk(bflo(xv.x) + bflo(sv.x), bfhi(xv.x) + bfhi(sv.x)); w.y = cvtpk(bflo(xv.y) + bflo(sv.y), bfhi(xv.y) + bfhi(sv.y));
;         w.z = cvtpk(bflo(xv.z) + bflo(sv.z), bfhi(xv.z) + bfhi(sv.z)); w.w = cvtpk(bflo(xv.w) + bflo(sv.w), bfhi(xv.w) + bfhi(sv.w));
;         *(u32x4*)(x2b + gi) = w;
	v_lshlrev_b32_e32 v18, 16, v8
	v_and_b32_e32 v19, 0xffff0000, v8
	v_lshlrev_b32_e32 v8, 16, v9
	v_and_b32_e32 v9, 0xffff0000, v9
	v_lshlrev_b32_e32 v20, 16, v10
	v_and_b32_e32 v21, 0xffff0000, v10
	v_lshlrev_b32_e32 v10, 16, v11
	v_and_b32_e32 v11, 0xffff0000, v11
	v_lshlrev_b64 v[14:15], 1, v[14:15]
	v_lshl_add_u64 v[16:17], s[12:13], 0, v[14:15]
	v_add_u32_e32 v3, 0xe00, v2
	v_ashrrev_i32_e32 v3, 4, v3
	v_lshl_add_u64 v[14:15], s[2:3], 0, v[14:15]
	v_add_u32_e32 v2, 0xf00, v2
	s_waitcnt vmcnt(0)
	v_lshlrev_b32_e32 v22, 16, v4
	v_and_b32_e32 v23, 0xffff0000, v4
	v_lshlrev_b32_e32 v4, 16, v5
	v_and_b32_e32 v5, 0xffff0000, v5
	v_lshlrev_b32_e32 v24, 16, v6
	v_and_b32_e32 v25, 0xffff0000, v6
	v_lshlrev_b32_e32 v6, 16, v7
	v_and_b32_e32 v7, 0xffff0000, v7
	v_pk_add_f32 v[18:19], v[18:19], v[22:23]
	v_pk_add_f32 v[8:9], v[8:9], v[4:5]
	v_pk_add_f32 v[20:21], v[20:21], v[24:25]
	v_pk_add_f32 v[10:11], v[10:11], v[6:7]
	v_cvt_pk_bf16_f32 v4, v18, v19
	v_cvt_pk_bf16_f32 v5, v8, v9
	v_cvt_pk_bf16_f32 v6, v20, v21
	v_cvt_pk_bf16_f32 v7, v10, v11
	global_store_dwordx4 v[12:13], v[4:7], off
	global_load_dwordx4 v[4:7], v[16:17], off
	v_mad_u64_u32 v[8:9], s[34:35], v26, s25, v[0:1]
	ds_read_b128 v[8:11], v8
	v_add_u32_e32 v12, s29, v3
	v_ashrrev_i32_e32 v13, 31, v12
	v_lshlrev_b64 v[12:13], 10, v[12:13]
	v_or3_b32 v12, v12, s30, v1
	s_waitcnt lgkmcnt(0)
	v_lshlrev_b32_e32 v18, 16, v8
	v_and_b32_e32 v19, 0xffff0000, v8
	v_lshlrev_b32_e32 v8, 16, v9
	v_and_b32_e32 v9, 0xffff0000, v9
	v_lshlrev_b32_e32 v20, 16, v10
	v_and_b32_e32 v21, 0xffff0000, v10
	v_lshlrev_b32_e32 v10, 16, v11
	v_and_b32_e32 v11, 0xffff0000, v11
	v_lshlrev_b64 v[12:13], 1, v[12:13]
	v_lshl_add_u64 v[16:17], s[12:13], 0, v[12:13]
	v_lshl_add_u64 v[12:13], s[2:3], 0, v[12:13]
	s_waitcnt vmcnt(0)
	v_lshlrev_b32_e32 v22, 16, v4
	v_and_b32_e32 v23, 0xffff0000, v4
	v_lshlrev_b32_e32 v4, 16, v5
	v_and_b32_e32 v5, 0xffff0000, v5
	v_lshlrev_b32_e32 v24, 16, v6
	v_and_b32_e32 v25, 0xffff0000, v6
	v_lshlrev_b32_e32 v6, 16, v7
	v_and_b32_e32 v7, 0xffff0000, v7
	v_pk_add_f32 v[18:19], v[18:19], v[22:23]
	v_pk_add_f32 v[8:9], v[8:9], v[4:5]
	v_pk_add_f32 v[20:21], v[20:21], v[24:25]
	v_pk_add_f32 v[10:11], v[10:11], v[6:7]
	v_cvt_pk_bf16_f32 v4, v18, v19
	v_cvt_pk_bf16_f32 v5, v8, v9
	v_cvt_pk_bf16_f32 v6, v20, v21
	v_cvt_pk_bf16_f32 v7, v10, v11
	global_store_dwordx4 v[14:15], v[4:7], off
	global_load_dwordx4 v[4:7], v[16:17], off
	v_mad_u64_u32 v[8:9], s[34:35], v3, s25, v[0:1]
	v_ashrrev_i32_e32 v24, 4, v2
	ds_read_b128 v[8:11], v8
	v_add_u32_e32 v2, s29, v24
	v_ashrrev_i32_e32 v3, 31, v2
	v_lshlrev_b64 v[2:3], 10, v[2:3]
	v_or3_b32 v2, v2, s30, v1
	v_lshlrev_b64 v[14:15], 1, v[2:3]
	s_waitcnt lgkmcnt(0)
	v_lshlrev_b32_e32 v2, 16, v8
	v_and_b32_e32 v3, 0xffff0000, v8
	v_lshlrev_b32_e32 v8, 16, v9
	v_and_b32_e32 v9, 0xffff0000, v9
	v_lshlrev_b32_e32 v18, 16, v10
	v_and_b32_e32 v19, 0xffff0000, v10
	v_lshlrev_b32_e32 v10, 16, v11
	v_and_b32_e32 v11, 0xffff0000, v11
	v_lshl_add_u64 v[16:17], s[12:13], 0, v[14:15]
	v_mad_u64_u32 v[0:1], s[30:31], v24, s25, v[0:1]
	s_waitcnt vmcnt(0)
	v_lshlrev_b32_e32 v20, 16, v4
	v_and_b32_e32 v21, 0xffff0000, v4
	v_lshlrev_b32_e32 v4, 16, v5
	v_and_b32_e32 v5, 0xffff0000, v5
	v_lshlrev_b32_e32 v22, 16, v6
	v_and_b32_e32 v23, 0xffff0000, v6
	v_lshlrev_b32_e32 v6, 16, v7
	v_and_b32_e32 v7, 0xffff0000, v7
	v_pk_add_f32 v[2:3], v[2:3], v[20:21]
	v_pk_add_f32 v[4:5], v[8:9], v[4:5]
	v_pk_add_f32 v[8:9], v[18:19], v[22:23]
	v_pk_add_f32 v[6:7], v[10:11], v[6:7]
	v_cvt_pk_bf16_f32 v2, v2, v3
	v_cvt_pk_bf16_f32 v3, v4, v5
	v_cvt_pk_bf16_f32 v4, v8, v9
	v_cvt_pk_bf16_f32 v5, v6, v7
	global_store_dwordx4 v[12:13], v[2:5], off
	global_load_dwordx4 v[2:5], v[16:17], off
	ds_read_b128 v[6:9], v0
	v_lshl_add_u64 v[10:11], s[2:3], 0, v[14:15]
	s_waitcnt lgkmcnt(0)
	v_lshlrev_b32_e32 v0, 16, v6
	v_and_b32_e32 v1, 0xffff0000, v6
	v_lshlrev_b32_e32 v6, 16, v7
	v_and_b32_e32 v7, 0xffff0000, v7
	v_lshlrev_b32_e32 v12, 16, v8
	v_and_b32_e32 v13, 0xffff0000, v8
	v_lshlrev_b32_e32 v8, 16, v9
	v_and_b32_e32 v9, 0xffff0000, v9
	s_waitcnt vmcnt(0)
	v_lshlrev_b32_e32 v14, 16, v2
	v_and_b32_e32 v15, 0xffff0000, v2
	v_lshlrev_b32_e32 v2, 16, v3
	v_and_b32_e32 v3, 0xffff0000, v3
	v_lshlrev_b32_e32 v16, 16, v4
	v_and_b32_e32 v17, 0xffff0000, v4
	v_lshlrev_b32_e32 v4, 16, v5
	v_and_b32_e32 v5, 0xffff0000, v5
	v_pk_add_f32 v[0:1], v[0:1], v[14:15]
	v_pk_add_f32 v[2:3], v[6:7], v[2:3]
	v_pk_add_f32 v[6:7], v[12:13], v[16:17]
	v_pk_add_f32 v[4:5], v[8:9], v[4:5]
	v_cvt_pk_bf16_f32 v0, v0, v1
	v_cvt_pk_bf16_f32 v1, v2, v3
	v_cvt_pk_bf16_f32 v2, v6, v7
	v_cvt_pk_bf16_f32 v3, v4, v5
	global_store_dwordx4 v[10:11], v[0:3], off
	v_mov_b32_e32 v243, 0x12000
	v_readfirstlane_b32 s98, v218
	s_cmp_lg_u32 s98, 0
	s_cbranch_scc1 .Lp9_dyn_skip_b
	s_waitcnt vmcnt(16)
	s_mov_b64 s[100:101], exec
	s_mov_b64 exec, 1
	ds_write_b32 v243, v240
	s_waitcnt lgkmcnt(0)
	s_mov_b64 exec, s[100:101]
